# full-line epilogue stores extended to the four stream-K GEMMs (G3/G6/G12/G15); all 8 GEMMs now store 8 rows x 128B per instruction
# baseline (speedup 1.0000x reference)
.LBB0_358:
	s_or_b64 exec, exec, s[0:1]
	v_readlane_b32 s0, v248, 10
	s_abs_i32 s4, s0
	s_waitcnt lgkmcnt(0)
	v_cvt_f32_u32_e32 v0, s4
	v_readlane_b32 s1, v248, 11
	s_sub_i32 s0, 0, s4
	v_mov_b32_e32 v8, v202
	v_rcp_iflag_f32_e32 v0, v0
	s_barrier
	v_mul_f32_e32 v0, 0x4f7ffffe, v0
	v_cvt_u32_f32_e32 v0, v0
	s_nop 0
	v_readfirstlane_b32 s30, v8
	v_readfirstlane_b32 s1, v0
	s_mul_i32 s0, s0, s1
	s_mul_hi_u32 s0, s1, s0
	s_add_i32 s0, s1, s0
	v_writelane_b32 v247, s0, 17
	s_mul_hi_u32 s0, s0, 0x2400
	s_mul_i32 s1, s0, s4
	s_sub_i32 s1, 0x2400, s1
	s_add_i32 s2, s0, 1
	s_sub_i32 s3, s1, s4
	s_cmp_ge_u32 s1, s4
	s_cselect_b32 s0, s2, s0
	s_cselect_b32 s1, s3, s1
	s_add_i32 s2, s0, 1
	v_writelane_b32 v247, s4, 18
	s_cmp_ge_u32 s1, s4
	s_cselect_b32 s0, s2, s0
	v_readlane_b32 s1, v247, 11
	s_xor_b32 s0, s0, s1
	s_sub_i32 s3, s0, s1
	s_add_u32 s4, s58, 0x1800000
	s_addc_u32 s5, s59, 0
	s_cmp_gt_i32 s3, 0
	s_cbranch_scc0 .LBB0_372
	v_lshlrev_b32_e32 v0, 4, v8
	v_add_u32_e32 v1, 0x2000, v0
	v_ashrrev_i32_e32 v2, 31, v1
	v_lshrrev_b32_e32 v2, 22, v2
	v_add_u32_e32 v2, v1, v2
	v_ashrrev_i32_e32 v9, 10, v2
	s_mul_i32 s7, s3, s42
	v_mul_i32_i24_e32 v2, 0x400, v9
	s_ashr_i32 s0, s7, 31
	s_mul_hi_i32 s1, s7, 0x38e38e39
	v_sub_u32_e32 v1, v1, v2
	s_lshr_b32 s0, s0, 27
	s_lshr_b32 s2, s1, 31
	s_ashr_i32 s1, s1, 6
	v_lshrrev_b32_e32 v2, 4, v1
	s_add_i32 s8, s7, s0
	s_add_i32 s1, s1, s2
	v_bitop3_b32 v1, v2, v1, 32 bitop3:0x6c
	s_ashr_i32 s0, s8, 5
	s_mul_i32 s2, s1, -9
	v_ashrrev_i32_e32 v2, 31, v1
	s_add_i32 s2, s2, s0
	v_lshrrev_b32_e32 v2, 26, v2
	s_and_b32 s39, s1, 7
	s_lshl_b32 s0, s2, 2
	s_ashr_i32 s1, s1, 3
	v_add_u32_e32 v2, v1, v2
	v_lshlrev_b32_e32 v3, 3, v9
	s_add_i32 s0, s0, s1
	v_ashrrev_i32_e32 v10, 6, v2
	v_and_b32_e32 v3, -16, v3
	s_ashr_i32 s1, s0, 31
	v_add_u32_e32 v3, v10, v3
	s_lshl_b64 s[18:19], s[0:1], 20
	v_and_b32_e32 v4, 3, v10
	s_mov_b32 s1, 0xfffe0
	v_lshrrev_b32_e32 v5, 2, v3
	v_lshlrev_b32_e32 v6, 1, v3
	v_and_b32_e32 v2, 0xc0, v2
	v_and_or_b32 v4, v3, s1, v4
	v_and_b32_e32 v5, 4, v5
	v_and_b32_e32 v6, 24, v6
	v_sub_u32_e32 v1, v1, v2
	v_mov_b32_e32 v2, 1
	v_or3_b32 v4, v4, v5, v6
	v_lshlrev_b32_e32 v5, 5, v9
	v_ashrrev_i16_sdwa v1, v2, sext(v1) dst_sel:DWORD dst_unused:UNUSED_PAD src0_sel:DWORD src1_sel:BYTE_0
	v_and_b32_e32 v5, 32, v5
	v_bfe_i32 v11, v1, 0, 16
	v_add_lshl_u32 v1, v5, v11, 1
	v_lshl_add_u32 v128, v4, 12, v1
	v_lshl_add_u32 v130, v3, 12, v1
	v_bfe_i32 v1, v8, 27, 1
	v_lshrrev_b32_e32 v1, 22, v1
	v_add_u32_e32 v1, v0, v1
	v_and_b32_e32 v1, 0xfffffc00, v1
	v_sub_u32_e32 v0, v0, v1
	v_lshrrev_b32_e32 v1, 4, v0
	v_ashrrev_i32_e32 v3, 31, v8
	v_bitop3_b32 v0, v1, v0, 32 bitop3:0x6c
	v_lshrrev_b32_e32 v3, 26, v3
	v_ashrrev_i32_e32 v1, 31, v0
	v_add_u32_e32 v3, v8, v3
	v_lshrrev_b32_e32 v1, 26, v1
	v_ashrrev_i32_e32 v13, 6, v3
	s_andn2_b32 s8, s8, 31
	v_add_u32_e32 v1, v0, v1
	v_lshlrev_b32_e32 v3, 3, v13
	s_sub_i32 s16, s7, s8
	v_ashrrev_i32_e32 v12, 6, v1
	v_and_b32_e32 v3, -16, v3
	s_ashr_i32 s2, s30, 6
	s_ashr_i32 s17, s16, 31
	v_add_u32_e32 v3, v12, v3
	s_ashr_i32 s6, s30, 8
	s_lshl_b32 s31, s2, 10
	s_lshl_b32 s9, s39, 20
	s_lshl_b64 s[16:17], s[16:17], 7
	v_and_b32_e32 v4, 3, v12
	v_lshrrev_b32_e32 v5, 2, v3
	v_lshlrev_b32_e32 v6, 1, v3
	v_and_b32_e32 v1, 0xc0, v1
	v_and_or_b32 v4, v3, s1, v4
	v_and_b32_e32 v5, 4, v5
	v_and_b32_e32 v6, 24, v6
	v_sub_u32_e32 v0, v0, v1
	s_add_u32 s1, s4, s9
	v_or3_b32 v4, v4, v5, v6
	v_lshlrev_b32_e32 v5, 5, v13
	v_ashrrev_i16_sdwa v0, v2, sext(v0) dst_sel:DWORD dst_unused:UNUSED_PAD src0_sel:DWORD src1_sel:BYTE_0
	s_addc_u32 s9, s5, 0
	v_and_b32_e32 v5, 32, v5
	v_bfe_i32 v14, v0, 0, 16
	s_add_u32 s26, s1, s16
	v_add_lshl_u32 v0, v5, v14, 1
	s_addc_u32 s27, s9, s17
	s_add_i32 s1, s31, 0
	v_lshl_add_u32 v132, v4, 12, v0
	s_add_i32 m0, s1, 0x10000
	v_lshl_add_u32 v134, v3, 12, v0
	v_mov_b32_e32 v230, s6
	v_lshlrev_b32_e32 v230, 17, v230
	v_add_u32_e32 v132, v132, v230
	v_add_u32_e32 v230, 0x40000, v230
	v_add_u32_e32 v128, v128, v230
	global_load_lds_dwordx4 v132, s[26:27]
	s_add_i32 m0, s1, 0x12000
	s_add_u32 s9, s14, s18
	s_addc_u32 s18, s15, s19
	s_add_u32 s24, s9, s16
	global_load_lds_dwordx4 v128, s[26:27]
	s_addc_u32 s25, s18, s17
	s_mov_b32 m0, s1
	s_add_i32 s33, s1, 0x2000
	global_load_lds_dwordx4 v134, s[24:25]
	s_mov_b32 m0, s33
	s_add_u32 s16, s26, 0x20000
	global_load_lds_dwordx4 v130, s[24:25]
	s_addc_u32 s17, s27, 0
	s_add_i32 m0, s1, 0x14000
	v_mov_b32_e32 v133, 0
	global_load_lds_dwordx4 v132, s[16:17]
	s_add_i32 m0, s1, 0x16000
	v_mov_b32_e32 v129, v133
	global_load_lds_dwordx4 v128, s[16:17]
	s_add_u32 s16, s24, 0x80000
	s_addc_u32 s17, s25, 0
	s_add_i32 s34, s1, 0x4000
	s_mov_b32 m0, s34
	s_add_i32 s35, s1, 0x6000
	global_load_lds_dwordx4 v134, s[16:17]
	s_mov_b32 m0, s35
	v_mov_b32_e32 v135, v133
	global_load_lds_dwordx4 v130, s[16:17]
	v_mov_b32_e32 v131, v133
	v_lshl_add_u64 v[6:7], s[26:27], 0, v[132:133]
	v_lshl_add_u64 v[4:5], s[26:27], 0, v[128:129]
	v_lshl_add_u64 v[0:1], s[24:25], 0, v[134:135]
	s_cmp_lg_u32 s6, 1
	v_lshl_add_u64 v[2:3], s[24:25], 0, v[130:131]
	s_cbranch_scc1 .LBB0_361
	s_barrier
.LBB0_361:
	s_add_i32 s36, s7, s3
	s_add_i32 s37, s8, 32
	s_min_i32 s3, s37, s36
	s_sub_i32 s46, s3, s7
	s_add_i32 s38, s8, 64
	s_cmp_eq_u32 s7, s8
	s_mov_b32 s3, 0x3c280000
	s_cselect_b32 s16, s3, 0x39e80000
	s_lshl_b32 s2, s2, 5
	s_and_b32 s18, s2, 0x60
	s_mov_b64 s[2:3], 0x80
	s_add_i32 m0, s1, 0x18000
	v_lshl_add_u64 v[6:7], v[6:7], 0, s[2:3]
	s_lshl_b32 s7, s6, 13
	s_lshl_b32 s19, s18, 7
	s_waitcnt vmcnt(4)
	s_barrier
	global_load_lds_dwordx4 v[6:7], off
	v_lshl_add_u64 v[4:5], v[4:5], 0, s[2:3]
	s_add_i32 m0, s1, 0x1a000
	s_add_i32 s40, s1, 0x8000
	s_add_i32 s41, s1, 0xa000
	global_load_lds_dwordx4 v[4:5], off
	v_lshl_add_u64 v[0:1], v[0:1], 0, s[2:3]
	s_mov_b32 m0, s40
	s_add_u32 s8, s26, 0x20080
	global_load_lds_dwordx4 v[0:1], off
	v_lshl_add_u64 v[0:1], v[2:3], 0, s[2:3]
	s_mov_b32 m0, s41
	s_addc_u32 s9, s27, 0
	global_load_lds_dwordx4 v[0:1], off
	s_add_i32 m0, s1, 0x1c000
	v_lshl_add_u64 v[0:1], s[8:9], 0, v[132:133]
	global_load_lds_dwordx4 v[0:1], off
	v_lshl_add_u64 v[0:1], s[8:9], 0, v[128:129]
	s_add_i32 m0, s1, 0x1e000
	s_mov_b32 s17, 0
	global_load_lds_dwordx4 v[0:1], off
	v_lshrrev_b32_e32 v1, 1, v8
	v_and_b32_e32 v1, 24, v1
	v_and_b32_e32 v0, 15, v8
	v_lshlrev_b32_e32 v2, 1, v1
	v_lshl_or_b32 v140, s6, 6, v0
	v_lshl_or_b32 v0, v0, 6, v2
	v_lshlrev_b32_e32 v2, 2, v8
	v_and_b32_e32 v2, 32, v2
	v_bitop3_b32 v3, v0, s7, v2 bitop3:0xde
	v_bitop3_b32 v141, v0, s19, v2 bitop3:0xde
	v_lshlrev_b32_e32 v0, 15, v13
	v_and_b32_e32 v0, 0xffff0000, v0
	v_or_b32_e32 v142, s18, v1
	v_lshl_add_u32 v0, v12, 12, v0
	v_and_b32_e32 v1, 1, v13
	v_lshl_or_b32 v0, v1, 6, v0
	v_lshl_add_u32 v136, v14, 1, v0
	v_lshlrev_b32_e32 v0, 15, v9
	v_and_b32_e32 v0, 0xffff0000, v0
	s_waitcnt vmcnt(6)
	v_lshl_add_u32 v0, v10, 12, v0
	v_and_b32_e32 v1, 1, v9
	v_lshl_or_b32 v0, v1, 6, v0
	s_add_i32 s42, 0, 0x10000
	s_add_i32 s43, 0, 0x14000
	v_mov_b32_e32 v137, v133
	v_lshl_add_u32 v138, v11, 1, v0
	v_mov_b32_e32 v139, v133
	v_add_u32_e32 v143, s42, v141
	v_add_u32_e32 v144, 0, v3
	v_add_u32_e32 v145, s43, v141
	s_mov_b32 s44, s17
	s_barrier
	s_branch .LBB0_364

.LBB0_363:
	s_add_i32 s44, s44, 1
	s_add_u32 s16, s58, s16
	s_addc_u32 s17, s59, s17
	s_mov_b32 s100, s16
	s_mov_b32 s101, s17
	v_and_b32_e32 v242, 15, v202
	v_bfe_u32 v243, v202, 4, 2
	v_bfe_u32 v244, v202, 6, 2
	v_lshrrev_b32_e32 v245, 8, v202
	v_and_b32_e32 v240, 7, v242
	v_lshl_add_u32 v240, v245, 6, v240
	v_lshl_add_u32 v240, s0, 8, v240
	v_lshlrev_b32_e32 v240, 12, v240
	v_lshrrev_b32_e32 v241, 3, v242
	v_lshlrev_b32_e32 v241, 6, v241
	v_lshl_add_u32 v241, v244, 7, v241
	v_lshl_add_u32 v241, v243, 4, v241
	v_add_u32_e32 v240, v240, v241
	s_lshl_b32 s98, s39, 9
	v_add_u32_e32 v240, s98, v240
	v_cvt_pk_bf16_f32 v228, v124, v125
	v_cvt_pk_bf16_f32 v229, v126, v127
	v_cvt_pk_bf16_f32 v230, v120, v121
	v_cvt_pk_bf16_f32 v231, v122, v123
	v_cvt_pk_bf16_f32 v232, v116, v117
	v_cvt_pk_bf16_f32 v233, v118, v119
	v_cvt_pk_bf16_f32 v234, v112, v113
	v_cvt_pk_bf16_f32 v235, v114, v115
	v_mov_b32_e32 v236, v228
	v_mov_b32_e32 v237, v229
	v_mov_b32_e32 v238, v230
	v_mov_b32_e32 v239, v231
	v_mov_b32_dpp v228, v232 row_ror:8 row_mask:0xf bank_mask:0xc
	v_mov_b32_dpp v229, v233 row_ror:8 row_mask:0xf bank_mask:0xc
	v_mov_b32_dpp v230, v234 row_ror:8 row_mask:0xf bank_mask:0xc
	v_mov_b32_dpp v231, v235 row_ror:8 row_mask:0xf bank_mask:0xc
	v_mov_b32_dpp v232, v236 row_ror:8 row_mask:0xf bank_mask:0x3
	v_mov_b32_dpp v233, v237 row_ror:8 row_mask:0xf bank_mask:0x3
	v_mov_b32_dpp v234, v238 row_ror:8 row_mask:0xf bank_mask:0x3
	v_mov_b32_dpp v235, v239 row_ror:8 row_mask:0xf bank_mask:0x3
	global_store_dwordx4 v240, v[228:231], s[100:101]
	s_add_u32 s100, s100, 0x8000
	s_addc_u32 s101, s101, 0
	global_store_dwordx4 v240, v[232:235], s[100:101]
	v_cvt_pk_bf16_f32 v228, v108, v109
	v_cvt_pk_bf16_f32 v229, v110, v111
	v_cvt_pk_bf16_f32 v230, v104, v105
	v_cvt_pk_bf16_f32 v231, v106, v107
	v_cvt_pk_bf16_f32 v232, v100, v101
	v_cvt_pk_bf16_f32 v233, v102, v103
	v_cvt_pk_bf16_f32 v234, v96, v97
	v_cvt_pk_bf16_f32 v235, v98, v99
	v_mov_b32_e32 v236, v228
	v_mov_b32_e32 v237, v229
	v_mov_b32_e32 v238, v230
	v_mov_b32_e32 v239, v231
	v_mov_b32_dpp v228, v232 row_ror:8 row_mask:0xf bank_mask:0xc
	v_mov_b32_dpp v229, v233 row_ror:8 row_mask:0xf bank_mask:0xc
	v_mov_b32_dpp v230, v234 row_ror:8 row_mask:0xf bank_mask:0xc
	v_mov_b32_dpp v231, v235 row_ror:8 row_mask:0xf bank_mask:0xc
	v_mov_b32_dpp v232, v236 row_ror:8 row_mask:0xf bank_mask:0x3
	v_mov_b32_dpp v233, v237 row_ror:8 row_mask:0xf bank_mask:0x3
	v_mov_b32_dpp v234, v238 row_ror:8 row_mask:0xf bank_mask:0x3
	v_mov_b32_dpp v235, v239 row_ror:8 row_mask:0xf bank_mask:0x3
	s_add_u32 s100, s100, 0x8000
	s_addc_u32 s101, s101, 0
	global_store_dwordx4 v240, v[228:231], s[100:101]
	s_add_u32 s100, s100, 0x8000
	s_addc_u32 s101, s101, 0
	global_store_dwordx4 v240, v[232:235], s[100:101]
	v_cvt_pk_bf16_f32 v228, v92, v93
	v_cvt_pk_bf16_f32 v229, v94, v95
	v_cvt_pk_bf16_f32 v230, v88, v89
	v_cvt_pk_bf16_f32 v231, v90, v91
	v_cvt_pk_bf16_f32 v232, v84, v85
	v_cvt_pk_bf16_f32 v233, v86, v87
	v_cvt_pk_bf16_f32 v234, v80, v81
	v_cvt_pk_bf16_f32 v235, v82, v83
	v_mov_b32_e32 v236, v228
	v_mov_b32_e32 v237, v229
	v_mov_b32_e32 v238, v230
	v_mov_b32_e32 v239, v231
	v_mov_b32_dpp v228, v232 row_ror:8 row_mask:0xf bank_mask:0xc
	v_mov_b32_dpp v229, v233 row_ror:8 row_mask:0xf bank_mask:0xc
	v_mov_b32_dpp v230, v234 row_ror:8 row_mask:0xf bank_mask:0xc
	v_mov_b32_dpp v231, v235 row_ror:8 row_mask:0xf bank_mask:0xc
	v_mov_b32_dpp v232, v236 row_ror:8 row_mask:0xf bank_mask:0x3
	v_mov_b32_dpp v233, v237 row_ror:8 row_mask:0xf bank_mask:0x3
	v_mov_b32_dpp v234, v238 row_ror:8 row_mask:0xf bank_mask:0x3
	v_mov_b32_dpp v235, v239 row_ror:8 row_mask:0xf bank_mask:0x3
	s_add_u32 s100, s100, 0x8000
	s_addc_u32 s101, s101, 0
	global_store_dwordx4 v240, v[228:231], s[100:101]
	s_add_u32 s100, s100, 0x8000
	s_addc_u32 s101, s101, 0
	global_store_dwordx4 v240, v[232:235], s[100:101]
	v_cvt_pk_bf16_f32 v228, v76, v77
	v_cvt_pk_bf16_f32 v229, v78, v79
	v_cvt_pk_bf16_f32 v230, v72, v73
	v_cvt_pk_bf16_f32 v231, v74, v75
	v_cvt_pk_bf16_f32 v232, v68, v69
	v_cvt_pk_bf16_f32 v233, v70, v71
	v_cvt_pk_bf16_f32 v234, v64, v65
	v_cvt_pk_bf16_f32 v235, v66, v67
	v_mov_b32_e32 v236, v228
	v_mov_b32_e32 v237, v229
	v_mov_b32_e32 v238, v230
	v_mov_b32_e32 v239, v231
	v_mov_b32_dpp v228, v232 row_ror:8 row_mask:0xf bank_mask:0xc
	v_mov_b32_dpp v229, v233 row_ror:8 row_mask:0xf bank_mask:0xc
	v_mov_b32_dpp v230, v234 row_ror:8 row_mask:0xf bank_mask:0xc
	v_mov_b32_dpp v231, v235 row_ror:8 row_mask:0xf bank_mask:0xc
	v_mov_b32_dpp v232, v236 row_ror:8 row_mask:0xf bank_mask:0x3
	v_mov_b32_dpp v233, v237 row_ror:8 row_mask:0xf bank_mask:0x3
	v_mov_b32_dpp v234, v238 row_ror:8 row_mask:0xf bank_mask:0x3
	v_mov_b32_dpp v235, v239 row_ror:8 row_mask:0xf bank_mask:0x3
	s_add_u32 s100, s100, 0x8000
	s_addc_u32 s101, s101, 0
	global_store_dwordx4 v240, v[228:231], s[100:101]
	s_add_u32 s100, s100, 0x8000
	s_addc_u32 s101, s101, 0
	global_store_dwordx4 v240, v[232:235], s[100:101]
	v_cvt_pk_bf16_f32 v228, v60, v61
	v_cvt_pk_bf16_f32 v229, v62, v63
	v_cvt_pk_bf16_f32 v230, v56, v57
	v_cvt_pk_bf16_f32 v231, v58, v59
	v_cvt_pk_bf16_f32 v232, v52, v53
	v_cvt_pk_bf16_f32 v233, v54, v55
	v_cvt_pk_bf16_f32 v234, v48, v49
	v_cvt_pk_bf16_f32 v235, v50, v51
	v_mov_b32_e32 v236, v228
	v_mov_b32_e32 v237, v229
	v_mov_b32_e32 v238, v230
	v_mov_b32_e32 v239, v231
	v_mov_b32_dpp v228, v232 row_ror:8 row_mask:0xf bank_mask:0xc
	v_mov_b32_dpp v229, v233 row_ror:8 row_mask:0xf bank_mask:0xc
	v_mov_b32_dpp v230, v234 row_ror:8 row_mask:0xf bank_mask:0xc
	v_mov_b32_dpp v231, v235 row_ror:8 row_mask:0xf bank_mask:0xc
	v_mov_b32_dpp v232, v236 row_ror:8 row_mask:0xf bank_mask:0x3
	v_mov_b32_dpp v233, v237 row_ror:8 row_mask:0xf bank_mask:0x3
	v_mov_b32_dpp v234, v238 row_ror:8 row_mask:0xf bank_mask:0x3
	v_mov_b32_dpp v235, v239 row_ror:8 row_mask:0xf bank_mask:0x3
	s_add_u32 s100, s100, 0x48000
	s_addc_u32 s101, s101, 0
	global_store_dwordx4 v240, v[228:231], s[100:101]
	s_add_u32 s100, s100, 0x8000
	s_addc_u32 s101, s101, 0
	global_store_dwordx4 v240, v[232:235], s[100:101]
	v_cvt_pk_bf16_f32 v228, v44, v45
	v_cvt_pk_bf16_f32 v229, v46, v47
	v_cvt_pk_bf16_f32 v230, v40, v41
	v_cvt_pk_bf16_f32 v231, v42, v43
	v_cvt_pk_bf16_f32 v232, v36, v37
	v_cvt_pk_bf16_f32 v233, v38, v39
	v_cvt_pk_bf16_f32 v234, v32, v33
	v_cvt_pk_bf16_f32 v235, v34, v35
	v_mov_b32_e32 v236, v228
	v_mov_b32_e32 v237, v229
	v_mov_b32_e32 v238, v230
	v_mov_b32_e32 v239, v231
	v_mov_b32_dpp v228, v232 row_ror:8 row_mask:0xf bank_mask:0xc
	v_mov_b32_dpp v229, v233 row_ror:8 row_mask:0xf bank_mask:0xc
	v_mov_b32_dpp v230, v234 row_ror:8 row_mask:0xf bank_mask:0xc
	v_mov_b32_dpp v231, v235 row_ror:8 row_mask:0xf bank_mask:0xc
	v_mov_b32_dpp v232, v236 row_ror:8 row_mask:0xf bank_mask:0x3
	v_mov_b32_dpp v233, v237 row_ror:8 row_mask:0xf bank_mask:0x3
	v_mov_b32_dpp v234, v238 row_ror:8 row_mask:0xf bank_mask:0x3
	v_mov_b32_dpp v235, v239 row_ror:8 row_mask:0xf bank_mask:0x3
	s_add_u32 s100, s100, 0x8000
	s_addc_u32 s101, s101, 0
	global_store_dwordx4 v240, v[228:231], s[100:101]
	s_add_u32 s100, s100, 0x8000
	s_addc_u32 s101, s101, 0
	global_store_dwordx4 v240, v[232:235], s[100:101]
	v_cvt_pk_bf16_f32 v228, v28, v29
	v_cvt_pk_bf16_f32 v229, v30, v31
	v_cvt_pk_bf16_f32 v230, v24, v25
	v_cvt_pk_bf16_f32 v231, v26, v27
	v_cvt_pk_bf16_f32 v232, v20, v21
	v_cvt_pk_bf16_f32 v233, v22, v23
	v_cvt_pk_bf16_f32 v234, v16, v17
	v_cvt_pk_bf16_f32 v235, v18, v19
	v_mov_b32_e32 v236, v228
	v_mov_b32_e32 v237, v229
	v_mov_b32_e32 v238, v230
	v_mov_b32_e32 v239, v231
	v_mov_b32_dpp v228, v232 row_ror:8 row_mask:0xf bank_mask:0xc
	v_mov_b32_dpp v229, v233 row_ror:8 row_mask:0xf bank_mask:0xc
	v_mov_b32_dpp v230, v234 row_ror:8 row_mask:0xf bank_mask:0xc
	v_mov_b32_dpp v231, v235 row_ror:8 row_mask:0xf bank_mask:0xc
	v_mov_b32_dpp v232, v236 row_ror:8 row_mask:0xf bank_mask:0x3
	v_mov_b32_dpp v233, v237 row_ror:8 row_mask:0xf bank_mask:0x3
	v_mov_b32_dpp v234, v238 row_ror:8 row_mask:0xf bank_mask:0x3
	v_mov_b32_dpp v235, v239 row_ror:8 row_mask:0xf bank_mask:0x3
	s_add_u32 s100, s100, 0x8000
	s_addc_u32 s101, s101, 0
	global_store_dwordx4 v240, v[228:231], s[100:101]
	s_add_u32 s100, s100, 0x8000
	s_addc_u32 s101, s101, 0
	global_store_dwordx4 v240, v[232:235], s[100:101]
	v_cvt_pk_bf16_f32 v228, v12, v13
	v_cvt_pk_bf16_f32 v229, v14, v15
	v_cvt_pk_bf16_f32 v230, v8, v9
	v_cvt_pk_bf16_f32 v231, v10, v11
	v_cvt_pk_bf16_f32 v232, v4, v5
	v_cvt_pk_bf16_f32 v233, v6, v7
	v_cvt_pk_bf16_f32 v234, v0, v1
	v_cvt_pk_bf16_f32 v235, v2, v3
	v_mov_b32_e32 v236, v228
	v_mov_b32_e32 v237, v229
	v_mov_b32_e32 v238, v230
	v_mov_b32_e32 v239, v231
	v_mov_b32_dpp v228, v232 row_ror:8 row_mask:0xf bank_mask:0xc
	v_mov_b32_dpp v229, v233 row_ror:8 row_mask:0xf bank_mask:0xc
	v_mov_b32_dpp v230, v234 row_ror:8 row_mask:0xf bank_mask:0xc
	v_mov_b32_dpp v231, v235 row_ror:8 row_mask:0xf bank_mask:0xc
	v_mov_b32_dpp v232, v236 row_ror:8 row_mask:0xf bank_mask:0x3
	v_mov_b32_dpp v233, v237 row_ror:8 row_mask:0xf bank_mask:0x3
	v_mov_b32_dpp v234, v238 row_ror:8 row_mask:0xf bank_mask:0x3
	v_mov_b32_dpp v235, v239 row_ror:8 row_mask:0xf bank_mask:0x3
	s_add_u32 s100, s100, 0x8000
	s_addc_u32 s101, s101, 0
	global_store_dwordx4 v240, v[228:231], s[100:101]
	s_add_u32 s100, s100, 0x8000
	s_addc_u32 s101, s101, 0
	global_store_dwordx4 v240, v[232:235], s[100:101]
	s_mov_b32 s0, 0x80000
	s_mov_b32 s0, 0x90000
	s_nop 0
	s_mov_b32 s0, 0xa0000
	s_nop 0
	s_mov_b64 s[16:17], 0x80000
	s_mov_b64 s[16:17], 0x90000
	s_mov_b32 s0, 0xb0000
	s_mov_b64 s[16:17], 0xa0000
	s_mov_b64 s[16:17], 0xb0000
	s_mov_b64 s[16:17], 0x3c280000
	s_and_b64 vcc, exec, s[18:19]
	s_mov_b32 s46, s45
	s_mov_b32 s39, s6
	s_mov_b32 s0, s8
	s_mov_b64 s[26:27], s[22:23]
	s_mov_b64 s[24:25], s[20:21]
	s_cbranch_vccnz .LBB0_369

.LBB0_368:
	ds_read_b128 v[146:149], v143
	ds_read_b128 v[150:153], v143 offset:1024
	ds_read_b128 v[154:157], v143 offset:2048
	ds_read_b128 v[158:161], v143 offset:3072
	s_add_i32 s52, s26, 2
	s_add_u32 s27, s24, 0xfff80080
	s_addc_u32 s28, s25, -1
	s_cmp_eq_u32 s49, s26
	s_cselect_b32 s26, s48, s50
	s_cselect_b32 s29, s7, s28
	s_cselect_b32 s28, s9, s27
	s_cselect_b32 s27, s47, s51
	v_lshl_add_u64 v[194:195], s[24:25], 0, v[136:137]
	s_add_i32 m0, s1, 0xc000
	ds_read_b128 v[162:165], v144
	ds_read_b128 v[166:169], v144 offset:1024
	ds_read_b128 v[170:173], v144 offset:2048
	ds_read_b128 v[174:177], v144 offset:3072
	ds_read_b128 v[178:181], v144 offset:4096
	ds_read_b128 v[182:185], v144 offset:5120
	ds_read_b128 v[186:189], v144 offset:6144
	ds_read_b128 v[190:193], v144 offset:7168
	global_load_lds_dwordx4 v[194:195], off
	v_lshl_add_u64 v[194:195], s[24:25], 0, v[138:139]
	s_add_i32 m0, s1, 0xe000
	s_nop 0
	global_load_lds_dwordx4 v[194:195], off
	s_waitcnt lgkmcnt(8)
	s_barrier
	s_waitcnt lgkmcnt(0)
	s_setprio 1
	s_waitcnt lgkmcnt(0)
	v_mfma_f32_16x16x32_bf16 v[124:127], v[146:149], v[162:165], v[124:127]
	v_mfma_f32_16x16x32_bf16 v[120:123], v[154:157], v[162:165], v[120:123]
	v_mfma_f32_16x16x32_bf16 v[108:111], v[146:149], v[170:173], v[108:111]
	v_mfma_f32_16x16x32_bf16 v[104:107], v[154:157], v[170:173], v[104:107]
	v_mfma_f32_16x16x32_bf16 v[92:95], v[146:149], v[178:181], v[92:95]
	v_mfma_f32_16x16x32_bf16 v[88:91], v[154:157], v[178:181], v[88:91]
	v_mfma_f32_16x16x32_bf16 v[76:79], v[146:149], v[186:189], v[76:79]
	v_mfma_f32_16x16x32_bf16 v[72:75], v[154:157], v[186:189], v[72:75]
	v_mfma_f32_16x16x32_bf16 v[124:127], v[150:153], v[166:169], v[124:127]
	v_mfma_f32_16x16x32_bf16 v[120:123], v[158:161], v[166:169], v[120:123]
	v_mfma_f32_16x16x32_bf16 v[108:111], v[150:153], v[174:177], v[108:111]
	v_mfma_f32_16x16x32_bf16 v[104:107], v[158:161], v[174:177], v[104:107]
	v_mfma_f32_16x16x32_bf16 v[92:95], v[150:153], v[182:185], v[92:95]
	v_mfma_f32_16x16x32_bf16 v[88:91], v[158:161], v[182:185], v[88:91]
	v_mfma_f32_16x16x32_bf16 v[76:79], v[150:153], v[190:193], v[76:79]
	v_mfma_f32_16x16x32_bf16 v[72:75], v[158:161], v[190:193], v[72:75]
	s_setprio 0
	s_barrier
	s_add_i32 s53, s42, s31
	v_lshl_add_u64 v[212:213], s[26:27], 0, v[132:133]
	s_mov_b32 m0, s53
	ds_read_b128 v[194:197], v145
	ds_read_b128 v[198:201], v145 offset:1024
	ds_read_b128 v[204:207], v145 offset:2048
	ds_read_b128 v[208:211], v145 offset:3072
	global_load_lds_dwordx4 v[212:213], off
	v_lshl_add_u64 v[214:215], s[26:27], 0, v[128:129]
	s_add_i32 m0, s53, 0x2000
	s_nop 0
	global_load_lds_dwordx4 v[214:215], off
	s_barrier
	s_waitcnt lgkmcnt(0)
	s_setprio 1
	s_waitcnt lgkmcnt(0)
	v_mfma_f32_16x16x32_bf16 v[116:119], v[194:197], v[162:165], v[116:119]
	v_mfma_f32_16x16x32_bf16 v[112:115], v[204:207], v[162:165], v[112:115]
	v_mfma_f32_16x16x32_bf16 v[100:103], v[194:197], v[170:173], v[100:103]
	v_mfma_f32_16x16x32_bf16 v[96:99], v[204:207], v[170:173], v[96:99]
	v_mfma_f32_16x16x32_bf16 v[84:87], v[194:197], v[178:181], v[84:87]
	v_mfma_f32_16x16x32_bf16 v[80:83], v[204:207], v[178:181], v[80:83]
	v_mfma_f32_16x16x32_bf16 v[68:71], v[194:197], v[186:189], v[68:71]
	v_mfma_f32_16x16x32_bf16 v[64:67], v[204:207], v[186:189], v[64:67]
	v_mfma_f32_16x16x32_bf16 v[116:119], v[198:201], v[166:169], v[116:119]
	v_mfma_f32_16x16x32_bf16 v[112:115], v[208:211], v[166:169], v[112:115]
	v_mfma_f32_16x16x32_bf16 v[100:103], v[198:201], v[174:177], v[100:103]
	v_mfma_f32_16x16x32_bf16 v[96:99], v[208:211], v[174:177], v[96:99]
	v_mfma_f32_16x16x32_bf16 v[84:87], v[198:201], v[182:185], v[84:87]
	v_mfma_f32_16x16x32_bf16 v[80:83], v[208:211], v[182:185], v[80:83]
	v_mfma_f32_16x16x32_bf16 v[68:71], v[198:201], v[190:193], v[68:71]
	v_mfma_f32_16x16x32_bf16 v[64:67], v[208:211], v[190:193], v[64:67]
	s_setprio 0
	s_mov_b32 m0, s1
	v_lshl_add_u64 v[216:217], s[28:29], 0, v[134:135]
	s_barrier
	ds_read_b128 v[162:165], v144 offset:16384
	ds_read_b128 v[166:169], v144 offset:17408
	ds_read_b128 v[170:173], v144 offset:18432
	ds_read_b128 v[174:177], v144 offset:19456
	ds_read_b128 v[178:181], v144 offset:20480
	ds_read_b128 v[182:185], v144 offset:21504
	ds_read_b128 v[186:189], v144 offset:22528
	ds_read_b128 v[190:193], v144 offset:23552
	global_load_lds_dwordx4 v[216:217], off
	v_lshl_add_u64 v[218:219], s[28:29], 0, v[130:131]
	s_mov_b32 m0, s33
	s_nop 0
	global_load_lds_dwordx4 v[218:219], off
	s_barrier
	s_waitcnt lgkmcnt(0)
	s_setprio 1
	s_waitcnt lgkmcnt(0)
	v_mfma_f32_16x16x32_bf16 v[60:63], v[146:149], v[162:165], v[60:63]
	v_mfma_f32_16x16x32_bf16 v[56:59], v[154:157], v[162:165], v[56:59]
	v_mfma_f32_16x16x32_bf16 v[44:47], v[146:149], v[170:173], v[44:47]
	v_mfma_f32_16x16x32_bf16 v[40:43], v[154:157], v[170:173], v[40:43]
	v_mfma_f32_16x16x32_bf16 v[28:31], v[146:149], v[178:181], v[28:31]
	v_mfma_f32_16x16x32_bf16 v[24:27], v[154:157], v[178:181], v[24:27]
	v_mfma_f32_16x16x32_bf16 v[12:15], v[146:149], v[186:189], v[12:15]
	v_mfma_f32_16x16x32_bf16 v[8:11], v[154:157], v[186:189], v[8:11]
	v_mfma_f32_16x16x32_bf16 v[60:63], v[150:153], v[166:169], v[60:63]
	v_mfma_f32_16x16x32_bf16 v[56:59], v[158:161], v[166:169], v[56:59]
	v_mfma_f32_16x16x32_bf16 v[44:47], v[150:153], v[174:177], v[44:47]
	v_mfma_f32_16x16x32_bf16 v[40:43], v[158:161], v[174:177], v[40:43]
	v_mfma_f32_16x16x32_bf16 v[28:31], v[150:153], v[182:185], v[28:31]
	v_mfma_f32_16x16x32_bf16 v[24:27], v[158:161], v[182:185], v[24:27]
	v_mfma_f32_16x16x32_bf16 v[12:15], v[150:153], v[190:193], v[12:15]
	v_mfma_f32_16x16x32_bf16 v[8:11], v[158:161], v[190:193], v[8:11]
	s_setprio 0
	s_barrier
	s_add_u32 s54, s26, 0x20000
	s_addc_u32 s55, s27, 0
	s_add_i32 s53, s43, s31
	v_lshl_add_u64 v[146:147], s[54:55], 0, v[132:133]
	s_mov_b32 m0, s53
	s_nop 0
	global_load_lds_dwordx4 v[146:147], off
	v_lshl_add_u64 v[146:147], s[54:55], 0, v[128:129]
	s_add_i32 m0, s53, 0x2000
	s_nop 0
	global_load_lds_dwordx4 v[146:147], off
	s_waitcnt vmcnt(6)
	s_barrier
	s_setprio 1
	v_mfma_f32_16x16x32_bf16 v[52:55], v[194:197], v[162:165], v[52:55]
	v_mfma_f32_16x16x32_bf16 v[48:51], v[204:207], v[162:165], v[48:51]
	v_mfma_f32_16x16x32_bf16 v[36:39], v[194:197], v[170:173], v[36:39]
	v_mfma_f32_16x16x32_bf16 v[32:35], v[204:207], v[170:173], v[32:35]
	v_mfma_f32_16x16x32_bf16 v[20:23], v[194:197], v[178:181], v[20:23]
	v_mfma_f32_16x16x32_bf16 v[16:19], v[204:207], v[178:181], v[16:19]
	v_mfma_f32_16x16x32_bf16 v[4:7], v[194:197], v[186:189], v[4:7]
	v_mfma_f32_16x16x32_bf16 v[0:3], v[204:207], v[186:189], v[0:3]
	v_mfma_f32_16x16x32_bf16 v[52:55], v[198:201], v[166:169], v[52:55]
	v_mfma_f32_16x16x32_bf16 v[48:51], v[208:211], v[166:169], v[48:51]
	v_mfma_f32_16x16x32_bf16 v[36:39], v[198:201], v[174:177], v[36:39]
	v_mfma_f32_16x16x32_bf16 v[32:35], v[208:211], v[174:177], v[32:35]
	v_mfma_f32_16x16x32_bf16 v[20:23], v[198:201], v[182:185], v[20:23]
	v_mfma_f32_16x16x32_bf16 v[16:19], v[208:211], v[182:185], v[16:19]
	v_mfma_f32_16x16x32_bf16 v[4:7], v[198:201], v[190:193], v[4:7]
	v_mfma_f32_16x16x32_bf16 v[0:3], v[208:211], v[190:193], v[0:3]
	s_setprio 0
	s_add_i32 s53, 0, 0x18000
	v_add_u32_e32 v158, s53, v141
	s_barrier
	ds_read_b128 v[146:149], v158
	ds_read_b128 v[150:153], v158 offset:1024
	ds_read_b128 v[154:157], v158 offset:2048
	ds_read_b128 v[158:161], v158 offset:3072
	s_add_u32 s28, s28, 0x80000
	s_addc_u32 s29, s29, 0
	s_mov_b32 m0, s34
	v_lshl_add_u64 v[194:195], s[28:29], 0, v[134:135]
	ds_read_b128 v[162:165], v144 offset:32768
	ds_read_b128 v[166:169], v144 offset:33792
	ds_read_b128 v[170:173], v144 offset:34816
	ds_read_b128 v[174:177], v144 offset:35840
	ds_read_b128 v[178:181], v144 offset:36864
	ds_read_b128 v[182:185], v144 offset:37888
	ds_read_b128 v[186:189], v144 offset:38912
	ds_read_b128 v[190:193], v144 offset:39936
	global_load_lds_dwordx4 v[194:195], off
	v_lshl_add_u64 v[194:195], s[28:29], 0, v[130:131]
	s_mov_b32 m0, s35
	s_nop 0
	global_load_lds_dwordx4 v[194:195], off
	s_waitcnt lgkmcnt(8)
	s_barrier
	s_waitcnt lgkmcnt(0)
	s_setprio 1
	s_waitcnt lgkmcnt(0)
	v_mfma_f32_16x16x32_bf16 v[124:127], v[146:149], v[162:165], v[124:127]
	v_mfma_f32_16x16x32_bf16 v[120:123], v[154:157], v[162:165], v[120:123]
	v_mfma_f32_16x16x32_bf16 v[108:111], v[146:149], v[170:173], v[108:111]
	v_mfma_f32_16x16x32_bf16 v[104:107], v[154:157], v[170:173], v[104:107]
	v_mfma_f32_16x16x32_bf16 v[92:95], v[146:149], v[178:181], v[92:95]
	v_mfma_f32_16x16x32_bf16 v[88:91], v[154:157], v[178:181], v[88:91]
	v_mfma_f32_16x16x32_bf16 v[76:79], v[146:149], v[186:189], v[76:79]
	v_mfma_f32_16x16x32_bf16 v[72:75], v[154:157], v[186:189], v[72:75]
	v_mfma_f32_16x16x32_bf16 v[124:127], v[150:153], v[166:169], v[124:127]
	v_mfma_f32_16x16x32_bf16 v[120:123], v[158:161], v[166:169], v[120:123]
	v_mfma_f32_16x16x32_bf16 v[108:111], v[150:153], v[174:177], v[108:111]
	v_mfma_f32_16x16x32_bf16 v[104:107], v[158:161], v[174:177], v[104:107]
	v_mfma_f32_16x16x32_bf16 v[92:95], v[150:153], v[182:185], v[92:95]
	v_mfma_f32_16x16x32_bf16 v[88:91], v[158:161], v[182:185], v[88:91]
	v_mfma_f32_16x16x32_bf16 v[76:79], v[150:153], v[190:193], v[76:79]
	v_mfma_f32_16x16x32_bf16 v[72:75], v[158:161], v[190:193], v[72:75]
	s_setprio 0
	s_barrier
	s_add_i32 s28, 0, 0x1c000
	s_add_i32 s29, s53, s31
	v_add_u32_e32 v208, s28, v141
	v_lshl_add_u64 v[212:213], v[212:213], 0, s[2:3]
	s_mov_b32 m0, s29
	ds_read_b128 v[194:197], v208
	ds_read_b128 v[198:201], v208 offset:1024
	ds_read_b128 v[204:207], v208 offset:2048
	ds_read_b128 v[208:211], v208 offset:3072
	global_load_lds_dwordx4 v[212:213], off
	v_lshl_add_u64 v[212:213], v[214:215], 0, s[2:3]
	s_add_i32 m0, s29, 0x2000
	s_nop 0
	global_load_lds_dwordx4 v[212:213], off
	s_barrier
	s_waitcnt lgkmcnt(0)
	s_setprio 1
	s_waitcnt lgkmcnt(0)
	v_mfma_f32_16x16x32_bf16 v[116:119], v[194:197], v[162:165], v[116:119]
	v_mfma_f32_16x16x32_bf16 v[112:115], v[204:207], v[162:165], v[112:115]
	v_mfma_f32_16x16x32_bf16 v[100:103], v[194:197], v[170:173], v[100:103]
	v_mfma_f32_16x16x32_bf16 v[96:99], v[204:207], v[170:173], v[96:99]
	v_mfma_f32_16x16x32_bf16 v[84:87], v[194:197], v[178:181], v[84:87]
	v_mfma_f32_16x16x32_bf16 v[80:83], v[204:207], v[178:181], v[80:83]
	v_mfma_f32_16x16x32_bf16 v[68:71], v[194:197], v[186:189], v[68:71]
	v_mfma_f32_16x16x32_bf16 v[64:67], v[204:207], v[186:189], v[64:67]
	v_mfma_f32_16x16x32_bf16 v[116:119], v[198:201], v[166:169], v[116:119]
	v_mfma_f32_16x16x32_bf16 v[112:115], v[208:211], v[166:169], v[112:115]
	v_mfma_f32_16x16x32_bf16 v[100:103], v[198:201], v[174:177], v[100:103]
	v_mfma_f32_16x16x32_bf16 v[96:99], v[208:211], v[174:177], v[96:99]
	v_mfma_f32_16x16x32_bf16 v[84:87], v[198:201], v[182:185], v[84:87]
	v_mfma_f32_16x16x32_bf16 v[80:83], v[208:211], v[182:185], v[80:83]
	v_mfma_f32_16x16x32_bf16 v[68:71], v[198:201], v[190:193], v[68:71]
	v_mfma_f32_16x16x32_bf16 v[64:67], v[208:211], v[190:193], v[64:67]
	s_setprio 0
	s_mov_b32 m0, s40
	v_lshl_add_u64 v[212:213], v[216:217], 0, s[2:3]
	s_barrier
	ds_read_b128 v[162:165], v144 offset:49152
	ds_read_b128 v[166:169], v144 offset:50176
	ds_read_b128 v[170:173], v144 offset:51200
	ds_read_b128 v[174:177], v144 offset:52224
	ds_read_b128 v[178:181], v144 offset:53248
	ds_read_b128 v[182:185], v144 offset:54272
	ds_read_b128 v[186:189], v144 offset:55296
	ds_read_b128 v[190:193], v144 offset:56320
	global_load_lds_dwordx4 v[212:213], off
	v_lshl_add_u64 v[212:213], v[218:219], 0, s[2:3]
	s_mov_b32 m0, s41
	s_nop 0
	global_load_lds_dwordx4 v[212:213], off
	s_barrier
	s_waitcnt lgkmcnt(0)
	s_setprio 1
	s_waitcnt lgkmcnt(0)
	v_mfma_f32_16x16x32_bf16 v[60:63], v[146:149], v[162:165], v[60:63]
	v_mfma_f32_16x16x32_bf16 v[56:59], v[154:157], v[162:165], v[56:59]
	v_mfma_f32_16x16x32_bf16 v[44:47], v[146:149], v[170:173], v[44:47]
	v_mfma_f32_16x16x32_bf16 v[40:43], v[154:157], v[170:173], v[40:43]
	v_mfma_f32_16x16x32_bf16 v[28:31], v[146:149], v[178:181], v[28:31]
	v_mfma_f32_16x16x32_bf16 v[24:27], v[154:157], v[178:181], v[24:27]
	v_mfma_f32_16x16x32_bf16 v[12:15], v[146:149], v[186:189], v[12:15]
	v_mfma_f32_16x16x32_bf16 v[8:11], v[154:157], v[186:189], v[8:11]
	v_mfma_f32_16x16x32_bf16 v[60:63], v[150:153], v[166:169], v[60:63]
	v_mfma_f32_16x16x32_bf16 v[56:59], v[158:161], v[166:169], v[56:59]
	v_mfma_f32_16x16x32_bf16 v[44:47], v[150:153], v[174:177], v[44:47]
	v_mfma_f32_16x16x32_bf16 v[40:43], v[158:161], v[174:177], v[40:43]
	v_mfma_f32_16x16x32_bf16 v[28:31], v[150:153], v[182:185], v[28:31]
	v_mfma_f32_16x16x32_bf16 v[24:27], v[158:161], v[182:185], v[24:27]
	v_mfma_f32_16x16x32_bf16 v[12:15], v[150:153], v[190:193], v[12:15]
	v_mfma_f32_16x16x32_bf16 v[8:11], v[158:161], v[190:193], v[8:11]
	s_setprio 0
	s_barrier
	s_add_u32 s26, s26, 0x20080
	s_addc_u32 s27, s27, 0
	s_add_i32 s28, s28, s31
	v_lshl_add_u64 v[146:147], s[26:27], 0, v[132:133]
	s_mov_b32 m0, s28
	s_nop 0
	global_load_lds_dwordx4 v[146:147], off
	v_lshl_add_u64 v[146:147], s[26:27], 0, v[128:129]
	s_add_i32 m0, s28, 0x2000
	s_nop 0
	global_load_lds_dwordx4 v[146:147], off
	s_waitcnt vmcnt(6)
	s_barrier
	s_setprio 1
	v_mfma_f32_16x16x32_bf16 v[52:55], v[194:197], v[162:165], v[52:55]
	v_mfma_f32_16x16x32_bf16 v[48:51], v[204:207], v[162:165], v[48:51]
	v_mfma_f32_16x16x32_bf16 v[36:39], v[194:197], v[170:173], v[36:39]
	v_mfma_f32_16x16x32_bf16 v[32:35], v[204:207], v[170:173], v[32:35]
	v_mfma_f32_16x16x32_bf16 v[20:23], v[194:197], v[178:181], v[20:23]
	v_mfma_f32_16x16x32_bf16 v[16:19], v[204:207], v[178:181], v[16:19]
	v_mfma_f32_16x16x32_bf16 v[4:7], v[194:197], v[186:189], v[4:7]
	v_mfma_f32_16x16x32_bf16 v[0:3], v[204:207], v[186:189], v[0:3]
	v_mfma_f32_16x16x32_bf16 v[52:55], v[198:201], v[166:169], v[52:55]
	v_mfma_f32_16x16x32_bf16 v[48:51], v[208:211], v[166:169], v[48:51]
	v_mfma_f32_16x16x32_bf16 v[36:39], v[198:201], v[174:177], v[36:39]
	v_mfma_f32_16x16x32_bf16 v[32:35], v[208:211], v[174:177], v[32:35]
	v_mfma_f32_16x16x32_bf16 v[20:23], v[198:201], v[182:185], v[20:23]
	v_mfma_f32_16x16x32_bf16 v[16:19], v[208:211], v[182:185], v[16:19]
	v_mfma_f32_16x16x32_bf16 v[4:7], v[198:201], v[190:193], v[4:7]
	v_mfma_f32_16x16x32_bf16 v[0:3], v[208:211], v[190:193], v[0:3]
	s_setprio 0
	s_add_u32 s24, s24, 0x100
	s_addc_u32 s25, s25, 0
	s_add_u32 s50, s50, 0x100
	s_addc_u32 s51, s51, 0
	s_cmp_ge_i32 s52, s46
	s_mov_b32 s26, s52
	s_barrier
	s_cbranch_scc0 .LBB0_368
	s_branch .LBB0_363

.LBB0_634:
	s_or_b64 exec, exec, s[0:1]
	v_readlane_b32 s0, v247, 17
	s_mul_hi_u32 s0, s0, 0x9000
	v_readlane_b32 s4, v247, 18
	s_mul_i32 s1, s0, s4
	s_sub_i32 s1, 0x9000, s1
	s_add_i32 s2, s0, 1
	s_sub_i32 s3, s1, s4
	s_cmp_ge_u32 s1, s4
	s_cselect_b32 s0, s2, s0
	s_cselect_b32 s1, s3, s1
	s_add_i32 s2, s0, 1
	s_cmp_ge_u32 s1, s4
	s_cselect_b32 s0, s2, s0
	v_readlane_b32 s1, v247, 11
	s_xor_b32 s0, s0, s1
	s_sub_i32 s0, s0, s1
	s_cmp_gt_i32 s0, 0
	s_mul_i32 s6, s0, s42
	s_cselect_b64 s[8:9], -1, 0
	s_add_i32 s4, s6, s0
	s_ashr_i32 s0, s6, 31
	s_mul_hi_i32 s2, s6, 0x38e38e39
	s_lshr_b32 s0, s0, 25
	s_lshr_b32 s3, s2, 31
	s_ashr_i32 s2, s2, 8
	s_add_i32 s0, s6, s0
	s_add_i32 s2, s2, s3
	s_ashr_i32 s1, s0, 7
	s_mul_i32 s3, s2, -9
	s_and_b32 s7, s0, 0xffffff80
	s_add_i32 s3, s3, s1
	s_add_i32 s0, s7, 0x80
	v_writelane_b32 v247, s4, 3
	s_and_b32 s1, s2, 7
	v_writelane_b32 v247, s0, 1
	s_min_i32 s0, s0, s4
	v_writelane_b32 v248, s1, 58
	s_lshl_b32 s1, s3, 2
	s_ashr_i32 s2, s2, 3
	s_add_i32 s2, s1, s2
	s_sub_i32 s33, s0, s6
	s_add_i32 s0, s7, 0x100
	v_writelane_b32 v247, s0, 2
	s_cmp_eq_u32 s6, s7
	s_mov_b32 s0, 0x3c280000
	s_mov_b32 s5, 0
	s_cselect_b32 s4, s0, 0x39e80000
	v_writelane_b32 v248, s2, 61
	v_writelane_b32 v247, s4, 4
	v_mov_b32_e32 v10, v202
	v_writelane_b32 v248, s3, 62
	v_writelane_b32 v247, s5, 5
	s_waitcnt lgkmcnt(0)
	s_barrier
	v_writelane_b32 v248, s6, 59
	v_writelane_b32 v247, s8, 12
	v_readfirstlane_b32 s22, v10
	s_and_b64 vcc, exec, s[8:9]
	v_writelane_b32 v248, s7, 60
	v_writelane_b32 v247, s9, 13
	s_cbranch_vccz .LBB0_648
	v_lshlrev_b32_e32 v0, 4, v10
	v_add_u32_e32 v1, 0x2000, v0
	v_ashrrev_i32_e32 v2, 31, v1
	v_lshrrev_b32_e32 v2, 22, v2
	v_add_u32_e32 v2, v1, v2
	v_ashrrev_i32_e32 v8, 10, v2
	v_mul_i32_i24_e32 v2, 0x400, v8
	v_sub_u32_e32 v1, v1, v2
	v_lshrrev_b32_e32 v2, 4, v1
	v_bitop3_b32 v1, v2, v1, 32 bitop3:0x6c
	v_ashrrev_i32_e32 v2, 31, v1
	v_lshrrev_b32_e32 v2, 26, v2
	v_add_u32_e32 v2, v1, v2
	v_lshlrev_b32_e32 v3, 3, v8
	v_ashrrev_i32_e32 v9, 6, v2
	v_and_b32_e32 v3, -16, v3
	s_add_u32 s23, s58, 0x4000000
	v_readlane_b32 s3, v248, 59
	v_readlane_b32 s4, v248, 60
	v_add_u32_e32 v3, v9, v3
	s_addc_u32 s24, s59, 0
	s_sub_i32 s4, s3, s4
	v_and_b32_e32 v4, 3, v9
	s_mov_b32 s3, 0x3ffe0
	v_lshrrev_b32_e32 v5, 2, v3
	v_lshlrev_b32_e32 v6, 1, v3
	v_and_b32_e32 v2, 0xc0, v2
	v_and_or_b32 v4, v3, s3, v4
	v_and_b32_e32 v5, 4, v5
	v_and_b32_e32 v6, 24, v6
	v_sub_u32_e32 v1, v1, v2
	v_mov_b32_e32 v2, 1
	v_or3_b32 v4, v4, v5, v6
	v_lshlrev_b32_e32 v5, 5, v8
	v_ashrrev_i16_sdwa v1, v2, sext(v1) dst_sel:DWORD dst_unused:UNUSED_PAD src0_sel:DWORD src1_sel:BYTE_0
	v_and_b32_e32 v5, 32, v5
	v_bfe_i32 v11, v1, 0, 16
	v_add_lshl_u32 v1, v5, v11, 1
	v_lshl_add_u32 v128, v4, 14, v1
	v_lshl_add_u32 v130, v3, 14, v1
	v_bfe_i32 v1, v10, 27, 1
	v_lshrrev_b32_e32 v1, 22, v1
	v_add_u32_e32 v1, v0, v1
	v_and_b32_e32 v1, 0xfffffc00, v1
	v_sub_u32_e32 v0, v0, v1
	v_lshrrev_b32_e32 v1, 4, v0
	v_ashrrev_i32_e32 v3, 31, v10
	v_bitop3_b32 v0, v1, v0, 32 bitop3:0x6c
	v_lshrrev_b32_e32 v3, 26, v3
	v_ashrrev_i32_e32 v1, 31, v0
	v_add_u32_e32 v3, v10, v3
	v_lshrrev_b32_e32 v1, 26, v1
	v_ashrrev_i32_e32 v13, 6, v3
	v_readlane_b32 s12, v248, 61
	v_add_u32_e32 v1, v0, v1
	v_lshlrev_b32_e32 v3, 3, v13
	v_readlane_b32 s13, v248, 62
	v_ashrrev_i32_e32 v12, 6, v1
	v_and_b32_e32 v3, -16, v3
	s_ashr_i32 s0, s22, 6
	v_readlane_b32 s1, v248, 58
	s_ashr_i32 s5, s4, 31
	s_ashr_i32 s13, s12, 31
	v_add_u32_e32 v3, v12, v3
	s_ashr_i32 s2, s22, 8
	s_lshl_b32 s25, s0, 10
	s_lshl_b32 s1, s1, 22
	s_lshl_b64 s[4:5], s[4:5], 7
	s_lshl_b64 s[6:7], s[12:13], 22
	v_and_b32_e32 v4, 3, v12
	v_lshrrev_b32_e32 v5, 2, v3
	v_lshlrev_b32_e32 v6, 1, v3
	v_and_b32_e32 v1, 0xc0, v1
	v_and_or_b32 v4, v3, s3, v4
	v_and_b32_e32 v5, 4, v5
	v_and_b32_e32 v6, 24, v6
	v_sub_u32_e32 v0, v0, v1
	s_add_u32 s1, s23, s1
	v_or3_b32 v4, v4, v5, v6
	v_lshlrev_b32_e32 v5, 5, v13
	v_ashrrev_i16_sdwa v0, v2, sext(v0) dst_sel:DWORD dst_unused:UNUSED_PAD src0_sel:DWORD src1_sel:BYTE_0
	s_addc_u32 s3, s24, 0
	v_and_b32_e32 v5, 32, v5
	v_bfe_i32 v14, v0, 0, 16
	s_add_u32 s18, s1, s4
	v_add_lshl_u32 v0, v5, v14, 1
	s_addc_u32 s19, s3, s5
	s_add_i32 s26, s25, 0
	v_lshl_add_u32 v132, v4, 14, v0
	s_add_i32 m0, s26, 0x10000
	v_readlane_b32 s8, v248, 63
	v_mov_b32_e32 v230, s2
	v_lshlrev_b32_e32 v230, 19, v230
	v_add_u32_e32 v132, v132, v230
	v_add_u32_e32 v230, 0x100000, v230
	v_add_u32_e32 v128, v128, v230
	global_load_lds_dwordx4 v132, s[18:19]
	s_add_i32 m0, s26, 0x12000
	v_readlane_b32 s9, v247, 0
	s_add_u32 s1, s8, s6
	s_addc_u32 s3, s9, s7
	s_add_u32 s16, s1, s4
	v_lshl_add_u32 v134, v3, 14, v0
	global_load_lds_dwordx4 v128, s[18:19]
	s_addc_u32 s17, s3, s5
	s_mov_b32 m0, s26
	s_add_i32 s27, s26, 0x2000
	global_load_lds_dwordx4 v134, s[16:17]
	s_mov_b32 m0, s27
	s_add_u32 s4, s18, 0x80000
	global_load_lds_dwordx4 v130, s[16:17]
	s_addc_u32 s5, s19, 0
	s_add_i32 m0, s26, 0x14000
	v_mov_b32_e32 v133, 0
	global_load_lds_dwordx4 v132, s[4:5]
	s_add_i32 m0, s26, 0x16000
	v_mov_b32_e32 v129, v133
	global_load_lds_dwordx4 v128, s[4:5]
	s_add_u32 s4, s16, 0x200000
	s_addc_u32 s5, s17, 0
	s_add_i32 s28, s26, 0x4000
	s_mov_b32 m0, s28
	s_add_i32 s29, s26, 0x6000
	global_load_lds_dwordx4 v134, s[4:5]
	s_mov_b32 m0, s29
	v_mov_b32_e32 v135, v133
	global_load_lds_dwordx4 v130, s[4:5]
	v_mov_b32_e32 v131, v133
	v_lshl_add_u64 v[6:7], s[18:19], 0, v[132:133]
	v_lshl_add_u64 v[4:5], s[18:19], 0, v[128:129]
	v_lshl_add_u64 v[2:3], s[16:17], 0, v[134:135]
	s_cmp_lg_u32 s2, 1
	v_lshl_add_u64 v[0:1], s[16:17], 0, v[130:131]
	s_cbranch_scc1 .LBB0_637
	s_barrier
.LBB0_637:
	s_lshl_b32 s0, s0, 5
	s_and_b32 s6, s0, 0x60
	s_mov_b64 s[0:1], 0x80
	s_add_i32 m0, s26, 0x18000
	v_lshl_add_u64 v[6:7], v[6:7], 0, s[0:1]
	s_lshl_b32 s3, s2, 13
	s_lshl_b32 s7, s6, 7
	s_waitcnt vmcnt(4)
	s_barrier
	global_load_lds_dwordx4 v[6:7], off
	v_lshl_add_u64 v[4:5], v[4:5], 0, s[0:1]
	s_add_i32 m0, s26, 0x1a000
	s_add_i32 s30, s26, 0x8000
	s_add_i32 s31, s26, 0xa000
	global_load_lds_dwordx4 v[4:5], off
	v_lshl_add_u64 v[2:3], v[2:3], 0, s[0:1]
	s_mov_b32 m0, s30
	s_add_u32 s4, s18, 0x80080
	global_load_lds_dwordx4 v[2:3], off
	v_lshl_add_u64 v[0:1], v[0:1], 0, s[0:1]
	s_mov_b32 m0, s31
	s_addc_u32 s5, s19, 0
	global_load_lds_dwordx4 v[0:1], off
	s_add_i32 m0, s26, 0x1c000
	v_lshl_add_u64 v[0:1], s[4:5], 0, v[132:133]
	global_load_lds_dwordx4 v[0:1], off
	v_lshl_add_u64 v[0:1], s[4:5], 0, v[128:129]
	s_add_i32 m0, s26, 0x1e000
	s_add_i32 s35, 0, 0x10000
	global_load_lds_dwordx4 v[0:1], off
	v_lshrrev_b32_e32 v1, 1, v10
	v_and_b32_e32 v1, 24, v1
	v_and_b32_e32 v0, 15, v10
	v_lshlrev_b32_e32 v2, 1, v1
	v_lshl_or_b32 v140, s2, 6, v0
	v_lshl_or_b32 v0, v0, 6, v2
	v_lshlrev_b32_e32 v2, 2, v10
	v_and_b32_e32 v2, 32, v2
	v_bitop3_b32 v3, v0, s3, v2 bitop3:0xde
	v_bitop3_b32 v141, v0, s7, v2 bitop3:0xde
	v_lshlrev_b32_e32 v0, 17, v13
	v_and_b32_e32 v0, 0xfffc0000, v0
	v_or_b32_e32 v142, s6, v1
	v_lshl_add_u32 v0, v12, 14, v0
	v_and_b32_e32 v1, 1, v13
	v_lshl_or_b32 v0, v1, 6, v0
	v_lshl_add_u32 v136, v14, 1, v0
	v_lshlrev_b32_e32 v0, 17, v8
	v_and_b32_e32 v0, 0xfffc0000, v0
	s_waitcnt vmcnt(6)
	v_lshl_add_u32 v0, v9, 14, v0
	v_and_b32_e32 v1, 1, v8
	v_lshl_or_b32 v0, v1, 6, v0
	s_add_i32 s36, 0, 0x14000
	v_readlane_b32 s14, v247, 4
	s_mov_b32 s2, s12
	s_mov_b32 s34, 0
	v_mov_b32_e32 v137, v133
	v_lshl_add_u32 v138, v11, 1, v0
	v_mov_b32_e32 v139, v133
	v_add_u32_e32 v143, s35, v141
	v_add_u32_e32 v144, 0, v3
	v_add_u32_e32 v145, s36, v141
	s_mov_b32 s40, s33
	v_readlane_b32 s15, v247, 5
	v_readlane_b32 s39, v248, 58
	v_writelane_b32 v248, s2, 61
	s_mov_b32 s38, s12
	s_barrier
	v_writelane_b32 v248, s3, 62
	s_branch .LBB0_640

.LBB0_639:
	s_add_i32 s34, s34, 1
	s_add_u32 s14, s58, s14
	s_addc_u32 s15, s59, s15
	s_mov_b32 s100, s14
	s_mov_b32 s101, s15
	v_and_b32_e32 v242, 15, v202
	v_bfe_u32 v243, v202, 4, 2
	v_bfe_u32 v244, v202, 6, 2
	v_lshrrev_b32_e32 v245, 8, v202
	v_and_b32_e32 v240, 7, v242
	v_lshl_add_u32 v240, v245, 6, v240
	v_lshl_add_u32 v240, s38, 8, v240
	v_lshlrev_b32_e32 v240, 12, v240
	v_lshrrev_b32_e32 v241, 3, v242
	v_lshlrev_b32_e32 v241, 6, v241
	v_lshl_add_u32 v241, v244, 7, v241
	v_lshl_add_u32 v241, v243, 4, v241
	v_add_u32_e32 v240, v240, v241
	s_lshl_b32 s98, s39, 9
	v_add_u32_e32 v240, s98, v240
	v_cvt_pk_bf16_f32 v228, v124, v125
	v_cvt_pk_bf16_f32 v229, v126, v127
	v_cvt_pk_bf16_f32 v230, v120, v121
	v_cvt_pk_bf16_f32 v231, v122, v123
	v_cvt_pk_bf16_f32 v232, v116, v117
	v_cvt_pk_bf16_f32 v233, v118, v119
	v_cvt_pk_bf16_f32 v234, v112, v113
	v_cvt_pk_bf16_f32 v235, v114, v115
	v_mov_b32_e32 v236, v228
	v_mov_b32_e32 v237, v229
	v_mov_b32_e32 v238, v230
	v_mov_b32_e32 v239, v231
	v_mov_b32_dpp v228, v232 row_ror:8 row_mask:0xf bank_mask:0xc
	v_mov_b32_dpp v229, v233 row_ror:8 row_mask:0xf bank_mask:0xc
	v_mov_b32_dpp v230, v234 row_ror:8 row_mask:0xf bank_mask:0xc
	v_mov_b32_dpp v231, v235 row_ror:8 row_mask:0xf bank_mask:0xc
	v_mov_b32_dpp v232, v236 row_ror:8 row_mask:0xf bank_mask:0x3
	v_mov_b32_dpp v233, v237 row_ror:8 row_mask:0xf bank_mask:0x3
	v_mov_b32_dpp v234, v238 row_ror:8 row_mask:0xf bank_mask:0x3
	v_mov_b32_dpp v235, v239 row_ror:8 row_mask:0xf bank_mask:0x3
	global_store_dwordx4 v240, v[228:231], s[100:101]
	s_add_u32 s100, s100, 0x8000
	s_addc_u32 s101, s101, 0
	global_store_dwordx4 v240, v[232:235], s[100:101]
	v_cvt_pk_bf16_f32 v228, v108, v109
	v_cvt_pk_bf16_f32 v229, v110, v111
	v_cvt_pk_bf16_f32 v230, v104, v105
	v_cvt_pk_bf16_f32 v231, v106, v107
	v_cvt_pk_bf16_f32 v232, v100, v101
	v_cvt_pk_bf16_f32 v233, v102, v103
	v_cvt_pk_bf16_f32 v234, v96, v97
	v_cvt_pk_bf16_f32 v235, v98, v99
	v_mov_b32_e32 v236, v228
	v_mov_b32_e32 v237, v229
	v_mov_b32_e32 v238, v230
	v_mov_b32_e32 v239, v231
	v_mov_b32_dpp v228, v232 row_ror:8 row_mask:0xf bank_mask:0xc
	v_mov_b32_dpp v229, v233 row_ror:8 row_mask:0xf bank_mask:0xc
	v_mov_b32_dpp v230, v234 row_ror:8 row_mask:0xf bank_mask:0xc
	v_mov_b32_dpp v231, v235 row_ror:8 row_mask:0xf bank_mask:0xc
	v_mov_b32_dpp v232, v236 row_ror:8 row_mask:0xf bank_mask:0x3
	v_mov_b32_dpp v233, v237 row_ror:8 row_mask:0xf bank_mask:0x3
	v_mov_b32_dpp v234, v238 row_ror:8 row_mask:0xf bank_mask:0x3
	v_mov_b32_dpp v235, v239 row_ror:8 row_mask:0xf bank_mask:0x3
	s_add_u32 s100, s100, 0x8000
	s_addc_u32 s101, s101, 0
	global_store_dwordx4 v240, v[228:231], s[100:101]
	s_add_u32 s100, s100, 0x8000
	s_addc_u32 s101, s101, 0
	global_store_dwordx4 v240, v[232:235], s[100:101]
	v_cvt_pk_bf16_f32 v228, v92, v93
	v_cvt_pk_bf16_f32 v229, v94, v95
	v_cvt_pk_bf16_f32 v230, v88, v89
	v_cvt_pk_bf16_f32 v231, v90, v91
	v_cvt_pk_bf16_f32 v232, v84, v85
	v_cvt_pk_bf16_f32 v233, v86, v87
	v_cvt_pk_bf16_f32 v234, v80, v81
	v_cvt_pk_bf16_f32 v235, v82, v83
	v_mov_b32_e32 v236, v228
	v_mov_b32_e32 v237, v229
	v_mov_b32_e32 v238, v230
	v_mov_b32_e32 v239, v231
	v_mov_b32_dpp v228, v232 row_ror:8 row_mask:0xf bank_mask:0xc
	v_mov_b32_dpp v229, v233 row_ror:8 row_mask:0xf bank_mask:0xc
	v_mov_b32_dpp v230, v234 row_ror:8 row_mask:0xf bank_mask:0xc
	v_mov_b32_dpp v231, v235 row_ror:8 row_mask:0xf bank_mask:0xc
	v_mov_b32_dpp v232, v236 row_ror:8 row_mask:0xf bank_mask:0x3
	v_mov_b32_dpp v233, v237 row_ror:8 row_mask:0xf bank_mask:0x3
	v_mov_b32_dpp v234, v238 row_ror:8 row_mask:0xf bank_mask:0x3
	v_mov_b32_dpp v235, v239 row_ror:8 row_mask:0xf bank_mask:0x3
	s_add_u32 s100, s100, 0x8000
	s_addc_u32 s101, s101, 0
	global_store_dwordx4 v240, v[228:231], s[100:101]
	s_add_u32 s100, s100, 0x8000
	s_addc_u32 s101, s101, 0
	global_store_dwordx4 v240, v[232:235], s[100:101]
	v_cvt_pk_bf16_f32 v228, v76, v77
	v_cvt_pk_bf16_f32 v229, v78, v79
	v_cvt_pk_bf16_f32 v230, v72, v73
	v_cvt_pk_bf16_f32 v231, v74, v75
	v_cvt_pk_bf16_f32 v232, v68, v69
	v_cvt_pk_bf16_f32 v233, v70, v71
	v_cvt_pk_bf16_f32 v234, v64, v65
	v_cvt_pk_bf16_f32 v235, v66, v67
	v_mov_b32_e32 v236, v228
	v_mov_b32_e32 v237, v229
	v_mov_b32_e32 v238, v230
	v_mov_b32_e32 v239, v231
	v_mov_b32_dpp v228, v232 row_ror:8 row_mask:0xf bank_mask:0xc
	v_mov_b32_dpp v229, v233 row_ror:8 row_mask:0xf bank_mask:0xc
	v_mov_b32_dpp v230, v234 row_ror:8 row_mask:0xf bank_mask:0xc
	v_mov_b32_dpp v231, v235 row_ror:8 row_mask:0xf bank_mask:0xc
	v_mov_b32_dpp v232, v236 row_ror:8 row_mask:0xf bank_mask:0x3
	v_mov_b32_dpp v233, v237 row_ror:8 row_mask:0xf bank_mask:0x3
	v_mov_b32_dpp v234, v238 row_ror:8 row_mask:0xf bank_mask:0x3
	v_mov_b32_dpp v235, v239 row_ror:8 row_mask:0xf bank_mask:0x3
	s_add_u32 s100, s100, 0x8000
	s_addc_u32 s101, s101, 0
	global_store_dwordx4 v240, v[228:231], s[100:101]
	s_add_u32 s100, s100, 0x8000
	s_addc_u32 s101, s101, 0
	global_store_dwordx4 v240, v[232:235], s[100:101]
	v_cvt_pk_bf16_f32 v228, v60, v61
	v_cvt_pk_bf16_f32 v229, v62, v63
	v_cvt_pk_bf16_f32 v230, v56, v57
	v_cvt_pk_bf16_f32 v231, v58, v59
	v_cvt_pk_bf16_f32 v232, v52, v53
	v_cvt_pk_bf16_f32 v233, v54, v55
	v_cvt_pk_bf16_f32 v234, v48, v49
	v_cvt_pk_bf16_f32 v235, v50, v51
	v_mov_b32_e32 v236, v228
	v_mov_b32_e32 v237, v229
	v_mov_b32_e32 v238, v230
	v_mov_b32_e32 v239, v231
	v_mov_b32_dpp v228, v232 row_ror:8 row_mask:0xf bank_mask:0xc
	v_mov_b32_dpp v229, v233 row_ror:8 row_mask:0xf bank_mask:0xc
	v_mov_b32_dpp v230, v234 row_ror:8 row_mask:0xf bank_mask:0xc
	v_mov_b32_dpp v231, v235 row_ror:8 row_mask:0xf bank_mask:0xc
	v_mov_b32_dpp v232, v236 row_ror:8 row_mask:0xf bank_mask:0x3
	v_mov_b32_dpp v233, v237 row_ror:8 row_mask:0xf bank_mask:0x3
	v_mov_b32_dpp v234, v238 row_ror:8 row_mask:0xf bank_mask:0x3
	v_mov_b32_dpp v235, v239 row_ror:8 row_mask:0xf bank_mask:0x3
	s_add_u32 s100, s100, 0x48000
	s_addc_u32 s101, s101, 0
	global_store_dwordx4 v240, v[228:231], s[100:101]
	s_add_u32 s100, s100, 0x8000
	s_addc_u32 s101, s101, 0
	global_store_dwordx4 v240, v[232:235], s[100:101]
	v_cvt_pk_bf16_f32 v228, v44, v45
	v_cvt_pk_bf16_f32 v229, v46, v47
	v_cvt_pk_bf16_f32 v230, v40, v41
	v_cvt_pk_bf16_f32 v231, v42, v43
	v_cvt_pk_bf16_f32 v232, v36, v37
	v_cvt_pk_bf16_f32 v233, v38, v39
	v_cvt_pk_bf16_f32 v234, v32, v33
	v_cvt_pk_bf16_f32 v235, v34, v35
	v_mov_b32_e32 v236, v228
	v_mov_b32_e32 v237, v229
	v_mov_b32_e32 v238, v230
	v_mov_b32_e32 v239, v231
	v_mov_b32_dpp v228, v232 row_ror:8 row_mask:0xf bank_mask:0xc
	v_mov_b32_dpp v229, v233 row_ror:8 row_mask:0xf bank_mask:0xc
	v_mov_b32_dpp v230, v234 row_ror:8 row_mask:0xf bank_mask:0xc
	v_mov_b32_dpp v231, v235 row_ror:8 row_mask:0xf bank_mask:0xc
	v_mov_b32_dpp v232, v236 row_ror:8 row_mask:0xf bank_mask:0x3
	v_mov_b32_dpp v233, v237 row_ror:8 row_mask:0xf bank_mask:0x3
	v_mov_b32_dpp v234, v238 row_ror:8 row_mask:0xf bank_mask:0x3
	v_mov_b32_dpp v235, v239 row_ror:8 row_mask:0xf bank_mask:0x3
	s_add_u32 s100, s100, 0x8000
	s_addc_u32 s101, s101, 0
	global_store_dwordx4 v240, v[228:231], s[100:101]
	s_add_u32 s100, s100, 0x8000
	s_addc_u32 s101, s101, 0
	global_store_dwordx4 v240, v[232:235], s[100:101]
	v_cvt_pk_bf16_f32 v228, v28, v29
	v_cvt_pk_bf16_f32 v229, v30, v31
	v_cvt_pk_bf16_f32 v230, v24, v25
	v_cvt_pk_bf16_f32 v231, v26, v27
	v_cvt_pk_bf16_f32 v232, v20, v21
	v_cvt_pk_bf16_f32 v233, v22, v23
	v_cvt_pk_bf16_f32 v234, v16, v17
	v_cvt_pk_bf16_f32 v235, v18, v19
	v_mov_b32_e32 v236, v228
	v_mov_b32_e32 v237, v229
	v_mov_b32_e32 v238, v230
	v_mov_b32_e32 v239, v231
	v_mov_b32_dpp v228, v232 row_ror:8 row_mask:0xf bank_mask:0xc
	v_mov_b32_dpp v229, v233 row_ror:8 row_mask:0xf bank_mask:0xc
	v_mov_b32_dpp v230, v234 row_ror:8 row_mask:0xf bank_mask:0xc
	v_mov_b32_dpp v231, v235 row_ror:8 row_mask:0xf bank_mask:0xc
	v_mov_b32_dpp v232, v236 row_ror:8 row_mask:0xf bank_mask:0x3
	v_mov_b32_dpp v233, v237 row_ror:8 row_mask:0xf bank_mask:0x3
	v_mov_b32_dpp v234, v238 row_ror:8 row_mask:0xf bank_mask:0x3
	v_mov_b32_dpp v235, v239 row_ror:8 row_mask:0xf bank_mask:0x3
	s_add_u32 s100, s100, 0x8000
	s_addc_u32 s101, s101, 0
	global_store_dwordx4 v240, v[228:231], s[100:101]
	s_add_u32 s100, s100, 0x8000
	s_addc_u32 s101, s101, 0
	global_store_dwordx4 v240, v[232:235], s[100:101]
	v_cvt_pk_bf16_f32 v228, v12, v13
	v_cvt_pk_bf16_f32 v229, v14, v15
	v_cvt_pk_bf16_f32 v230, v8, v9
	v_cvt_pk_bf16_f32 v231, v10, v11
	v_cvt_pk_bf16_f32 v232, v4, v5
	v_cvt_pk_bf16_f32 v233, v6, v7
	v_cvt_pk_bf16_f32 v234, v0, v1
	v_cvt_pk_bf16_f32 v235, v2, v3
	v_mov_b32_e32 v236, v228
	v_mov_b32_e32 v237, v229
	v_mov_b32_e32 v238, v230
	v_mov_b32_e32 v239, v231
	v_mov_b32_dpp v228, v232 row_ror:8 row_mask:0xf bank_mask:0xc
	v_mov_b32_dpp v229, v233 row_ror:8 row_mask:0xf bank_mask:0xc
	v_mov_b32_dpp v230, v234 row_ror:8 row_mask:0xf bank_mask:0xc
	v_mov_b32_dpp v231, v235 row_ror:8 row_mask:0xf bank_mask:0xc
	v_mov_b32_dpp v232, v236 row_ror:8 row_mask:0xf bank_mask:0x3
	v_mov_b32_dpp v233, v237 row_ror:8 row_mask:0xf bank_mask:0x3
	v_mov_b32_dpp v234, v238 row_ror:8 row_mask:0xf bank_mask:0x3
	v_mov_b32_dpp v235, v239 row_ror:8 row_mask:0xf bank_mask:0x3
	s_add_u32 s100, s100, 0x8000
	s_addc_u32 s101, s101, 0
	global_store_dwordx4 v240, v[228:231], s[100:101]
	s_add_u32 s100, s100, 0x8000
	s_addc_u32 s101, s101, 0
	global_store_dwordx4 v240, v[232:235], s[100:101]
	s_mov_b32 s3, 0x80000
	s_mov_b32 s3, 0x90000
	s_nop 0
	s_mov_b32 s3, 0xa0000
	s_nop 0
	s_mov_b64 s[14:15], 0x80000
	s_mov_b64 s[14:15], 0x90000
	s_mov_b32 s3, 0xb0000
	s_mov_b64 s[14:15], 0xa0000
	s_mov_b64 s[14:15], 0xb0000
	s_mov_b64 s[14:15], 0x3c280000
	s_and_b64 vcc, exec, s[6:7]
	s_mov_b32 s40, s37
	s_mov_b32 s39, s2
	s_mov_b32 s38, s4
	s_mov_b64 s[18:19], s[12:13]
	s_mov_b64 s[16:17], s[8:9]
	s_cbranch_vccnz .LBB0_645

.LBB0_644:
	ds_read_b128 v[146:149], v143
	ds_read_b128 v[150:153], v143 offset:1024
	ds_read_b128 v[154:157], v143 offset:2048
	ds_read_b128 v[158:161], v143 offset:3072
	s_add_i32 s46, s18, 2
	s_add_u32 s19, s16, 0xffe00080
	s_addc_u32 s20, s17, -1
	s_cmp_eq_u32 s43, s18
	s_cselect_b32 s18, s42, s44
	s_cselect_b32 s21, s3, s20
	s_cselect_b32 s20, s5, s19
	s_cselect_b32 s19, s41, s45
	v_lshl_add_u64 v[194:195], s[16:17], 0, v[136:137]
	s_add_i32 m0, s26, 0xc000
	ds_read_b128 v[162:165], v144
	ds_read_b128 v[166:169], v144 offset:1024
	ds_read_b128 v[170:173], v144 offset:2048
	ds_read_b128 v[174:177], v144 offset:3072
	ds_read_b128 v[178:181], v144 offset:4096
	ds_read_b128 v[182:185], v144 offset:5120
	ds_read_b128 v[186:189], v144 offset:6144
	ds_read_b128 v[190:193], v144 offset:7168
	global_load_lds_dwordx4 v[194:195], off
	v_lshl_add_u64 v[194:195], s[16:17], 0, v[138:139]
	s_add_i32 m0, s26, 0xe000
	s_nop 0
	global_load_lds_dwordx4 v[194:195], off
	s_waitcnt lgkmcnt(8)
	s_barrier
	s_waitcnt lgkmcnt(0)
	s_setprio 1
	s_waitcnt lgkmcnt(0)
	v_mfma_f32_16x16x32_bf16 v[124:127], v[146:149], v[162:165], v[124:127]
	v_mfma_f32_16x16x32_bf16 v[120:123], v[154:157], v[162:165], v[120:123]
	v_mfma_f32_16x16x32_bf16 v[108:111], v[146:149], v[170:173], v[108:111]
	v_mfma_f32_16x16x32_bf16 v[104:107], v[154:157], v[170:173], v[104:107]
	v_mfma_f32_16x16x32_bf16 v[92:95], v[146:149], v[178:181], v[92:95]
	v_mfma_f32_16x16x32_bf16 v[88:91], v[154:157], v[178:181], v[88:91]
	v_mfma_f32_16x16x32_bf16 v[76:79], v[146:149], v[186:189], v[76:79]
	v_mfma_f32_16x16x32_bf16 v[72:75], v[154:157], v[186:189], v[72:75]
	v_mfma_f32_16x16x32_bf16 v[124:127], v[150:153], v[166:169], v[124:127]
	v_mfma_f32_16x16x32_bf16 v[120:123], v[158:161], v[166:169], v[120:123]
	v_mfma_f32_16x16x32_bf16 v[108:111], v[150:153], v[174:177], v[108:111]
	v_mfma_f32_16x16x32_bf16 v[104:107], v[158:161], v[174:177], v[104:107]
	v_mfma_f32_16x16x32_bf16 v[92:95], v[150:153], v[182:185], v[92:95]
	v_mfma_f32_16x16x32_bf16 v[88:91], v[158:161], v[182:185], v[88:91]
	v_mfma_f32_16x16x32_bf16 v[76:79], v[150:153], v[190:193], v[76:79]
	v_mfma_f32_16x16x32_bf16 v[72:75], v[158:161], v[190:193], v[72:75]
	s_setprio 0
	s_barrier
	s_add_i32 s47, s35, s25
	v_lshl_add_u64 v[212:213], s[18:19], 0, v[132:133]
	s_mov_b32 m0, s47
	ds_read_b128 v[194:197], v145
	ds_read_b128 v[198:201], v145 offset:1024
	ds_read_b128 v[204:207], v145 offset:2048
	ds_read_b128 v[208:211], v145 offset:3072
	global_load_lds_dwordx4 v[212:213], off
	v_lshl_add_u64 v[214:215], s[18:19], 0, v[128:129]
	s_add_i32 m0, s47, 0x2000
	s_nop 0
	global_load_lds_dwordx4 v[214:215], off
	s_barrier
	s_waitcnt lgkmcnt(0)
	s_setprio 1
	s_waitcnt lgkmcnt(0)
	v_mfma_f32_16x16x32_bf16 v[116:119], v[194:197], v[162:165], v[116:119]
	v_mfma_f32_16x16x32_bf16 v[112:115], v[204:207], v[162:165], v[112:115]
	v_mfma_f32_16x16x32_bf16 v[100:103], v[194:197], v[170:173], v[100:103]
	v_mfma_f32_16x16x32_bf16 v[96:99], v[204:207], v[170:173], v[96:99]
	v_mfma_f32_16x16x32_bf16 v[84:87], v[194:197], v[178:181], v[84:87]
	v_mfma_f32_16x16x32_bf16 v[80:83], v[204:207], v[178:181], v[80:83]
	v_mfma_f32_16x16x32_bf16 v[68:71], v[194:197], v[186:189], v[68:71]
	v_mfma_f32_16x16x32_bf16 v[64:67], v[204:207], v[186:189], v[64:67]
	v_mfma_f32_16x16x32_bf16 v[116:119], v[198:201], v[166:169], v[116:119]
	v_mfma_f32_16x16x32_bf16 v[112:115], v[208:211], v[166:169], v[112:115]
	v_mfma_f32_16x16x32_bf16 v[100:103], v[198:201], v[174:177], v[100:103]
	v_mfma_f32_16x16x32_bf16 v[96:99], v[208:211], v[174:177], v[96:99]
	v_mfma_f32_16x16x32_bf16 v[84:87], v[198:201], v[182:185], v[84:87]
	v_mfma_f32_16x16x32_bf16 v[80:83], v[208:211], v[182:185], v[80:83]
	v_mfma_f32_16x16x32_bf16 v[68:71], v[198:201], v[190:193], v[68:71]
	v_mfma_f32_16x16x32_bf16 v[64:67], v[208:211], v[190:193], v[64:67]
	s_setprio 0
	s_mov_b32 m0, s26
	v_lshl_add_u64 v[216:217], s[20:21], 0, v[134:135]
	s_barrier
	ds_read_b128 v[162:165], v144 offset:16384
	ds_read_b128 v[166:169], v144 offset:17408
	ds_read_b128 v[170:173], v144 offset:18432
	ds_read_b128 v[174:177], v144 offset:19456
	ds_read_b128 v[178:181], v144 offset:20480
	ds_read_b128 v[182:185], v144 offset:21504
	ds_read_b128 v[186:189], v144 offset:22528
	ds_read_b128 v[190:193], v144 offset:23552
	global_load_lds_dwordx4 v[216:217], off
	v_lshl_add_u64 v[218:219], s[20:21], 0, v[130:131]
	s_mov_b32 m0, s27
	s_nop 0
	global_load_lds_dwordx4 v[218:219], off
	s_barrier
	s_waitcnt lgkmcnt(0)
	s_setprio 1
	s_waitcnt lgkmcnt(0)
	v_mfma_f32_16x16x32_bf16 v[60:63], v[146:149], v[162:165], v[60:63]
	v_mfma_f32_16x16x32_bf16 v[56:59], v[154:157], v[162:165], v[56:59]
	v_mfma_f32_16x16x32_bf16 v[44:47], v[146:149], v[170:173], v[44:47]
	v_mfma_f32_16x16x32_bf16 v[40:43], v[154:157], v[170:173], v[40:43]
	v_mfma_f32_16x16x32_bf16 v[28:31], v[146:149], v[178:181], v[28:31]
	v_mfma_f32_16x16x32_bf16 v[24:27], v[154:157], v[178:181], v[24:27]
	v_mfma_f32_16x16x32_bf16 v[12:15], v[146:149], v[186:189], v[12:15]
	v_mfma_f32_16x16x32_bf16 v[8:11], v[154:157], v[186:189], v[8:11]
	v_mfma_f32_16x16x32_bf16 v[60:63], v[150:153], v[166:169], v[60:63]
	v_mfma_f32_16x16x32_bf16 v[56:59], v[158:161], v[166:169], v[56:59]
	v_mfma_f32_16x16x32_bf16 v[44:47], v[150:153], v[174:177], v[44:47]
	v_mfma_f32_16x16x32_bf16 v[40:43], v[158:161], v[174:177], v[40:43]
	v_mfma_f32_16x16x32_bf16 v[28:31], v[150:153], v[182:185], v[28:31]
	v_mfma_f32_16x16x32_bf16 v[24:27], v[158:161], v[182:185], v[24:27]
	v_mfma_f32_16x16x32_bf16 v[12:15], v[150:153], v[190:193], v[12:15]
	v_mfma_f32_16x16x32_bf16 v[8:11], v[158:161], v[190:193], v[8:11]
	s_setprio 0
	s_barrier
	s_add_u32 s48, s18, 0x80000
	s_addc_u32 s49, s19, 0
	s_add_i32 s47, s36, s25
	v_lshl_add_u64 v[146:147], s[48:49], 0, v[132:133]
	s_mov_b32 m0, s47
	s_nop 0
	global_load_lds_dwordx4 v[146:147], off
	v_lshl_add_u64 v[146:147], s[48:49], 0, v[128:129]
	s_add_i32 m0, s47, 0x2000
	s_nop 0
	global_load_lds_dwordx4 v[146:147], off
	s_waitcnt vmcnt(6)
	s_barrier
	s_setprio 1
	v_mfma_f32_16x16x32_bf16 v[52:55], v[194:197], v[162:165], v[52:55]
	v_mfma_f32_16x16x32_bf16 v[48:51], v[204:207], v[162:165], v[48:51]
	v_mfma_f32_16x16x32_bf16 v[36:39], v[194:197], v[170:173], v[36:39]
	v_mfma_f32_16x16x32_bf16 v[32:35], v[204:207], v[170:173], v[32:35]
	v_mfma_f32_16x16x32_bf16 v[20:23], v[194:197], v[178:181], v[20:23]
	v_mfma_f32_16x16x32_bf16 v[16:19], v[204:207], v[178:181], v[16:19]
	v_mfma_f32_16x16x32_bf16 v[4:7], v[194:197], v[186:189], v[4:7]
	v_mfma_f32_16x16x32_bf16 v[0:3], v[204:207], v[186:189], v[0:3]
	v_mfma_f32_16x16x32_bf16 v[52:55], v[198:201], v[166:169], v[52:55]
	v_mfma_f32_16x16x32_bf16 v[48:51], v[208:211], v[166:169], v[48:51]
	v_mfma_f32_16x16x32_bf16 v[36:39], v[198:201], v[174:177], v[36:39]
	v_mfma_f32_16x16x32_bf16 v[32:35], v[208:211], v[174:177], v[32:35]
	v_mfma_f32_16x16x32_bf16 v[20:23], v[198:201], v[182:185], v[20:23]
	v_mfma_f32_16x16x32_bf16 v[16:19], v[208:211], v[182:185], v[16:19]
	v_mfma_f32_16x16x32_bf16 v[4:7], v[198:201], v[190:193], v[4:7]
	v_mfma_f32_16x16x32_bf16 v[0:3], v[208:211], v[190:193], v[0:3]
	s_setprio 0
	s_add_i32 s47, 0, 0x18000
	v_add_u32_e32 v158, s47, v141
	s_barrier
	ds_read_b128 v[146:149], v158
	ds_read_b128 v[150:153], v158 offset:1024
	ds_read_b128 v[154:157], v158 offset:2048
	ds_read_b128 v[158:161], v158 offset:3072
	s_add_u32 s20, s20, 0x200000
	s_addc_u32 s21, s21, 0
	s_mov_b32 m0, s28
	v_lshl_add_u64 v[194:195], s[20:21], 0, v[134:135]
	ds_read_b128 v[162:165], v144 offset:32768
	ds_read_b128 v[166:169], v144 offset:33792
	ds_read_b128 v[170:173], v144 offset:34816
	ds_read_b128 v[174:177], v144 offset:35840
	ds_read_b128 v[178:181], v144 offset:36864
	ds_read_b128 v[182:185], v144 offset:37888
	ds_read_b128 v[186:189], v144 offset:38912
	ds_read_b128 v[190:193], v144 offset:39936
	global_load_lds_dwordx4 v[194:195], off
	v_lshl_add_u64 v[194:195], s[20:21], 0, v[130:131]
	s_mov_b32 m0, s29
	s_nop 0
	global_load_lds_dwordx4 v[194:195], off
	s_waitcnt lgkmcnt(8)
	s_barrier
	s_waitcnt lgkmcnt(0)
	s_setprio 1
	s_waitcnt lgkmcnt(0)
	v_mfma_f32_16x16x32_bf16 v[124:127], v[146:149], v[162:165], v[124:127]
	v_mfma_f32_16x16x32_bf16 v[120:123], v[154:157], v[162:165], v[120:123]
	v_mfma_f32_16x16x32_bf16 v[108:111], v[146:149], v[170:173], v[108:111]
	v_mfma_f32_16x16x32_bf16 v[104:107], v[154:157], v[170:173], v[104:107]
	v_mfma_f32_16x16x32_bf16 v[92:95], v[146:149], v[178:181], v[92:95]
	v_mfma_f32_16x16x32_bf16 v[88:91], v[154:157], v[178:181], v[88:91]
	v_mfma_f32_16x16x32_bf16 v[76:79], v[146:149], v[186:189], v[76:79]
	v_mfma_f32_16x16x32_bf16 v[72:75], v[154:157], v[186:189], v[72:75]
	v_mfma_f32_16x16x32_bf16 v[124:127], v[150:153], v[166:169], v[124:127]
	v_mfma_f32_16x16x32_bf16 v[120:123], v[158:161], v[166:169], v[120:123]
	v_mfma_f32_16x16x32_bf16 v[108:111], v[150:153], v[174:177], v[108:111]
	v_mfma_f32_16x16x32_bf16 v[104:107], v[158:161], v[174:177], v[104:107]
	v_mfma_f32_16x16x32_bf16 v[92:95], v[150:153], v[182:185], v[92:95]
	v_mfma_f32_16x16x32_bf16 v[88:91], v[158:161], v[182:185], v[88:91]
	v_mfma_f32_16x16x32_bf16 v[76:79], v[150:153], v[190:193], v[76:79]
	v_mfma_f32_16x16x32_bf16 v[72:75], v[158:161], v[190:193], v[72:75]
	s_setprio 0
	s_barrier
	s_add_i32 s20, 0, 0x1c000
	s_add_i32 s21, s47, s25
	v_add_u32_e32 v208, s20, v141
	v_lshl_add_u64 v[212:213], v[212:213], 0, s[0:1]
	s_mov_b32 m0, s21
	ds_read_b128 v[194:197], v208
	ds_read_b128 v[198:201], v208 offset:1024
	ds_read_b128 v[204:207], v208 offset:2048
	ds_read_b128 v[208:211], v208 offset:3072
	global_load_lds_dwordx4 v[212:213], off
	v_lshl_add_u64 v[212:213], v[214:215], 0, s[0:1]
	s_add_i32 m0, s21, 0x2000
	s_nop 0
	global_load_lds_dwordx4 v[212:213], off
	s_barrier
	s_waitcnt lgkmcnt(0)
	s_setprio 1
	s_waitcnt lgkmcnt(0)
	v_mfma_f32_16x16x32_bf16 v[116:119], v[194:197], v[162:165], v[116:119]
	v_mfma_f32_16x16x32_bf16 v[112:115], v[204:207], v[162:165], v[112:115]
	v_mfma_f32_16x16x32_bf16 v[100:103], v[194:197], v[170:173], v[100:103]
	v_mfma_f32_16x16x32_bf16 v[96:99], v[204:207], v[170:173], v[96:99]
	v_mfma_f32_16x16x32_bf16 v[84:87], v[194:197], v[178:181], v[84:87]
	v_mfma_f32_16x16x32_bf16 v[80:83], v[204:207], v[178:181], v[80:83]
	v_mfma_f32_16x16x32_bf16 v[68:71], v[194:197], v[186:189], v[68:71]
	v_mfma_f32_16x16x32_bf16 v[64:67], v[204:207], v[186:189], v[64:67]
	v_mfma_f32_16x16x32_bf16 v[116:119], v[198:201], v[166:169], v[116:119]
	v_mfma_f32_16x16x32_bf16 v[112:115], v[208:211], v[166:169], v[112:115]
	v_mfma_f32_16x16x32_bf16 v[100:103], v[198:201], v[174:177], v[100:103]
	v_mfma_f32_16x16x32_bf16 v[96:99], v[208:211], v[174:177], v[96:99]
	v_mfma_f32_16x16x32_bf16 v[84:87], v[198:201], v[182:185], v[84:87]
	v_mfma_f32_16x16x32_bf16 v[80:83], v[208:211], v[182:185], v[80:83]
	v_mfma_f32_16x16x32_bf16 v[68:71], v[198:201], v[190:193], v[68:71]
	v_mfma_f32_16x16x32_bf16 v[64:67], v[208:211], v[190:193], v[64:67]
	s_setprio 0
	s_mov_b32 m0, s30
	v_lshl_add_u64 v[212:213], v[216:217], 0, s[0:1]
	s_barrier
	ds_read_b128 v[162:165], v144 offset:49152
	ds_read_b128 v[166:169], v144 offset:50176
	ds_read_b128 v[170:173], v144 offset:51200
	ds_read_b128 v[174:177], v144 offset:52224
	ds_read_b128 v[178:181], v144 offset:53248
	ds_read_b128 v[182:185], v144 offset:54272
	ds_read_b128 v[186:189], v144 offset:55296
	ds_read_b128 v[190:193], v144 offset:56320
	global_load_lds_dwordx4 v[212:213], off
	v_lshl_add_u64 v[212:213], v[218:219], 0, s[0:1]
	s_mov_b32 m0, s31
	s_nop 0
	global_load_lds_dwordx4 v[212:213], off
	s_barrier
	s_waitcnt lgkmcnt(0)
	s_setprio 1
	s_waitcnt lgkmcnt(0)
	v_mfma_f32_16x16x32_bf16 v[60:63], v[146:149], v[162:165], v[60:63]
	v_mfma_f32_16x16x32_bf16 v[56:59], v[154:157], v[162:165], v[56:59]
	v_mfma_f32_16x16x32_bf16 v[44:47], v[146:149], v[170:173], v[44:47]
	v_mfma_f32_16x16x32_bf16 v[40:43], v[154:157], v[170:173], v[40:43]
	v_mfma_f32_16x16x32_bf16 v[28:31], v[146:149], v[178:181], v[28:31]
	v_mfma_f32_16x16x32_bf16 v[24:27], v[154:157], v[178:181], v[24:27]
	v_mfma_f32_16x16x32_bf16 v[12:15], v[146:149], v[186:189], v[12:15]
	v_mfma_f32_16x16x32_bf16 v[8:11], v[154:157], v[186:189], v[8:11]
	v_mfma_f32_16x16x32_bf16 v[60:63], v[150:153], v[166:169], v[60:63]
	v_mfma_f32_16x16x32_bf16 v[56:59], v[158:161], v[166:169], v[56:59]
	v_mfma_f32_16x16x32_bf16 v[44:47], v[150:153], v[174:177], v[44:47]
	v_mfma_f32_16x16x32_bf16 v[40:43], v[158:161], v[174:177], v[40:43]
	v_mfma_f32_16x16x32_bf16 v[28:31], v[150:153], v[182:185], v[28:31]
	v_mfma_f32_16x16x32_bf16 v[24:27], v[158:161], v[182:185], v[24:27]
	v_mfma_f32_16x16x32_bf16 v[12:15], v[150:153], v[190:193], v[12:15]
	v_mfma_f32_16x16x32_bf16 v[8:11], v[158:161], v[190:193], v[8:11]
	s_setprio 0
	s_barrier
	s_add_u32 s18, s18, 0x80080
	s_addc_u32 s19, s19, 0
	s_add_i32 s20, s20, s25
	v_lshl_add_u64 v[146:147], s[18:19], 0, v[132:133]
	s_mov_b32 m0, s20
	s_nop 0
	global_load_lds_dwordx4 v[146:147], off
	v_lshl_add_u64 v[146:147], s[18:19], 0, v[128:129]
	s_add_i32 m0, s20, 0x2000
	s_nop 0
	global_load_lds_dwordx4 v[146:147], off
	s_waitcnt vmcnt(6)
	s_barrier
	s_setprio 1
	v_mfma_f32_16x16x32_bf16 v[52:55], v[194:197], v[162:165], v[52:55]
	v_mfma_f32_16x16x32_bf16 v[48:51], v[204:207], v[162:165], v[48:51]
	v_mfma_f32_16x16x32_bf16 v[36:39], v[194:197], v[170:173], v[36:39]
	v_mfma_f32_16x16x32_bf16 v[32:35], v[204:207], v[170:173], v[32:35]
	v_mfma_f32_16x16x32_bf16 v[20:23], v[194:197], v[178:181], v[20:23]
	v_mfma_f32_16x16x32_bf16 v[16:19], v[204:207], v[178:181], v[16:19]
	v_mfma_f32_16x16x32_bf16 v[4:7], v[194:197], v[186:189], v[4:7]
	v_mfma_f32_16x16x32_bf16 v[0:3], v[204:207], v[186:189], v[0:3]
	v_mfma_f32_16x16x32_bf16 v[52:55], v[198:201], v[166:169], v[52:55]
	v_mfma_f32_16x16x32_bf16 v[48:51], v[208:211], v[166:169], v[48:51]
	v_mfma_f32_16x16x32_bf16 v[36:39], v[198:201], v[174:177], v[36:39]
	v_mfma_f32_16x16x32_bf16 v[32:35], v[208:211], v[174:177], v[32:35]
	v_mfma_f32_16x16x32_bf16 v[20:23], v[198:201], v[182:185], v[20:23]
	v_mfma_f32_16x16x32_bf16 v[16:19], v[208:211], v[182:185], v[16:19]
	v_mfma_f32_16x16x32_bf16 v[4:7], v[198:201], v[190:193], v[4:7]
	v_mfma_f32_16x16x32_bf16 v[0:3], v[208:211], v[190:193], v[0:3]
	s_setprio 0
	s_add_u32 s16, s16, 0x100
	s_addc_u32 s17, s17, 0
	s_add_u32 s44, s44, 0x100
	s_addc_u32 s45, s45, 0
	s_cmp_ge_i32 s46, s40
	s_mov_b32 s18, s46
	s_barrier
	s_cbranch_scc0 .LBB0_644
	s_branch .LBB0_639

.LBB0_1399:
	s_or_b64 exec, exec, s[0:1]
	v_readlane_b32 s0, v247, 17
	s_mul_hi_u32 s0, s0, 0x4800
	v_readlane_b32 s4, v247, 18
	s_mul_i32 s1, s0, s4
	s_sub_i32 s1, 0x4800, s1
	s_add_i32 s2, s0, 1
	s_sub_i32 s3, s1, s4
	s_cmp_ge_u32 s1, s4
	s_cselect_b32 s0, s2, s0
	s_cselect_b32 s1, s3, s1
	s_add_i32 s2, s0, 1
	s_cmp_ge_u32 s1, s4
	s_cselect_b32 s0, s2, s0
	v_readlane_b32 s1, v247, 11
	s_xor_b32 s0, s0, s1
	s_sub_i32 s0, s0, s1
	v_mov_b32_e32 v8, v202
	s_waitcnt lgkmcnt(0)
	s_barrier
	s_cmp_gt_i32 s0, 0
	s_nop 0
	v_readfirstlane_b32 s24, v8
	s_cbranch_scc0 .LBB0_1413
	v_lshlrev_b32_e32 v0, 4, v8
	v_add_u32_e32 v1, 0x2000, v0
	v_ashrrev_i32_e32 v2, 31, v1
	v_lshrrev_b32_e32 v2, 22, v2
	v_readlane_b32 s1, v248, 45
	v_add_u32_e32 v2, v1, v2
	s_mul_i32 s1, s0, s1
	v_ashrrev_i32_e32 v9, 10, v2
	s_ashr_i32 s2, s1, 31
	s_mul_hi_i32 s3, s1, 0x38e38e39
	v_mul_i32_i24_e32 v2, 0x400, v9
	s_lshr_b32 s2, s2, 26
	s_lshr_b32 s4, s3, 31
	s_ashr_i32 s3, s3, 7
	v_sub_u32_e32 v1, v1, v2
	s_add_i32 s6, s1, s2
	s_add_i32 s3, s3, s4
	v_lshrrev_b32_e32 v2, 4, v1
	s_ashr_i32 s2, s6, 6
	s_mul_i32 s4, s3, -9
	v_bitop3_b32 v1, v2, v1, 32 bitop3:0x6c
	s_add_i32 s4, s4, s2
	v_ashrrev_i32_e32 v2, 31, v1
	s_and_b32 s38, s3, 7
	s_lshl_b32 s2, s4, 2
	s_ashr_i32 s3, s3, 3
	v_lshrrev_b32_e32 v2, 26, v2
	s_andn2_b32 s6, s6, 63
	s_add_i32 s2, s2, s3
	v_add_u32_e32 v2, v1, v2
	v_lshlrev_b32_e32 v3, 3, v9
	s_add_u32 s25, s58, 0x9100000
	v_ashrrev_i32_e32 v10, 6, v2
	v_and_b32_e32 v3, -16, v3
	s_addc_u32 s26, s59, 0
	s_ashr_i32 s3, s2, 31
	v_add_u32_e32 v3, v10, v3
	s_lshl_b64 s[10:11], s[2:3], 21
	v_and_b32_e32 v4, 3, v10
	s_mov_b32 s3, 0x7ffe0
	v_lshrrev_b32_e32 v5, 2, v3
	v_lshlrev_b32_e32 v6, 1, v3
	v_and_b32_e32 v2, 0xc0, v2
	v_and_or_b32 v4, v3, s3, v4
	v_and_b32_e32 v5, 4, v5
	v_and_b32_e32 v6, 24, v6
	v_sub_u32_e32 v1, v1, v2
	v_mov_b32_e32 v2, 1
	v_or3_b32 v4, v4, v5, v6
	v_lshlrev_b32_e32 v5, 5, v9
	v_ashrrev_i16_sdwa v1, v2, sext(v1) dst_sel:DWORD dst_unused:UNUSED_PAD src0_sel:DWORD src1_sel:BYTE_0
	v_and_b32_e32 v5, 32, v5
	v_bfe_i32 v11, v1, 0, 16
	v_add_lshl_u32 v1, v5, v11, 1
	v_lshl_add_u32 v128, v4, 13, v1
	v_lshl_add_u32 v130, v3, 13, v1
	v_bfe_i32 v1, v8, 27, 1
	v_lshrrev_b32_e32 v1, 22, v1
	v_add_u32_e32 v1, v0, v1
	v_and_b32_e32 v1, 0xfffffc00, v1
	v_sub_u32_e32 v0, v0, v1
	v_lshrrev_b32_e32 v1, 4, v0
	v_ashrrev_i32_e32 v3, 31, v8
	v_bitop3_b32 v0, v1, v0, 32 bitop3:0x6c
	v_lshrrev_b32_e32 v3, 26, v3
	v_ashrrev_i32_e32 v1, 31, v0
	v_add_u32_e32 v3, v8, v3
	v_lshrrev_b32_e32 v1, 26, v1
	v_ashrrev_i32_e32 v13, 6, v3
	v_add_u32_e32 v1, v0, v1
	v_lshlrev_b32_e32 v3, 3, v13
	s_sub_i32 s8, s1, s6
	v_ashrrev_i32_e32 v12, 6, v1
	v_and_b32_e32 v3, -16, v3
	s_ashr_i32 s5, s24, 6
	s_ashr_i32 s9, s8, 31
	v_add_u32_e32 v3, v12, v3
	s_ashr_i32 s4, s24, 8
	s_lshl_b32 s27, s5, 10
	s_lshl_b32 s7, s38, 21
	s_lshl_b64 s[8:9], s[8:9], 7
	v_and_b32_e32 v4, 3, v12
	v_lshrrev_b32_e32 v5, 2, v3
	v_lshlrev_b32_e32 v6, 1, v3
	v_and_b32_e32 v1, 0xc0, v1
	v_and_or_b32 v4, v3, s3, v4
	v_and_b32_e32 v5, 4, v5
	v_and_b32_e32 v6, 24, v6
	v_sub_u32_e32 v0, v0, v1
	s_add_u32 s3, s25, s7
	v_or3_b32 v4, v4, v5, v6
	v_lshlrev_b32_e32 v5, 5, v13
	v_ashrrev_i16_sdwa v0, v2, sext(v0) dst_sel:DWORD dst_unused:UNUSED_PAD src0_sel:DWORD src1_sel:BYTE_0
	s_addc_u32 s7, s26, 0
	v_and_b32_e32 v5, 32, v5
	v_bfe_i32 v14, v0, 0, 16
	s_add_u32 s20, s3, s8
	v_add_lshl_u32 v0, v5, v14, 1
	s_addc_u32 s21, s7, s9
	s_add_i32 s3, s27, 0
	v_lshl_add_u32 v132, v4, 13, v0
	s_add_i32 m0, s3, 0x10000
	v_readlane_b32 s12, v247, 9
	v_mov_b32_e32 v230, s4
	v_lshlrev_b32_e32 v230, 18, v230
	v_add_u32_e32 v132, v132, v230
	v_add_u32_e32 v230, 0x80000, v230
	v_add_u32_e32 v128, v128, v230
	global_load_lds_dwordx4 v132, s[20:21]
	s_add_i32 m0, s3, 0x12000
	v_readlane_b32 s13, v247, 10
	s_add_u32 s7, s12, s10
	s_addc_u32 s10, s13, s11
	s_add_u32 s18, s7, s8
	v_lshl_add_u32 v134, v3, 13, v0
	global_load_lds_dwordx4 v128, s[20:21]
	s_addc_u32 s19, s10, s9
	s_mov_b32 m0, s3
	s_add_i32 s28, s3, 0x2000
	global_load_lds_dwordx4 v134, s[18:19]
	s_mov_b32 m0, s28
	s_add_u32 s8, s20, 0x40000
	global_load_lds_dwordx4 v130, s[18:19]
	s_addc_u32 s9, s21, 0
	s_add_i32 m0, s3, 0x14000
	v_mov_b32_e32 v133, 0
	global_load_lds_dwordx4 v132, s[8:9]
	s_add_i32 m0, s3, 0x16000
	v_mov_b32_e32 v129, v133
	global_load_lds_dwordx4 v128, s[8:9]
	s_add_u32 s8, s18, 0x100000
	s_addc_u32 s9, s19, 0
	s_add_i32 s29, s3, 0x4000
	s_mov_b32 m0, s29
	s_add_i32 s30, s3, 0x6000
	global_load_lds_dwordx4 v134, s[8:9]
	s_mov_b32 m0, s30
	v_mov_b32_e32 v135, v133
	global_load_lds_dwordx4 v130, s[8:9]
	v_mov_b32_e32 v131, v133
	v_lshl_add_u64 v[6:7], s[20:21], 0, v[132:133]
	v_lshl_add_u64 v[4:5], s[20:21], 0, v[128:129]
	v_lshl_add_u64 v[2:3], s[18:19], 0, v[134:135]
	s_cmp_lg_u32 s4, 1
	v_lshl_add_u64 v[0:1], s[18:19], 0, v[130:131]
	s_cbranch_scc1 .LBB0_1402
	s_barrier
.LBB0_1402:
	s_add_i32 s31, s1, s0
	s_add_i32 s34, s6, 64
	s_min_i32 s0, s34, s31
	s_sub_i32 s45, s0, s1
	s_add_i32 s35, s6, 0x80
	s_cmp_eq_u32 s1, s6
	s_mov_b32 s0, 0x3c280000
	s_cselect_b32 s16, s0, 0x39e80000
	s_lshl_b32 s0, s5, 5
	s_and_b32 s5, s0, 0x60
	s_mov_b64 s[0:1], 0x80
	s_add_i32 m0, s3, 0x18000
	v_lshl_add_u64 v[6:7], v[6:7], 0, s[0:1]
	s_lshl_b32 s8, s4, 13
	s_lshl_b32 s9, s5, 7
	s_waitcnt vmcnt(4)
	s_barrier
	global_load_lds_dwordx4 v[6:7], off
	v_lshl_add_u64 v[4:5], v[4:5], 0, s[0:1]
	s_add_i32 m0, s3, 0x1a000
	s_add_i32 s36, s3, 0x8000
	s_add_i32 s37, s3, 0xa000
	global_load_lds_dwordx4 v[4:5], off
	v_lshl_add_u64 v[2:3], v[2:3], 0, s[0:1]
	s_mov_b32 m0, s36
	s_add_u32 s6, s20, 0x40080
	global_load_lds_dwordx4 v[2:3], off
	v_lshl_add_u64 v[0:1], v[0:1], 0, s[0:1]
	s_mov_b32 m0, s37
	s_addc_u32 s7, s21, 0
	global_load_lds_dwordx4 v[0:1], off
	s_add_i32 m0, s3, 0x1c000
	v_lshl_add_u64 v[0:1], s[6:7], 0, v[132:133]
	global_load_lds_dwordx4 v[0:1], off
	v_lshl_add_u64 v[0:1], s[6:7], 0, v[128:129]
	s_add_i32 m0, s3, 0x1e000
	s_mov_b32 s17, 0
	global_load_lds_dwordx4 v[0:1], off
	v_lshrrev_b32_e32 v1, 1, v8
	v_and_b32_e32 v1, 24, v1
	v_and_b32_e32 v0, 15, v8
	v_lshlrev_b32_e32 v2, 1, v1
	v_lshl_or_b32 v140, s4, 6, v0
	v_lshl_or_b32 v0, v0, 6, v2
	v_lshlrev_b32_e32 v2, 2, v8
	v_and_b32_e32 v2, 32, v2
	v_bitop3_b32 v3, v0, s8, v2 bitop3:0xde
	v_bitop3_b32 v141, v0, s9, v2 bitop3:0xde
	v_lshlrev_b32_e32 v0, 16, v13
	v_and_b32_e32 v0, 0xfffe0000, v0
	v_or_b32_e32 v142, s5, v1
	v_lshl_add_u32 v0, v12, 13, v0
	v_and_b32_e32 v1, 1, v13
	v_lshl_or_b32 v0, v1, 6, v0
	v_lshl_add_u32 v136, v14, 1, v0
	v_lshlrev_b32_e32 v0, 16, v9
	v_and_b32_e32 v0, 0xfffe0000, v0
	s_waitcnt vmcnt(6)
	v_lshl_add_u32 v0, v10, 13, v0
	v_and_b32_e32 v1, 1, v9
	v_lshl_or_b32 v0, v1, 6, v0
	s_add_i32 s39, 0, 0x10000
	s_add_i32 s40, 0, 0x14000
	v_mov_b32_e32 v137, v133
	v_lshl_add_u32 v138, v11, 1, v0
	v_mov_b32_e32 v139, v133
	v_add_u32_e32 v143, s39, v141
	v_add_u32_e32 v144, 0, v3
	v_add_u32_e32 v145, s40, v141
	s_mov_b32 s41, 0xa0000
	s_mov_b64 s[4:5], 0xb0000
	s_mov_b32 s42, 0xb0000
	s_mov_b32 s43, s17
	s_barrier
	s_branch .LBB0_1405

.LBB0_1404:
	s_add_i32 s43, s43, 1
	s_add_u32 s16, s58, s16
	s_addc_u32 s17, s59, s17
	s_mov_b32 s100, s16
	s_mov_b32 s101, s17
	v_and_b32_e32 v242, 15, v202
	v_bfe_u32 v243, v202, 4, 2
	v_bfe_u32 v244, v202, 6, 2
	v_lshrrev_b32_e32 v245, 8, v202
	v_and_b32_e32 v240, 7, v242
	v_lshl_add_u32 v240, v245, 6, v240
	v_lshl_add_u32 v240, s2, 8, v240
	v_lshlrev_b32_e32 v240, 12, v240
	v_lshrrev_b32_e32 v241, 3, v242
	v_lshlrev_b32_e32 v241, 6, v241
	v_lshl_add_u32 v241, v244, 7, v241
	v_lshl_add_u32 v241, v243, 4, v241
	v_add_u32_e32 v240, v240, v241
	s_lshl_b32 s98, s38, 9
	v_add_u32_e32 v240, s98, v240
	v_cvt_pk_bf16_f32 v228, v124, v125
	v_cvt_pk_bf16_f32 v229, v126, v127
	v_cvt_pk_bf16_f32 v230, v120, v121
	v_cvt_pk_bf16_f32 v231, v122, v123
	v_cvt_pk_bf16_f32 v232, v116, v117
	v_cvt_pk_bf16_f32 v233, v118, v119
	v_cvt_pk_bf16_f32 v234, v112, v113
	v_cvt_pk_bf16_f32 v235, v114, v115
	v_mov_b32_e32 v236, v228
	v_mov_b32_e32 v237, v229
	v_mov_b32_e32 v238, v230
	v_mov_b32_e32 v239, v231
	v_mov_b32_dpp v228, v232 row_ror:8 row_mask:0xf bank_mask:0xc
	v_mov_b32_dpp v229, v233 row_ror:8 row_mask:0xf bank_mask:0xc
	v_mov_b32_dpp v230, v234 row_ror:8 row_mask:0xf bank_mask:0xc
	v_mov_b32_dpp v231, v235 row_ror:8 row_mask:0xf bank_mask:0xc
	v_mov_b32_dpp v232, v236 row_ror:8 row_mask:0xf bank_mask:0x3
	v_mov_b32_dpp v233, v237 row_ror:8 row_mask:0xf bank_mask:0x3
	v_mov_b32_dpp v234, v238 row_ror:8 row_mask:0xf bank_mask:0x3
	v_mov_b32_dpp v235, v239 row_ror:8 row_mask:0xf bank_mask:0x3
	global_store_dwordx4 v240, v[228:231], s[100:101]
	s_add_u32 s100, s100, 0x8000
	s_addc_u32 s101, s101, 0
	global_store_dwordx4 v240, v[232:235], s[100:101]
	v_cvt_pk_bf16_f32 v228, v108, v109
	v_cvt_pk_bf16_f32 v229, v110, v111
	v_cvt_pk_bf16_f32 v230, v104, v105
	v_cvt_pk_bf16_f32 v231, v106, v107
	v_cvt_pk_bf16_f32 v232, v100, v101
	v_cvt_pk_bf16_f32 v233, v102, v103
	v_cvt_pk_bf16_f32 v234, v96, v97
	v_cvt_pk_bf16_f32 v235, v98, v99
	v_mov_b32_e32 v236, v228
	v_mov_b32_e32 v237, v229
	v_mov_b32_e32 v238, v230
	v_mov_b32_e32 v239, v231
	v_mov_b32_dpp v228, v232 row_ror:8 row_mask:0xf bank_mask:0xc
	v_mov_b32_dpp v229, v233 row_ror:8 row_mask:0xf bank_mask:0xc
	v_mov_b32_dpp v230, v234 row_ror:8 row_mask:0xf bank_mask:0xc
	v_mov_b32_dpp v231, v235 row_ror:8 row_mask:0xf bank_mask:0xc
	v_mov_b32_dpp v232, v236 row_ror:8 row_mask:0xf bank_mask:0x3
	v_mov_b32_dpp v233, v237 row_ror:8 row_mask:0xf bank_mask:0x3
	v_mov_b32_dpp v234, v238 row_ror:8 row_mask:0xf bank_mask:0x3
	v_mov_b32_dpp v235, v239 row_ror:8 row_mask:0xf bank_mask:0x3
	s_add_u32 s100, s100, 0x8000
	s_addc_u32 s101, s101, 0
	global_store_dwordx4 v240, v[228:231], s[100:101]
	s_add_u32 s100, s100, 0x8000
	s_addc_u32 s101, s101, 0
	global_store_dwordx4 v240, v[232:235], s[100:101]
	v_cvt_pk_bf16_f32 v228, v92, v93
	v_cvt_pk_bf16_f32 v229, v94, v95
	v_cvt_pk_bf16_f32 v230, v88, v89
	v_cvt_pk_bf16_f32 v231, v90, v91
	v_cvt_pk_bf16_f32 v232, v84, v85
	v_cvt_pk_bf16_f32 v233, v86, v87
	v_cvt_pk_bf16_f32 v234, v80, v81
	v_cvt_pk_bf16_f32 v235, v82, v83
	v_mov_b32_e32 v236, v228
	v_mov_b32_e32 v237, v229
	v_mov_b32_e32 v238, v230
	v_mov_b32_e32 v239, v231
	v_mov_b32_dpp v228, v232 row_ror:8 row_mask:0xf bank_mask:0xc
	v_mov_b32_dpp v229, v233 row_ror:8 row_mask:0xf bank_mask:0xc
	v_mov_b32_dpp v230, v234 row_ror:8 row_mask:0xf bank_mask:0xc
	v_mov_b32_dpp v231, v235 row_ror:8 row_mask:0xf bank_mask:0xc
	v_mov_b32_dpp v232, v236 row_ror:8 row_mask:0xf bank_mask:0x3
	v_mov_b32_dpp v233, v237 row_ror:8 row_mask:0xf bank_mask:0x3
	v_mov_b32_dpp v234, v238 row_ror:8 row_mask:0xf bank_mask:0x3
	v_mov_b32_dpp v235, v239 row_ror:8 row_mask:0xf bank_mask:0x3
	s_add_u32 s100, s100, 0x8000
	s_addc_u32 s101, s101, 0
	global_store_dwordx4 v240, v[228:231], s[100:101]
	s_add_u32 s100, s100, 0x8000
	s_addc_u32 s101, s101, 0
	global_store_dwordx4 v240, v[232:235], s[100:101]
	v_cvt_pk_bf16_f32 v228, v76, v77
	v_cvt_pk_bf16_f32 v229, v78, v79
	v_cvt_pk_bf16_f32 v230, v72, v73
	v_cvt_pk_bf16_f32 v231, v74, v75
	v_cvt_pk_bf16_f32 v232, v68, v69
	v_cvt_pk_bf16_f32 v233, v70, v71
	v_cvt_pk_bf16_f32 v234, v64, v65
	v_cvt_pk_bf16_f32 v235, v66, v67
	v_mov_b32_e32 v236, v228
	v_mov_b32_e32 v237, v229
	v_mov_b32_e32 v238, v230
	v_mov_b32_e32 v239, v231
	v_mov_b32_dpp v228, v232 row_ror:8 row_mask:0xf bank_mask:0xc
	v_mov_b32_dpp v229, v233 row_ror:8 row_mask:0xf bank_mask:0xc
	v_mov_b32_dpp v230, v234 row_ror:8 row_mask:0xf bank_mask:0xc
	v_mov_b32_dpp v231, v235 row_ror:8 row_mask:0xf bank_mask:0xc
	v_mov_b32_dpp v232, v236 row_ror:8 row_mask:0xf bank_mask:0x3
	v_mov_b32_dpp v233, v237 row_ror:8 row_mask:0xf bank_mask:0x3
	v_mov_b32_dpp v234, v238 row_ror:8 row_mask:0xf bank_mask:0x3
	v_mov_b32_dpp v235, v239 row_ror:8 row_mask:0xf bank_mask:0x3
	s_add_u32 s100, s100, 0x8000
	s_addc_u32 s101, s101, 0
	global_store_dwordx4 v240, v[228:231], s[100:101]
	s_add_u32 s100, s100, 0x8000
	s_addc_u32 s101, s101, 0
	global_store_dwordx4 v240, v[232:235], s[100:101]
	v_cvt_pk_bf16_f32 v228, v60, v61
	v_cvt_pk_bf16_f32 v229, v62, v63
	v_cvt_pk_bf16_f32 v230, v56, v57
	v_cvt_pk_bf16_f32 v231, v58, v59
	v_cvt_pk_bf16_f32 v232, v52, v53
	v_cvt_pk_bf16_f32 v233, v54, v55
	v_cvt_pk_bf16_f32 v234, v48, v49
	v_cvt_pk_bf16_f32 v235, v50, v51
	v_mov_b32_e32 v236, v228
	v_mov_b32_e32 v237, v229
	v_mov_b32_e32 v238, v230
	v_mov_b32_e32 v239, v231
	v_mov_b32_dpp v228, v232 row_ror:8 row_mask:0xf bank_mask:0xc
	v_mov_b32_dpp v229, v233 row_ror:8 row_mask:0xf bank_mask:0xc
	v_mov_b32_dpp v230, v234 row_ror:8 row_mask:0xf bank_mask:0xc
	v_mov_b32_dpp v231, v235 row_ror:8 row_mask:0xf bank_mask:0xc
	v_mov_b32_dpp v232, v236 row_ror:8 row_mask:0xf bank_mask:0x3
	v_mov_b32_dpp v233, v237 row_ror:8 row_mask:0xf bank_mask:0x3
	v_mov_b32_dpp v234, v238 row_ror:8 row_mask:0xf bank_mask:0x3
	v_mov_b32_dpp v235, v239 row_ror:8 row_mask:0xf bank_mask:0x3
	s_add_u32 s100, s100, 0x48000
	s_addc_u32 s101, s101, 0
	global_store_dwordx4 v240, v[228:231], s[100:101]
	s_add_u32 s100, s100, 0x8000
	s_addc_u32 s101, s101, 0
	global_store_dwordx4 v240, v[232:235], s[100:101]
	v_cvt_pk_bf16_f32 v228, v44, v45
	v_cvt_pk_bf16_f32 v229, v46, v47
	v_cvt_pk_bf16_f32 v230, v40, v41
	v_cvt_pk_bf16_f32 v231, v42, v43
	v_cvt_pk_bf16_f32 v232, v36, v37
	v_cvt_pk_bf16_f32 v233, v38, v39
	v_cvt_pk_bf16_f32 v234, v32, v33
	v_cvt_pk_bf16_f32 v235, v34, v35
	v_mov_b32_e32 v236, v228
	v_mov_b32_e32 v237, v229
	v_mov_b32_e32 v238, v230
	v_mov_b32_e32 v239, v231
	v_mov_b32_dpp v228, v232 row_ror:8 row_mask:0xf bank_mask:0xc
	v_mov_b32_dpp v229, v233 row_ror:8 row_mask:0xf bank_mask:0xc
	v_mov_b32_dpp v230, v234 row_ror:8 row_mask:0xf bank_mask:0xc
	v_mov_b32_dpp v231, v235 row_ror:8 row_mask:0xf bank_mask:0xc
	v_mov_b32_dpp v232, v236 row_ror:8 row_mask:0xf bank_mask:0x3
	v_mov_b32_dpp v233, v237 row_ror:8 row_mask:0xf bank_mask:0x3
	v_mov_b32_dpp v234, v238 row_ror:8 row_mask:0xf bank_mask:0x3
	v_mov_b32_dpp v235, v239 row_ror:8 row_mask:0xf bank_mask:0x3
	s_add_u32 s100, s100, 0x8000
	s_addc_u32 s101, s101, 0
	global_store_dwordx4 v240, v[228:231], s[100:101]
	s_add_u32 s100, s100, 0x8000
	s_addc_u32 s101, s101, 0
	global_store_dwordx4 v240, v[232:235], s[100:101]
	v_cvt_pk_bf16_f32 v228, v28, v29
	v_cvt_pk_bf16_f32 v229, v30, v31
	v_cvt_pk_bf16_f32 v230, v24, v25
	v_cvt_pk_bf16_f32 v231, v26, v27
	v_cvt_pk_bf16_f32 v232, v20, v21
	v_cvt_pk_bf16_f32 v233, v22, v23
	v_cvt_pk_bf16_f32 v234, v16, v17
	v_cvt_pk_bf16_f32 v235, v18, v19
	v_mov_b32_e32 v236, v228
	v_mov_b32_e32 v237, v229
	v_mov_b32_e32 v238, v230
	v_mov_b32_e32 v239, v231
	v_mov_b32_dpp v228, v232 row_ror:8 row_mask:0xf bank_mask:0xc
	v_mov_b32_dpp v229, v233 row_ror:8 row_mask:0xf bank_mask:0xc
	v_mov_b32_dpp v230, v234 row_ror:8 row_mask:0xf bank_mask:0xc
	v_mov_b32_dpp v231, v235 row_ror:8 row_mask:0xf bank_mask:0xc
	v_mov_b32_dpp v232, v236 row_ror:8 row_mask:0xf bank_mask:0x3
	v_mov_b32_dpp v233, v237 row_ror:8 row_mask:0xf bank_mask:0x3
	v_mov_b32_dpp v234, v238 row_ror:8 row_mask:0xf bank_mask:0x3
	v_mov_b32_dpp v235, v239 row_ror:8 row_mask:0xf bank_mask:0x3
	s_add_u32 s100, s100, 0x8000
	s_addc_u32 s101, s101, 0
	global_store_dwordx4 v240, v[228:231], s[100:101]
	s_add_u32 s100, s100, 0x8000
	s_addc_u32 s101, s101, 0
	global_store_dwordx4 v240, v[232:235], s[100:101]
	v_cvt_pk_bf16_f32 v228, v12, v13
	v_cvt_pk_bf16_f32 v229, v14, v15
	v_cvt_pk_bf16_f32 v230, v8, v9
	v_cvt_pk_bf16_f32 v231, v10, v11
	v_cvt_pk_bf16_f32 v232, v4, v5
	v_cvt_pk_bf16_f32 v233, v6, v7
	v_cvt_pk_bf16_f32 v234, v0, v1
	v_cvt_pk_bf16_f32 v235, v2, v3
	v_mov_b32_e32 v236, v228
	v_mov_b32_e32 v237, v229
	v_mov_b32_e32 v238, v230
	v_mov_b32_e32 v239, v231
	v_mov_b32_dpp v228, v232 row_ror:8 row_mask:0xf bank_mask:0xc
	v_mov_b32_dpp v229, v233 row_ror:8 row_mask:0xf bank_mask:0xc
	v_mov_b32_dpp v230, v234 row_ror:8 row_mask:0xf bank_mask:0xc
	v_mov_b32_dpp v231, v235 row_ror:8 row_mask:0xf bank_mask:0xc
	v_mov_b32_dpp v232, v236 row_ror:8 row_mask:0xf bank_mask:0x3
	v_mov_b32_dpp v233, v237 row_ror:8 row_mask:0xf bank_mask:0x3
	v_mov_b32_dpp v234, v238 row_ror:8 row_mask:0xf bank_mask:0x3
	v_mov_b32_dpp v235, v239 row_ror:8 row_mask:0xf bank_mask:0x3
	s_add_u32 s100, s100, 0x8000
	s_addc_u32 s101, s101, 0
	global_store_dwordx4 v240, v[228:231], s[100:101]
	s_add_u32 s100, s100, 0x8000
	s_addc_u32 s101, s101, 0
	global_store_dwordx4 v240, v[232:235], s[100:101]
	s_mov_b32 s2, 0x80000
	s_mov_b32 s2, 0x90000
	s_nop 0
	s_nop 0
	s_mov_b64 s[16:17], 0x80000
	s_mov_b64 s[16:17], 0x90000
	s_mov_b64 s[16:17], 0xa0000
	s_mov_b64 s[16:17], 0x3c280000
	s_and_b64 vcc, exec, s[10:11]
	s_mov_b32 s45, s44
	s_mov_b32 s38, s6
	s_mov_b32 s2, s8
	s_mov_b64 s[20:21], s[14:15]
	s_mov_b64 s[18:19], s[12:13]
	s_cbranch_vccnz .LBB0_1410

.LBB0_1409:
	ds_read_b128 v[146:149], v143
	ds_read_b128 v[150:153], v143 offset:1024
	ds_read_b128 v[154:157], v143 offset:2048
	ds_read_b128 v[158:161], v143 offset:3072
	s_add_i32 s51, s20, 2
	s_add_u32 s21, s18, 0xfff00080
	s_addc_u32 s22, s19, -1
	s_cmp_eq_u32 s48, s20
	s_cselect_b32 s20, s47, s49
	s_cselect_b32 s23, s7, s22
	s_cselect_b32 s22, s9, s21
	s_cselect_b32 s21, s46, s50
	v_lshl_add_u64 v[194:195], s[18:19], 0, v[136:137]
	s_add_i32 m0, s3, 0xc000
	ds_read_b128 v[162:165], v144
	ds_read_b128 v[166:169], v144 offset:1024
	ds_read_b128 v[170:173], v144 offset:2048
	ds_read_b128 v[174:177], v144 offset:3072
	ds_read_b128 v[178:181], v144 offset:4096
	ds_read_b128 v[182:185], v144 offset:5120
	ds_read_b128 v[186:189], v144 offset:6144
	ds_read_b128 v[190:193], v144 offset:7168
	global_load_lds_dwordx4 v[194:195], off
	v_lshl_add_u64 v[194:195], s[18:19], 0, v[138:139]
	s_add_i32 m0, s3, 0xe000
	s_nop 0
	global_load_lds_dwordx4 v[194:195], off
	s_waitcnt lgkmcnt(8)
	s_barrier
	s_waitcnt lgkmcnt(0)
	s_setprio 1
	s_waitcnt lgkmcnt(0)
	v_mfma_f32_16x16x32_bf16 v[124:127], v[146:149], v[162:165], v[124:127]
	v_mfma_f32_16x16x32_bf16 v[120:123], v[154:157], v[162:165], v[120:123]
	v_mfma_f32_16x16x32_bf16 v[108:111], v[146:149], v[170:173], v[108:111]
	v_mfma_f32_16x16x32_bf16 v[104:107], v[154:157], v[170:173], v[104:107]
	v_mfma_f32_16x16x32_bf16 v[92:95], v[146:149], v[178:181], v[92:95]
	v_mfma_f32_16x16x32_bf16 v[88:91], v[154:157], v[178:181], v[88:91]
	v_mfma_f32_16x16x32_bf16 v[76:79], v[146:149], v[186:189], v[76:79]
	v_mfma_f32_16x16x32_bf16 v[72:75], v[154:157], v[186:189], v[72:75]
	v_mfma_f32_16x16x32_bf16 v[124:127], v[150:153], v[166:169], v[124:127]
	v_mfma_f32_16x16x32_bf16 v[120:123], v[158:161], v[166:169], v[120:123]
	v_mfma_f32_16x16x32_bf16 v[108:111], v[150:153], v[174:177], v[108:111]
	v_mfma_f32_16x16x32_bf16 v[104:107], v[158:161], v[174:177], v[104:107]
	v_mfma_f32_16x16x32_bf16 v[92:95], v[150:153], v[182:185], v[92:95]
	v_mfma_f32_16x16x32_bf16 v[88:91], v[158:161], v[182:185], v[88:91]
	v_mfma_f32_16x16x32_bf16 v[76:79], v[150:153], v[190:193], v[76:79]
	v_mfma_f32_16x16x32_bf16 v[72:75], v[158:161], v[190:193], v[72:75]
	s_setprio 0
	s_barrier
	s_add_i32 s52, s39, s27
	v_lshl_add_u64 v[212:213], s[20:21], 0, v[132:133]
	s_mov_b32 m0, s52
	ds_read_b128 v[194:197], v145
	ds_read_b128 v[198:201], v145 offset:1024
	ds_read_b128 v[204:207], v145 offset:2048
	ds_read_b128 v[208:211], v145 offset:3072
	global_load_lds_dwordx4 v[212:213], off
	v_lshl_add_u64 v[214:215], s[20:21], 0, v[128:129]
	s_add_i32 m0, s52, 0x2000
	s_nop 0
	global_load_lds_dwordx4 v[214:215], off
	s_barrier
	s_waitcnt lgkmcnt(0)
	s_setprio 1
	s_waitcnt lgkmcnt(0)
	v_mfma_f32_16x16x32_bf16 v[116:119], v[194:197], v[162:165], v[116:119]
	v_mfma_f32_16x16x32_bf16 v[112:115], v[204:207], v[162:165], v[112:115]
	v_mfma_f32_16x16x32_bf16 v[100:103], v[194:197], v[170:173], v[100:103]
	v_mfma_f32_16x16x32_bf16 v[96:99], v[204:207], v[170:173], v[96:99]
	v_mfma_f32_16x16x32_bf16 v[84:87], v[194:197], v[178:181], v[84:87]
	v_mfma_f32_16x16x32_bf16 v[80:83], v[204:207], v[178:181], v[80:83]
	v_mfma_f32_16x16x32_bf16 v[68:71], v[194:197], v[186:189], v[68:71]
	v_mfma_f32_16x16x32_bf16 v[64:67], v[204:207], v[186:189], v[64:67]
	v_mfma_f32_16x16x32_bf16 v[116:119], v[198:201], v[166:169], v[116:119]
	v_mfma_f32_16x16x32_bf16 v[112:115], v[208:211], v[166:169], v[112:115]
	v_mfma_f32_16x16x32_bf16 v[100:103], v[198:201], v[174:177], v[100:103]
	v_mfma_f32_16x16x32_bf16 v[96:99], v[208:211], v[174:177], v[96:99]
	v_mfma_f32_16x16x32_bf16 v[84:87], v[198:201], v[182:185], v[84:87]
	v_mfma_f32_16x16x32_bf16 v[80:83], v[208:211], v[182:185], v[80:83]
	v_mfma_f32_16x16x32_bf16 v[68:71], v[198:201], v[190:193], v[68:71]
	v_mfma_f32_16x16x32_bf16 v[64:67], v[208:211], v[190:193], v[64:67]
	s_setprio 0
	s_mov_b32 m0, s3
	v_lshl_add_u64 v[216:217], s[22:23], 0, v[134:135]
	s_barrier
	ds_read_b128 v[162:165], v144 offset:16384
	ds_read_b128 v[166:169], v144 offset:17408
	ds_read_b128 v[170:173], v144 offset:18432
	ds_read_b128 v[174:177], v144 offset:19456
	ds_read_b128 v[178:181], v144 offset:20480
	ds_read_b128 v[182:185], v144 offset:21504
	ds_read_b128 v[186:189], v144 offset:22528
	ds_read_b128 v[190:193], v144 offset:23552
	global_load_lds_dwordx4 v[216:217], off
	v_lshl_add_u64 v[218:219], s[22:23], 0, v[130:131]
	s_mov_b32 m0, s28
	s_nop 0
	global_load_lds_dwordx4 v[218:219], off
	s_barrier
	s_waitcnt lgkmcnt(0)
	s_setprio 1
	s_waitcnt lgkmcnt(0)
	v_mfma_f32_16x16x32_bf16 v[60:63], v[146:149], v[162:165], v[60:63]
	v_mfma_f32_16x16x32_bf16 v[56:59], v[154:157], v[162:165], v[56:59]
	v_mfma_f32_16x16x32_bf16 v[44:47], v[146:149], v[170:173], v[44:47]
	v_mfma_f32_16x16x32_bf16 v[40:43], v[154:157], v[170:173], v[40:43]
	v_mfma_f32_16x16x32_bf16 v[28:31], v[146:149], v[178:181], v[28:31]
	v_mfma_f32_16x16x32_bf16 v[24:27], v[154:157], v[178:181], v[24:27]
	v_mfma_f32_16x16x32_bf16 v[12:15], v[146:149], v[186:189], v[12:15]
	v_mfma_f32_16x16x32_bf16 v[8:11], v[154:157], v[186:189], v[8:11]
	v_mfma_f32_16x16x32_bf16 v[60:63], v[150:153], v[166:169], v[60:63]
	v_mfma_f32_16x16x32_bf16 v[56:59], v[158:161], v[166:169], v[56:59]
	v_mfma_f32_16x16x32_bf16 v[44:47], v[150:153], v[174:177], v[44:47]
	v_mfma_f32_16x16x32_bf16 v[40:43], v[158:161], v[174:177], v[40:43]
	v_mfma_f32_16x16x32_bf16 v[28:31], v[150:153], v[182:185], v[28:31]
	v_mfma_f32_16x16x32_bf16 v[24:27], v[158:161], v[182:185], v[24:27]
	v_mfma_f32_16x16x32_bf16 v[12:15], v[150:153], v[190:193], v[12:15]
	v_mfma_f32_16x16x32_bf16 v[8:11], v[158:161], v[190:193], v[8:11]
	s_setprio 0
	s_barrier
	s_add_u32 s52, s20, 0x40000
	s_addc_u32 s53, s21, 0
	s_add_i32 s54, s40, s27
	v_lshl_add_u64 v[146:147], s[52:53], 0, v[132:133]
	s_mov_b32 m0, s54
	s_nop 0
	global_load_lds_dwordx4 v[146:147], off
	v_lshl_add_u64 v[146:147], s[52:53], 0, v[128:129]
	s_add_i32 m0, s54, 0x2000
	s_nop 0
	global_load_lds_dwordx4 v[146:147], off
	s_waitcnt vmcnt(6)
	s_barrier
	s_setprio 1
	v_mfma_f32_16x16x32_bf16 v[52:55], v[194:197], v[162:165], v[52:55]
	v_mfma_f32_16x16x32_bf16 v[48:51], v[204:207], v[162:165], v[48:51]
	v_mfma_f32_16x16x32_bf16 v[36:39], v[194:197], v[170:173], v[36:39]
	v_mfma_f32_16x16x32_bf16 v[32:35], v[204:207], v[170:173], v[32:35]
	v_mfma_f32_16x16x32_bf16 v[20:23], v[194:197], v[178:181], v[20:23]
	v_mfma_f32_16x16x32_bf16 v[16:19], v[204:207], v[178:181], v[16:19]
	v_mfma_f32_16x16x32_bf16 v[4:7], v[194:197], v[186:189], v[4:7]
	v_mfma_f32_16x16x32_bf16 v[0:3], v[204:207], v[186:189], v[0:3]
	v_mfma_f32_16x16x32_bf16 v[52:55], v[198:201], v[166:169], v[52:55]
	v_mfma_f32_16x16x32_bf16 v[48:51], v[208:211], v[166:169], v[48:51]
	v_mfma_f32_16x16x32_bf16 v[36:39], v[198:201], v[174:177], v[36:39]
	v_mfma_f32_16x16x32_bf16 v[32:35], v[208:211], v[174:177], v[32:35]
	v_mfma_f32_16x16x32_bf16 v[20:23], v[198:201], v[182:185], v[20:23]
	v_mfma_f32_16x16x32_bf16 v[16:19], v[208:211], v[182:185], v[16:19]
	v_mfma_f32_16x16x32_bf16 v[4:7], v[198:201], v[190:193], v[4:7]
	v_mfma_f32_16x16x32_bf16 v[0:3], v[208:211], v[190:193], v[0:3]
	s_setprio 0
	s_add_i32 s52, 0, 0x18000
	v_add_u32_e32 v158, s52, v141
	s_barrier
	ds_read_b128 v[146:149], v158
	ds_read_b128 v[150:153], v158 offset:1024
	ds_read_b128 v[154:157], v158 offset:2048
	ds_read_b128 v[158:161], v158 offset:3072
	s_add_u32 s22, s22, 0x100000
	s_addc_u32 s23, s23, 0
	s_mov_b32 m0, s29
	v_lshl_add_u64 v[194:195], s[22:23], 0, v[134:135]
	ds_read_b128 v[162:165], v144 offset:32768
	ds_read_b128 v[166:169], v144 offset:33792
	ds_read_b128 v[170:173], v144 offset:34816
	ds_read_b128 v[174:177], v144 offset:35840
	ds_read_b128 v[178:181], v144 offset:36864
	ds_read_b128 v[182:185], v144 offset:37888
	ds_read_b128 v[186:189], v144 offset:38912
	ds_read_b128 v[190:193], v144 offset:39936
	global_load_lds_dwordx4 v[194:195], off
	v_lshl_add_u64 v[194:195], s[22:23], 0, v[130:131]
	s_mov_b32 m0, s30
	s_nop 0
	global_load_lds_dwordx4 v[194:195], off
	s_waitcnt lgkmcnt(8)
	s_barrier
	s_waitcnt lgkmcnt(0)
	s_setprio 1
	s_waitcnt lgkmcnt(0)
	v_mfma_f32_16x16x32_bf16 v[124:127], v[146:149], v[162:165], v[124:127]
	v_mfma_f32_16x16x32_bf16 v[120:123], v[154:157], v[162:165], v[120:123]
	v_mfma_f32_16x16x32_bf16 v[108:111], v[146:149], v[170:173], v[108:111]
	v_mfma_f32_16x16x32_bf16 v[104:107], v[154:157], v[170:173], v[104:107]
	v_mfma_f32_16x16x32_bf16 v[92:95], v[146:149], v[178:181], v[92:95]
	v_mfma_f32_16x16x32_bf16 v[88:91], v[154:157], v[178:181], v[88:91]
	v_mfma_f32_16x16x32_bf16 v[76:79], v[146:149], v[186:189], v[76:79]
	v_mfma_f32_16x16x32_bf16 v[72:75], v[154:157], v[186:189], v[72:75]
	v_mfma_f32_16x16x32_bf16 v[124:127], v[150:153], v[166:169], v[124:127]
	v_mfma_f32_16x16x32_bf16 v[120:123], v[158:161], v[166:169], v[120:123]
	v_mfma_f32_16x16x32_bf16 v[108:111], v[150:153], v[174:177], v[108:111]
	v_mfma_f32_16x16x32_bf16 v[104:107], v[158:161], v[174:177], v[104:107]
	v_mfma_f32_16x16x32_bf16 v[92:95], v[150:153], v[182:185], v[92:95]
	v_mfma_f32_16x16x32_bf16 v[88:91], v[158:161], v[182:185], v[88:91]
	v_mfma_f32_16x16x32_bf16 v[76:79], v[150:153], v[190:193], v[76:79]
	v_mfma_f32_16x16x32_bf16 v[72:75], v[158:161], v[190:193], v[72:75]
	s_setprio 0
	s_barrier
	s_add_i32 s22, 0, 0x1c000
	s_add_i32 s23, s52, s27
	v_add_u32_e32 v208, s22, v141
	v_lshl_add_u64 v[212:213], v[212:213], 0, s[0:1]
	s_mov_b32 m0, s23
	ds_read_b128 v[194:197], v208
	ds_read_b128 v[198:201], v208 offset:1024
	ds_read_b128 v[204:207], v208 offset:2048
	ds_read_b128 v[208:211], v208 offset:3072
	global_load_lds_dwordx4 v[212:213], off
	v_lshl_add_u64 v[212:213], v[214:215], 0, s[0:1]
	s_add_i32 m0, s23, 0x2000
	s_nop 0
	global_load_lds_dwordx4 v[212:213], off
	s_barrier
	s_waitcnt lgkmcnt(0)
	s_setprio 1
	s_waitcnt lgkmcnt(0)
	v_mfma_f32_16x16x32_bf16 v[116:119], v[194:197], v[162:165], v[116:119]
	v_mfma_f32_16x16x32_bf16 v[112:115], v[204:207], v[162:165], v[112:115]
	v_mfma_f32_16x16x32_bf16 v[100:103], v[194:197], v[170:173], v[100:103]
	v_mfma_f32_16x16x32_bf16 v[96:99], v[204:207], v[170:173], v[96:99]
	v_mfma_f32_16x16x32_bf16 v[84:87], v[194:197], v[178:181], v[84:87]
	v_mfma_f32_16x16x32_bf16 v[80:83], v[204:207], v[178:181], v[80:83]
	v_mfma_f32_16x16x32_bf16 v[68:71], v[194:197], v[186:189], v[68:71]
	v_mfma_f32_16x16x32_bf16 v[64:67], v[204:207], v[186:189], v[64:67]
	v_mfma_f32_16x16x32_bf16 v[116:119], v[198:201], v[166:169], v[116:119]
	v_mfma_f32_16x16x32_bf16 v[112:115], v[208:211], v[166:169], v[112:115]
	v_mfma_f32_16x16x32_bf16 v[100:103], v[198:201], v[174:177], v[100:103]
	v_mfma_f32_16x16x32_bf16 v[96:99], v[208:211], v[174:177], v[96:99]
	v_mfma_f32_16x16x32_bf16 v[84:87], v[198:201], v[182:185], v[84:87]
	v_mfma_f32_16x16x32_bf16 v[80:83], v[208:211], v[182:185], v[80:83]
	v_mfma_f32_16x16x32_bf16 v[68:71], v[198:201], v[190:193], v[68:71]
	v_mfma_f32_16x16x32_bf16 v[64:67], v[208:211], v[190:193], v[64:67]
	s_setprio 0
	s_mov_b32 m0, s36
	v_lshl_add_u64 v[212:213], v[216:217], 0, s[0:1]
	s_barrier
	ds_read_b128 v[162:165], v144 offset:49152
	ds_read_b128 v[166:169], v144 offset:50176
	ds_read_b128 v[170:173], v144 offset:51200
	ds_read_b128 v[174:177], v144 offset:52224
	ds_read_b128 v[178:181], v144 offset:53248
	ds_read_b128 v[182:185], v144 offset:54272
	ds_read_b128 v[186:189], v144 offset:55296
	ds_read_b128 v[190:193], v144 offset:56320
	global_load_lds_dwordx4 v[212:213], off
	v_lshl_add_u64 v[212:213], v[218:219], 0, s[0:1]
	s_mov_b32 m0, s37
	s_nop 0
	global_load_lds_dwordx4 v[212:213], off
	s_barrier
	s_waitcnt lgkmcnt(0)
	s_setprio 1
	s_waitcnt lgkmcnt(0)
	v_mfma_f32_16x16x32_bf16 v[60:63], v[146:149], v[162:165], v[60:63]
	v_mfma_f32_16x16x32_bf16 v[56:59], v[154:157], v[162:165], v[56:59]
	v_mfma_f32_16x16x32_bf16 v[44:47], v[146:149], v[170:173], v[44:47]
	v_mfma_f32_16x16x32_bf16 v[40:43], v[154:157], v[170:173], v[40:43]
	v_mfma_f32_16x16x32_bf16 v[28:31], v[146:149], v[178:181], v[28:31]
	v_mfma_f32_16x16x32_bf16 v[24:27], v[154:157], v[178:181], v[24:27]
	v_mfma_f32_16x16x32_bf16 v[12:15], v[146:149], v[186:189], v[12:15]
	v_mfma_f32_16x16x32_bf16 v[8:11], v[154:157], v[186:189], v[8:11]
	v_mfma_f32_16x16x32_bf16 v[60:63], v[150:153], v[166:169], v[60:63]
	v_mfma_f32_16x16x32_bf16 v[56:59], v[158:161], v[166:169], v[56:59]
	v_mfma_f32_16x16x32_bf16 v[44:47], v[150:153], v[174:177], v[44:47]
	v_mfma_f32_16x16x32_bf16 v[40:43], v[158:161], v[174:177], v[40:43]
	v_mfma_f32_16x16x32_bf16 v[28:31], v[150:153], v[182:185], v[28:31]
	v_mfma_f32_16x16x32_bf16 v[24:27], v[158:161], v[182:185], v[24:27]
	v_mfma_f32_16x16x32_bf16 v[12:15], v[150:153], v[190:193], v[12:15]
	v_mfma_f32_16x16x32_bf16 v[8:11], v[158:161], v[190:193], v[8:11]
	s_setprio 0
	s_barrier
	s_add_u32 s20, s20, 0x40080
	s_addc_u32 s21, s21, 0
	s_add_i32 s22, s22, s27
	v_lshl_add_u64 v[146:147], s[20:21], 0, v[132:133]
	s_mov_b32 m0, s22
	s_nop 0
	global_load_lds_dwordx4 v[146:147], off
	v_lshl_add_u64 v[146:147], s[20:21], 0, v[128:129]
	s_add_i32 m0, s22, 0x2000
	s_nop 0
	global_load_lds_dwordx4 v[146:147], off
	s_waitcnt vmcnt(6)
	s_barrier
	s_setprio 1
	v_mfma_f32_16x16x32_bf16 v[52:55], v[194:197], v[162:165], v[52:55]
	v_mfma_f32_16x16x32_bf16 v[48:51], v[204:207], v[162:165], v[48:51]
	v_mfma_f32_16x16x32_bf16 v[36:39], v[194:197], v[170:173], v[36:39]
	v_mfma_f32_16x16x32_bf16 v[32:35], v[204:207], v[170:173], v[32:35]
	v_mfma_f32_16x16x32_bf16 v[20:23], v[194:197], v[178:181], v[20:23]
	v_mfma_f32_16x16x32_bf16 v[16:19], v[204:207], v[178:181], v[16:19]
	v_mfma_f32_16x16x32_bf16 v[4:7], v[194:197], v[186:189], v[4:7]
	v_mfma_f32_16x16x32_bf16 v[0:3], v[204:207], v[186:189], v[0:3]
	v_mfma_f32_16x16x32_bf16 v[52:55], v[198:201], v[166:169], v[52:55]
	v_mfma_f32_16x16x32_bf16 v[48:51], v[208:211], v[166:169], v[48:51]
	v_mfma_f32_16x16x32_bf16 v[36:39], v[198:201], v[174:177], v[36:39]
	v_mfma_f32_16x16x32_bf16 v[32:35], v[208:211], v[174:177], v[32:35]
	v_mfma_f32_16x16x32_bf16 v[20:23], v[198:201], v[182:185], v[20:23]
	v_mfma_f32_16x16x32_bf16 v[16:19], v[208:211], v[182:185], v[16:19]
	v_mfma_f32_16x16x32_bf16 v[4:7], v[198:201], v[190:193], v[4:7]
	v_mfma_f32_16x16x32_bf16 v[0:3], v[208:211], v[190:193], v[0:3]
	s_setprio 0
	s_add_u32 s18, s18, 0x100
	s_addc_u32 s19, s19, 0
	s_add_u32 s49, s49, 0x100
	s_addc_u32 s50, s50, 0
	s_cmp_ge_i32 s51, s45
	s_mov_b32 s20, s51
	s_barrier
	s_cbranch_scc0 .LBB0_1409
	s_branch .LBB0_1404

.LBB0_1621:
	s_or_b64 exec, exec, s[0:1]
	v_readlane_b32 s0, v247, 12
	v_mov_b32_e32 v8, v202
	v_readlane_b32 s1, v247, 13
	s_waitcnt lgkmcnt(0)
	s_barrier
	s_and_b64 vcc, exec, s[0:1]
	v_readfirstlane_b32 s26, v8
	s_cbranch_vccz .LBB0_1635
	v_lshlrev_b32_e32 v0, 4, v8
	v_add_u32_e32 v1, 0x2000, v0
	v_ashrrev_i32_e32 v2, 31, v1
	v_lshrrev_b32_e32 v2, 22, v2
	v_add_u32_e32 v2, v1, v2
	v_ashrrev_i32_e32 v9, 10, v2
	v_mul_i32_i24_e32 v2, 0x400, v9
	v_sub_u32_e32 v1, v1, v2
	v_lshrrev_b32_e32 v2, 4, v1
	v_bitop3_b32 v1, v2, v1, 32 bitop3:0x6c
	v_ashrrev_i32_e32 v2, 31, v1
	v_lshrrev_b32_e32 v2, 26, v2
	v_add_u32_e32 v2, v1, v2
	v_lshlrev_b32_e32 v3, 3, v9
	v_ashrrev_i32_e32 v10, 6, v2
	v_and_b32_e32 v3, -16, v3
	s_add_u32 s27, s58, 0xc100000
	v_readlane_b32 s3, v248, 59
	v_readlane_b32 s4, v248, 60
	v_add_u32_e32 v3, v10, v3
	s_addc_u32 s28, s59, 0
	s_sub_i32 s4, s3, s4
	v_and_b32_e32 v4, 3, v10
	s_mov_b32 s3, 0x3ffe0
	v_lshrrev_b32_e32 v5, 2, v3
	v_lshlrev_b32_e32 v6, 1, v3
	v_and_b32_e32 v2, 0xc0, v2
	v_and_or_b32 v4, v3, s3, v4
	v_and_b32_e32 v5, 4, v5
	v_and_b32_e32 v6, 24, v6
	v_sub_u32_e32 v1, v1, v2
	v_mov_b32_e32 v2, 1
	v_or3_b32 v4, v4, v5, v6
	v_lshlrev_b32_e32 v5, 5, v9
	v_ashrrev_i16_sdwa v1, v2, sext(v1) dst_sel:DWORD dst_unused:UNUSED_PAD src0_sel:DWORD src1_sel:BYTE_0
	v_and_b32_e32 v5, 32, v5
	v_bfe_i32 v11, v1, 0, 16
	v_add_lshl_u32 v1, v5, v11, 1
	v_lshl_add_u32 v128, v4, 14, v1
	v_lshl_add_u32 v130, v3, 14, v1
	v_bfe_i32 v1, v8, 27, 1
	v_lshrrev_b32_e32 v1, 22, v1
	v_add_u32_e32 v1, v0, v1
	v_and_b32_e32 v1, 0xfffffc00, v1
	v_sub_u32_e32 v0, v0, v1
	v_lshrrev_b32_e32 v1, 4, v0
	v_ashrrev_i32_e32 v3, 31, v8
	v_bitop3_b32 v0, v1, v0, 32 bitop3:0x6c
	v_lshrrev_b32_e32 v3, 26, v3
	v_ashrrev_i32_e32 v1, 31, v0
	v_add_u32_e32 v3, v8, v3
	v_lshrrev_b32_e32 v1, 26, v1
	v_ashrrev_i32_e32 v13, 6, v3
	v_readlane_b32 s6, v248, 61
	v_add_u32_e32 v1, v0, v1
	v_lshlrev_b32_e32 v3, 3, v13
	v_readlane_b32 s7, v248, 62
	v_ashrrev_i32_e32 v12, 6, v1
	v_and_b32_e32 v3, -16, v3
	s_ashr_i32 s0, s26, 6
	v_readlane_b32 s1, v248, 58
	s_ashr_i32 s5, s4, 31
	s_ashr_i32 s7, s6, 31
	v_add_u32_e32 v3, v12, v3
	s_ashr_i32 s2, s26, 8
	s_lshl_b32 s29, s0, 10
	s_lshl_b32 s1, s1, 22
	s_lshl_b64 s[4:5], s[4:5], 7
	s_mov_b32 s52, s6
	s_lshl_b64 s[6:7], s[6:7], 22
	v_and_b32_e32 v4, 3, v12
	v_lshrrev_b32_e32 v5, 2, v3
	v_lshlrev_b32_e32 v6, 1, v3
	v_and_b32_e32 v1, 0xc0, v1
	v_and_or_b32 v4, v3, s3, v4
	v_and_b32_e32 v5, 4, v5
	v_and_b32_e32 v6, 24, v6
	v_sub_u32_e32 v0, v0, v1
	s_add_u32 s1, s27, s1
	v_or3_b32 v4, v4, v5, v6
	v_lshlrev_b32_e32 v5, 5, v13
	v_ashrrev_i16_sdwa v0, v2, sext(v0) dst_sel:DWORD dst_unused:UNUSED_PAD src0_sel:DWORD src1_sel:BYTE_0
	s_addc_u32 s3, s28, 0
	v_and_b32_e32 v5, 32, v5
	v_bfe_i32 v14, v0, 0, 16
	s_add_u32 s22, s1, s4
	v_add_lshl_u32 v0, v5, v14, 1
	s_addc_u32 s23, s3, s5
	s_add_i32 s30, s29, 0
	v_lshl_add_u32 v132, v4, 14, v0
	s_add_i32 m0, s30, 0x10000
	v_readlane_b32 s8, v248, 63
	v_mov_b32_e32 v230, s2
	v_lshlrev_b32_e32 v230, 19, v230
	v_add_u32_e32 v132, v132, v230
	v_add_u32_e32 v230, 0x100000, v230
	v_add_u32_e32 v128, v128, v230
	global_load_lds_dwordx4 v132, s[22:23]
	s_add_i32 m0, s30, 0x12000
	v_readlane_b32 s9, v247, 0
	s_add_u32 s1, s8, s6
	s_addc_u32 s3, s9, s7
	s_add_u32 s20, s1, s4
	v_lshl_add_u32 v134, v3, 14, v0
	global_load_lds_dwordx4 v128, s[22:23]
	s_addc_u32 s21, s3, s5
	s_mov_b32 m0, s30
	s_add_i32 s31, s30, 0x2000
	global_load_lds_dwordx4 v134, s[20:21]
	s_mov_b32 m0, s31
	s_add_u32 s4, s22, 0x80000
	global_load_lds_dwordx4 v130, s[20:21]
	s_addc_u32 s5, s23, 0
	s_add_i32 m0, s30, 0x14000
	v_mov_b32_e32 v133, 0
	global_load_lds_dwordx4 v132, s[4:5]
	s_add_i32 m0, s30, 0x16000
	v_mov_b32_e32 v129, v133
	global_load_lds_dwordx4 v128, s[4:5]
	s_add_u32 s4, s20, 0x200000
	s_addc_u32 s5, s21, 0
	s_add_i32 s34, s30, 0x4000
	s_mov_b32 m0, s34
	s_add_i32 s35, s30, 0x6000
	global_load_lds_dwordx4 v134, s[4:5]
	s_mov_b32 m0, s35
	v_mov_b32_e32 v135, v133
	global_load_lds_dwordx4 v130, s[4:5]
	v_mov_b32_e32 v131, v133
	s_mov_b32 s36, 0
	v_lshl_add_u64 v[6:7], s[22:23], 0, v[132:133]
	v_lshl_add_u64 v[4:5], s[22:23], 0, v[128:129]
	v_lshl_add_u64 v[2:3], s[20:21], 0, v[134:135]
	s_cmp_lg_u32 s2, 1
	v_lshl_add_u64 v[0:1], s[20:21], 0, v[130:131]
	s_cbranch_scc1 .LBB0_1624
	s_barrier
.LBB0_1624:
	s_lshl_b32 s0, s0, 5
	s_and_b32 s6, s0, 0x60
	s_mov_b64 s[0:1], 0x80
	s_add_i32 m0, s30, 0x18000
	v_lshl_add_u64 v[6:7], v[6:7], 0, s[0:1]
	s_lshl_b32 s3, s2, 13
	s_lshl_b32 s7, s6, 7
	s_waitcnt vmcnt(4)
	s_barrier
	global_load_lds_dwordx4 v[6:7], off
	v_lshl_add_u64 v[4:5], v[4:5], 0, s[0:1]
	s_add_i32 m0, s30, 0x1a000
	s_add_i32 s37, s30, 0x8000
	s_add_i32 s38, s30, 0xa000
	global_load_lds_dwordx4 v[4:5], off
	v_lshl_add_u64 v[2:3], v[2:3], 0, s[0:1]
	s_mov_b32 m0, s37
	s_add_u32 s4, s22, 0x80080
	global_load_lds_dwordx4 v[2:3], off
	v_lshl_add_u64 v[0:1], v[0:1], 0, s[0:1]
	s_mov_b32 m0, s38
	s_addc_u32 s5, s23, 0
	global_load_lds_dwordx4 v[0:1], off
	s_add_i32 m0, s30, 0x1c000
	v_lshl_add_u64 v[0:1], s[4:5], 0, v[132:133]
	global_load_lds_dwordx4 v[0:1], off
	v_lshl_add_u64 v[0:1], s[4:5], 0, v[128:129]
	s_add_i32 m0, s30, 0x1e000
	s_add_i32 s39, 0, 0x10000
	global_load_lds_dwordx4 v[0:1], off
	v_lshrrev_b32_e32 v1, 1, v8
	v_and_b32_e32 v1, 24, v1
	v_and_b32_e32 v0, 15, v8
	v_lshlrev_b32_e32 v2, 1, v1
	v_lshl_or_b32 v140, s2, 6, v0
	v_lshl_or_b32 v0, v0, 6, v2
	v_lshlrev_b32_e32 v2, 2, v8
	v_and_b32_e32 v2, 32, v2
	v_bitop3_b32 v3, v0, s3, v2 bitop3:0xde
	v_bitop3_b32 v141, v0, s7, v2 bitop3:0xde
	v_lshlrev_b32_e32 v0, 17, v13
	v_and_b32_e32 v0, 0xfffc0000, v0
	v_or_b32_e32 v142, s6, v1
	v_lshl_add_u32 v0, v12, 14, v0
	v_and_b32_e32 v1, 1, v13
	v_lshl_or_b32 v0, v1, 6, v0
	v_lshl_add_u32 v136, v14, 1, v0
	v_lshlrev_b32_e32 v0, 17, v9
	v_and_b32_e32 v0, 0xfffc0000, v0
	s_waitcnt vmcnt(6)
	v_lshl_add_u32 v0, v10, 14, v0
	v_and_b32_e32 v1, 1, v9
	v_lshl_or_b32 v0, v1, 6, v0
	s_add_i32 s40, 0, 0x14000
	v_mov_b32_e32 v137, v133
	v_lshl_add_u32 v138, v11, 1, v0
	v_mov_b32_e32 v139, v133
	v_add_u32_e32 v143, s39, v141
	v_add_u32_e32 v144, 0, v3
	v_add_u32_e32 v145, s40, v141
	s_mov_b64 s[2:3], 0x80000
	s_mov_b32 s41, 0x80000
	s_mov_b64 s[4:5], 0x90000
	s_mov_b32 s42, 0x90000
	s_mov_b64 s[6:7], 0xa0000
	s_mov_b32 s43, 0xa0000
	s_mov_b64 s[8:9], 0xb0000
	s_mov_b32 s44, 0xb0000
	s_barrier
	s_branch .LBB0_1627

.LBB0_1626:
	s_add_i32 s36, s36, 1
	v_readlane_b32 s11, v248, 58
	v_readlane_b32 s20, v247, 4
	v_readlane_b32 s21, v247, 5
	s_add_u32 s20, s58, s20
	s_addc_u32 s21, s59, s21
	s_mov_b32 s100, s20
	s_mov_b32 s101, s21
	v_and_b32_e32 v242, 15, v202
	v_bfe_u32 v243, v202, 4, 2
	v_bfe_u32 v244, v202, 6, 2
	v_lshrrev_b32_e32 v245, 8, v202
	v_and_b32_e32 v240, 7, v242
	v_lshl_add_u32 v240, v245, 6, v240
	v_lshl_add_u32 v240, s62, 8, v240
	v_lshlrev_b32_e32 v240, 12, v240
	v_lshrrev_b32_e32 v241, 3, v242
	v_lshlrev_b32_e32 v241, 6, v241
	v_lshl_add_u32 v241, v244, 7, v241
	v_lshl_add_u32 v241, v243, 4, v241
	v_add_u32_e32 v240, v240, v241
	s_lshl_b32 s98, s11, 9
	v_add_u32_e32 v240, s98, v240
	v_cvt_pk_bf16_f32 v228, v124, v125
	v_cvt_pk_bf16_f32 v229, v126, v127
	v_cvt_pk_bf16_f32 v230, v120, v121
	v_cvt_pk_bf16_f32 v231, v122, v123
	v_cvt_pk_bf16_f32 v232, v116, v117
	v_cvt_pk_bf16_f32 v233, v118, v119
	v_cvt_pk_bf16_f32 v234, v112, v113
	v_cvt_pk_bf16_f32 v235, v114, v115
	v_mov_b32_e32 v236, v228
	v_mov_b32_e32 v237, v229
	v_mov_b32_e32 v238, v230
	v_mov_b32_e32 v239, v231
	v_mov_b32_dpp v228, v232 row_ror:8 row_mask:0xf bank_mask:0xc
	v_mov_b32_dpp v229, v233 row_ror:8 row_mask:0xf bank_mask:0xc
	v_mov_b32_dpp v230, v234 row_ror:8 row_mask:0xf bank_mask:0xc
	v_mov_b32_dpp v231, v235 row_ror:8 row_mask:0xf bank_mask:0xc
	v_mov_b32_dpp v232, v236 row_ror:8 row_mask:0xf bank_mask:0x3
	v_mov_b32_dpp v233, v237 row_ror:8 row_mask:0xf bank_mask:0x3
	v_mov_b32_dpp v234, v238 row_ror:8 row_mask:0xf bank_mask:0x3
	v_mov_b32_dpp v235, v239 row_ror:8 row_mask:0xf bank_mask:0x3
	global_store_dwordx4 v240, v[228:231], s[100:101]
	s_add_u32 s100, s100, 0x8000
	s_addc_u32 s101, s101, 0
	global_store_dwordx4 v240, v[232:235], s[100:101]
	v_cvt_pk_bf16_f32 v228, v108, v109
	v_cvt_pk_bf16_f32 v229, v110, v111
	v_cvt_pk_bf16_f32 v230, v104, v105
	v_cvt_pk_bf16_f32 v231, v106, v107
	v_cvt_pk_bf16_f32 v232, v100, v101
	v_cvt_pk_bf16_f32 v233, v102, v103
	v_cvt_pk_bf16_f32 v234, v96, v97
	v_cvt_pk_bf16_f32 v235, v98, v99
	v_mov_b32_e32 v236, v228
	v_mov_b32_e32 v237, v229
	v_mov_b32_e32 v238, v230
	v_mov_b32_e32 v239, v231
	v_mov_b32_dpp v228, v232 row_ror:8 row_mask:0xf bank_mask:0xc
	v_mov_b32_dpp v229, v233 row_ror:8 row_mask:0xf bank_mask:0xc
	v_mov_b32_dpp v230, v234 row_ror:8 row_mask:0xf bank_mask:0xc
	v_mov_b32_dpp v231, v235 row_ror:8 row_mask:0xf bank_mask:0xc
	v_mov_b32_dpp v232, v236 row_ror:8 row_mask:0xf bank_mask:0x3
	v_mov_b32_dpp v233, v237 row_ror:8 row_mask:0xf bank_mask:0x3
	v_mov_b32_dpp v234, v238 row_ror:8 row_mask:0xf bank_mask:0x3
	v_mov_b32_dpp v235, v239 row_ror:8 row_mask:0xf bank_mask:0x3
	s_add_u32 s100, s100, 0x8000
	s_addc_u32 s101, s101, 0
	global_store_dwordx4 v240, v[228:231], s[100:101]
	s_add_u32 s100, s100, 0x8000
	s_addc_u32 s101, s101, 0
	global_store_dwordx4 v240, v[232:235], s[100:101]
	v_cvt_pk_bf16_f32 v228, v92, v93
	v_cvt_pk_bf16_f32 v229, v94, v95
	v_cvt_pk_bf16_f32 v230, v88, v89
	v_cvt_pk_bf16_f32 v231, v90, v91
	v_cvt_pk_bf16_f32 v232, v84, v85
	v_cvt_pk_bf16_f32 v233, v86, v87
	v_cvt_pk_bf16_f32 v234, v80, v81
	v_cvt_pk_bf16_f32 v235, v82, v83
	v_mov_b32_e32 v236, v228
	v_mov_b32_e32 v237, v229
	v_mov_b32_e32 v238, v230
	v_mov_b32_e32 v239, v231
	v_mov_b32_dpp v228, v232 row_ror:8 row_mask:0xf bank_mask:0xc
	v_mov_b32_dpp v229, v233 row_ror:8 row_mask:0xf bank_mask:0xc
	v_mov_b32_dpp v230, v234 row_ror:8 row_mask:0xf bank_mask:0xc
	v_mov_b32_dpp v231, v235 row_ror:8 row_mask:0xf bank_mask:0xc
	v_mov_b32_dpp v232, v236 row_ror:8 row_mask:0xf bank_mask:0x3
	v_mov_b32_dpp v233, v237 row_ror:8 row_mask:0xf bank_mask:0x3
	v_mov_b32_dpp v234, v238 row_ror:8 row_mask:0xf bank_mask:0x3
	v_mov_b32_dpp v235, v239 row_ror:8 row_mask:0xf bank_mask:0x3
	s_add_u32 s100, s100, 0x8000
	s_addc_u32 s101, s101, 0
	global_store_dwordx4 v240, v[228:231], s[100:101]
	s_add_u32 s100, s100, 0x8000
	s_addc_u32 s101, s101, 0
	global_store_dwordx4 v240, v[232:235], s[100:101]
	v_cvt_pk_bf16_f32 v228, v76, v77
	v_cvt_pk_bf16_f32 v229, v78, v79
	v_cvt_pk_bf16_f32 v230, v72, v73
	v_cvt_pk_bf16_f32 v231, v74, v75
	v_cvt_pk_bf16_f32 v232, v68, v69
	v_cvt_pk_bf16_f32 v233, v70, v71
	v_cvt_pk_bf16_f32 v234, v64, v65
	v_cvt_pk_bf16_f32 v235, v66, v67
	v_mov_b32_e32 v236, v228
	v_mov_b32_e32 v237, v229
	v_mov_b32_e32 v238, v230
	v_mov_b32_e32 v239, v231
	v_mov_b32_dpp v228, v232 row_ror:8 row_mask:0xf bank_mask:0xc
	v_mov_b32_dpp v229, v233 row_ror:8 row_mask:0xf bank_mask:0xc
	v_mov_b32_dpp v230, v234 row_ror:8 row_mask:0xf bank_mask:0xc
	v_mov_b32_dpp v231, v235 row_ror:8 row_mask:0xf bank_mask:0xc
	v_mov_b32_dpp v232, v236 row_ror:8 row_mask:0xf bank_mask:0x3
	v_mov_b32_dpp v233, v237 row_ror:8 row_mask:0xf bank_mask:0x3
	v_mov_b32_dpp v234, v238 row_ror:8 row_mask:0xf bank_mask:0x3
	v_mov_b32_dpp v235, v239 row_ror:8 row_mask:0xf bank_mask:0x3
	s_add_u32 s100, s100, 0x8000
	s_addc_u32 s101, s101, 0
	global_store_dwordx4 v240, v[228:231], s[100:101]
	s_add_u32 s100, s100, 0x8000
	s_addc_u32 s101, s101, 0
	global_store_dwordx4 v240, v[232:235], s[100:101]
	v_cvt_pk_bf16_f32 v228, v60, v61
	v_cvt_pk_bf16_f32 v229, v62, v63
	v_cvt_pk_bf16_f32 v230, v56, v57
	v_cvt_pk_bf16_f32 v231, v58, v59
	v_cvt_pk_bf16_f32 v232, v52, v53
	v_cvt_pk_bf16_f32 v233, v54, v55
	v_cvt_pk_bf16_f32 v234, v48, v49
	v_cvt_pk_bf16_f32 v235, v50, v51
	v_mov_b32_e32 v236, v228
	v_mov_b32_e32 v237, v229
	v_mov_b32_e32 v238, v230
	v_mov_b32_e32 v239, v231
	v_mov_b32_dpp v228, v232 row_ror:8 row_mask:0xf bank_mask:0xc
	v_mov_b32_dpp v229, v233 row_ror:8 row_mask:0xf bank_mask:0xc
	v_mov_b32_dpp v230, v234 row_ror:8 row_mask:0xf bank_mask:0xc
	v_mov_b32_dpp v231, v235 row_ror:8 row_mask:0xf bank_mask:0xc
	v_mov_b32_dpp v232, v236 row_ror:8 row_mask:0xf bank_mask:0x3
	v_mov_b32_dpp v233, v237 row_ror:8 row_mask:0xf bank_mask:0x3
	v_mov_b32_dpp v234, v238 row_ror:8 row_mask:0xf bank_mask:0x3
	v_mov_b32_dpp v235, v239 row_ror:8 row_mask:0xf bank_mask:0x3
	s_add_u32 s100, s100, 0x48000
	s_addc_u32 s101, s101, 0
	global_store_dwordx4 v240, v[228:231], s[100:101]
	s_add_u32 s100, s100, 0x8000
	s_addc_u32 s101, s101, 0
	global_store_dwordx4 v240, v[232:235], s[100:101]
	v_cvt_pk_bf16_f32 v228, v44, v45
	v_cvt_pk_bf16_f32 v229, v46, v47
	v_cvt_pk_bf16_f32 v230, v40, v41
	v_cvt_pk_bf16_f32 v231, v42, v43
	v_cvt_pk_bf16_f32 v232, v36, v37
	v_cvt_pk_bf16_f32 v233, v38, v39
	v_cvt_pk_bf16_f32 v234, v32, v33
	v_cvt_pk_bf16_f32 v235, v34, v35
	v_mov_b32_e32 v236, v228
	v_mov_b32_e32 v237, v229
	v_mov_b32_e32 v238, v230
	v_mov_b32_e32 v239, v231
	v_mov_b32_dpp v228, v232 row_ror:8 row_mask:0xf bank_mask:0xc
	v_mov_b32_dpp v229, v233 row_ror:8 row_mask:0xf bank_mask:0xc
	v_mov_b32_dpp v230, v234 row_ror:8 row_mask:0xf bank_mask:0xc
	v_mov_b32_dpp v231, v235 row_ror:8 row_mask:0xf bank_mask:0xc
	v_mov_b32_dpp v232, v236 row_ror:8 row_mask:0xf bank_mask:0x3
	v_mov_b32_dpp v233, v237 row_ror:8 row_mask:0xf bank_mask:0x3
	v_mov_b32_dpp v234, v238 row_ror:8 row_mask:0xf bank_mask:0x3
	v_mov_b32_dpp v235, v239 row_ror:8 row_mask:0xf bank_mask:0x3
	s_add_u32 s100, s100, 0x8000
	s_addc_u32 s101, s101, 0
	global_store_dwordx4 v240, v[228:231], s[100:101]
	s_add_u32 s100, s100, 0x8000
	s_addc_u32 s101, s101, 0
	global_store_dwordx4 v240, v[232:235], s[100:101]
	v_cvt_pk_bf16_f32 v228, v28, v29
	v_cvt_pk_bf16_f32 v229, v30, v31
	v_cvt_pk_bf16_f32 v230, v24, v25
	v_cvt_pk_bf16_f32 v231, v26, v27
	v_cvt_pk_bf16_f32 v232, v20, v21
	v_cvt_pk_bf16_f32 v233, v22, v23
	v_cvt_pk_bf16_f32 v234, v16, v17
	v_cvt_pk_bf16_f32 v235, v18, v19
	v_mov_b32_e32 v236, v228
	v_mov_b32_e32 v237, v229
	v_mov_b32_e32 v238, v230
	v_mov_b32_e32 v239, v231
	v_mov_b32_dpp v228, v232 row_ror:8 row_mask:0xf bank_mask:0xc
	v_mov_b32_dpp v229, v233 row_ror:8 row_mask:0xf bank_mask:0xc
	v_mov_b32_dpp v230, v234 row_ror:8 row_mask:0xf bank_mask:0xc
	v_mov_b32_dpp v231, v235 row_ror:8 row_mask:0xf bank_mask:0xc
	v_mov_b32_dpp v232, v236 row_ror:8 row_mask:0xf bank_mask:0x3
	v_mov_b32_dpp v233, v237 row_ror:8 row_mask:0xf bank_mask:0x3
	v_mov_b32_dpp v234, v238 row_ror:8 row_mask:0xf bank_mask:0x3
	v_mov_b32_dpp v235, v239 row_ror:8 row_mask:0xf bank_mask:0x3
	s_add_u32 s100, s100, 0x8000
	s_addc_u32 s101, s101, 0
	global_store_dwordx4 v240, v[228:231], s[100:101]
	s_add_u32 s100, s100, 0x8000
	s_addc_u32 s101, s101, 0
	global_store_dwordx4 v240, v[232:235], s[100:101]
	v_cvt_pk_bf16_f32 v228, v12, v13
	v_cvt_pk_bf16_f32 v229, v14, v15
	v_cvt_pk_bf16_f32 v230, v8, v9
	v_cvt_pk_bf16_f32 v231, v10, v11
	v_cvt_pk_bf16_f32 v232, v4, v5
	v_cvt_pk_bf16_f32 v233, v6, v7
	v_cvt_pk_bf16_f32 v234, v0, v1
	v_cvt_pk_bf16_f32 v235, v2, v3
	v_mov_b32_e32 v236, v228
	v_mov_b32_e32 v237, v229
	v_mov_b32_e32 v238, v230
	v_mov_b32_e32 v239, v231
	v_mov_b32_dpp v228, v232 row_ror:8 row_mask:0xf bank_mask:0xc
	v_mov_b32_dpp v229, v233 row_ror:8 row_mask:0xf bank_mask:0xc
	v_mov_b32_dpp v230, v234 row_ror:8 row_mask:0xf bank_mask:0xc
	v_mov_b32_dpp v231, v235 row_ror:8 row_mask:0xf bank_mask:0xc
	v_mov_b32_dpp v232, v236 row_ror:8 row_mask:0xf bank_mask:0x3
	v_mov_b32_dpp v233, v237 row_ror:8 row_mask:0xf bank_mask:0x3
	v_mov_b32_dpp v234, v238 row_ror:8 row_mask:0xf bank_mask:0x3
	v_mov_b32_dpp v235, v239 row_ror:8 row_mask:0xf bank_mask:0x3
	s_add_u32 s100, s100, 0x8000
	s_addc_u32 s101, s101, 0
	global_store_dwordx4 v240, v[228:231], s[100:101]
	s_add_u32 s100, s100, 0x8000
	s_addc_u32 s101, s101, 0
	global_store_dwordx4 v240, v[232:235], s[100:101]
	s_nop 0
	s_nop 0
	s_mov_b64 s[20:21], 0x3c280000
	v_writelane_b32 v247, s20, 4
	v_writelane_b32 v247, s21, 5
	s_and_b64 vcc, exec, s[14:15]
	s_mov_b32 s33, s45
	s_mov_b32 s11, s10
	s_mov_b32 s52, s12
	s_mov_b64 s[22:23], s[18:19]
	s_mov_b64 s[20:21], s[16:17]
	v_writelane_b32 v248, s11, 58
	s_cbranch_vccnz .LBB0_1632

.LBB0_1631:
	ds_read_b128 v[146:149], v143
	ds_read_b128 v[150:153], v143 offset:1024
	ds_read_b128 v[154:157], v143 offset:2048
	ds_read_b128 v[158:161], v143 offset:3072
	s_add_i32 s51, s22, 2
	s_add_u32 s23, s20, 0xffe00080
	s_addc_u32 s24, s21, -1
	s_cmp_eq_u32 s48, s22
	s_cselect_b32 s22, s47, s49
	s_cselect_b32 s25, s11, s24
	s_cselect_b32 s24, s13, s23
	s_cselect_b32 s23, s46, s50
	v_lshl_add_u64 v[194:195], s[20:21], 0, v[136:137]
	s_add_i32 m0, s30, 0xc000
	ds_read_b128 v[162:165], v144
	ds_read_b128 v[166:169], v144 offset:1024
	ds_read_b128 v[170:173], v144 offset:2048
	ds_read_b128 v[174:177], v144 offset:3072
	ds_read_b128 v[178:181], v144 offset:4096
	ds_read_b128 v[182:185], v144 offset:5120
	ds_read_b128 v[186:189], v144 offset:6144
	ds_read_b128 v[190:193], v144 offset:7168
	global_load_lds_dwordx4 v[194:195], off
	v_lshl_add_u64 v[194:195], s[20:21], 0, v[138:139]
	s_add_i32 m0, s30, 0xe000
	s_nop 0
	global_load_lds_dwordx4 v[194:195], off
	s_waitcnt lgkmcnt(8)
	s_barrier
	s_waitcnt lgkmcnt(0)
	s_setprio 1
	s_waitcnt lgkmcnt(0)
	v_mfma_f32_16x16x32_bf16 v[124:127], v[146:149], v[162:165], v[124:127]
	v_mfma_f32_16x16x32_bf16 v[120:123], v[154:157], v[162:165], v[120:123]
	v_mfma_f32_16x16x32_bf16 v[108:111], v[146:149], v[170:173], v[108:111]
	v_mfma_f32_16x16x32_bf16 v[104:107], v[154:157], v[170:173], v[104:107]
	v_mfma_f32_16x16x32_bf16 v[92:95], v[146:149], v[178:181], v[92:95]
	v_mfma_f32_16x16x32_bf16 v[88:91], v[154:157], v[178:181], v[88:91]
	v_mfma_f32_16x16x32_bf16 v[76:79], v[146:149], v[186:189], v[76:79]
	v_mfma_f32_16x16x32_bf16 v[72:75], v[154:157], v[186:189], v[72:75]
	v_mfma_f32_16x16x32_bf16 v[124:127], v[150:153], v[166:169], v[124:127]
	v_mfma_f32_16x16x32_bf16 v[120:123], v[158:161], v[166:169], v[120:123]
	v_mfma_f32_16x16x32_bf16 v[108:111], v[150:153], v[174:177], v[108:111]
	v_mfma_f32_16x16x32_bf16 v[104:107], v[158:161], v[174:177], v[104:107]
	v_mfma_f32_16x16x32_bf16 v[92:95], v[150:153], v[182:185], v[92:95]
	v_mfma_f32_16x16x32_bf16 v[88:91], v[158:161], v[182:185], v[88:91]
	v_mfma_f32_16x16x32_bf16 v[76:79], v[150:153], v[190:193], v[76:79]
	v_mfma_f32_16x16x32_bf16 v[72:75], v[158:161], v[190:193], v[72:75]
	s_setprio 0
	s_barrier
	s_add_i32 s52, s39, s29
	v_lshl_add_u64 v[212:213], s[22:23], 0, v[132:133]
	s_mov_b32 m0, s52
	ds_read_b128 v[194:197], v145
	ds_read_b128 v[198:201], v145 offset:1024
	ds_read_b128 v[204:207], v145 offset:2048
	ds_read_b128 v[208:211], v145 offset:3072
	global_load_lds_dwordx4 v[212:213], off
	v_lshl_add_u64 v[214:215], s[22:23], 0, v[128:129]
	s_add_i32 m0, s52, 0x2000
	s_nop 0
	global_load_lds_dwordx4 v[214:215], off
	s_barrier
	s_waitcnt lgkmcnt(0)
	s_setprio 1
	s_waitcnt lgkmcnt(0)
	v_mfma_f32_16x16x32_bf16 v[116:119], v[194:197], v[162:165], v[116:119]
	v_mfma_f32_16x16x32_bf16 v[112:115], v[204:207], v[162:165], v[112:115]
	v_mfma_f32_16x16x32_bf16 v[100:103], v[194:197], v[170:173], v[100:103]
	v_mfma_f32_16x16x32_bf16 v[96:99], v[204:207], v[170:173], v[96:99]
	v_mfma_f32_16x16x32_bf16 v[84:87], v[194:197], v[178:181], v[84:87]
	v_mfma_f32_16x16x32_bf16 v[80:83], v[204:207], v[178:181], v[80:83]
	v_mfma_f32_16x16x32_bf16 v[68:71], v[194:197], v[186:189], v[68:71]
	v_mfma_f32_16x16x32_bf16 v[64:67], v[204:207], v[186:189], v[64:67]
	v_mfma_f32_16x16x32_bf16 v[116:119], v[198:201], v[166:169], v[116:119]
	v_mfma_f32_16x16x32_bf16 v[112:115], v[208:211], v[166:169], v[112:115]
	v_mfma_f32_16x16x32_bf16 v[100:103], v[198:201], v[174:177], v[100:103]
	v_mfma_f32_16x16x32_bf16 v[96:99], v[208:211], v[174:177], v[96:99]
	v_mfma_f32_16x16x32_bf16 v[84:87], v[198:201], v[182:185], v[84:87]
	v_mfma_f32_16x16x32_bf16 v[80:83], v[208:211], v[182:185], v[80:83]
	v_mfma_f32_16x16x32_bf16 v[68:71], v[198:201], v[190:193], v[68:71]
	v_mfma_f32_16x16x32_bf16 v[64:67], v[208:211], v[190:193], v[64:67]
	s_setprio 0
	s_mov_b32 m0, s30
	v_lshl_add_u64 v[216:217], s[24:25], 0, v[134:135]
	s_barrier
	ds_read_b128 v[162:165], v144 offset:16384
	ds_read_b128 v[166:169], v144 offset:17408
	ds_read_b128 v[170:173], v144 offset:18432
	ds_read_b128 v[174:177], v144 offset:19456
	ds_read_b128 v[178:181], v144 offset:20480
	ds_read_b128 v[182:185], v144 offset:21504
	ds_read_b128 v[186:189], v144 offset:22528
	ds_read_b128 v[190:193], v144 offset:23552
	global_load_lds_dwordx4 v[216:217], off
	v_lshl_add_u64 v[218:219], s[24:25], 0, v[130:131]
	s_mov_b32 m0, s31
	s_nop 0
	global_load_lds_dwordx4 v[218:219], off
	s_barrier
	s_waitcnt lgkmcnt(0)
	s_setprio 1
	s_waitcnt lgkmcnt(0)
	v_mfma_f32_16x16x32_bf16 v[60:63], v[146:149], v[162:165], v[60:63]
	v_mfma_f32_16x16x32_bf16 v[56:59], v[154:157], v[162:165], v[56:59]
	v_mfma_f32_16x16x32_bf16 v[44:47], v[146:149], v[170:173], v[44:47]
	v_mfma_f32_16x16x32_bf16 v[40:43], v[154:157], v[170:173], v[40:43]
	v_mfma_f32_16x16x32_bf16 v[28:31], v[146:149], v[178:181], v[28:31]
	v_mfma_f32_16x16x32_bf16 v[24:27], v[154:157], v[178:181], v[24:27]
	v_mfma_f32_16x16x32_bf16 v[12:15], v[146:149], v[186:189], v[12:15]
	v_mfma_f32_16x16x32_bf16 v[8:11], v[154:157], v[186:189], v[8:11]
	v_mfma_f32_16x16x32_bf16 v[60:63], v[150:153], v[166:169], v[60:63]
	v_mfma_f32_16x16x32_bf16 v[56:59], v[158:161], v[166:169], v[56:59]
	v_mfma_f32_16x16x32_bf16 v[44:47], v[150:153], v[174:177], v[44:47]
	v_mfma_f32_16x16x32_bf16 v[40:43], v[158:161], v[174:177], v[40:43]
	v_mfma_f32_16x16x32_bf16 v[28:31], v[150:153], v[182:185], v[28:31]
	v_mfma_f32_16x16x32_bf16 v[24:27], v[158:161], v[182:185], v[24:27]
	v_mfma_f32_16x16x32_bf16 v[12:15], v[150:153], v[190:193], v[12:15]
	v_mfma_f32_16x16x32_bf16 v[8:11], v[158:161], v[190:193], v[8:11]
	s_setprio 0
	s_barrier
	s_add_u32 s52, s22, 0x80000
	s_addc_u32 s53, s23, 0
	s_add_i32 s54, s40, s29
	v_lshl_add_u64 v[146:147], s[52:53], 0, v[132:133]
	s_mov_b32 m0, s54
	s_nop 0
	global_load_lds_dwordx4 v[146:147], off
	v_lshl_add_u64 v[146:147], s[52:53], 0, v[128:129]
	s_add_i32 m0, s54, 0x2000
	s_nop 0
	global_load_lds_dwordx4 v[146:147], off
	s_waitcnt vmcnt(6)
	s_barrier
	s_setprio 1
	v_mfma_f32_16x16x32_bf16 v[52:55], v[194:197], v[162:165], v[52:55]
	v_mfma_f32_16x16x32_bf16 v[48:51], v[204:207], v[162:165], v[48:51]
	v_mfma_f32_16x16x32_bf16 v[36:39], v[194:197], v[170:173], v[36:39]
	v_mfma_f32_16x16x32_bf16 v[32:35], v[204:207], v[170:173], v[32:35]
	v_mfma_f32_16x16x32_bf16 v[20:23], v[194:197], v[178:181], v[20:23]
	v_mfma_f32_16x16x32_bf16 v[16:19], v[204:207], v[178:181], v[16:19]
	v_mfma_f32_16x16x32_bf16 v[4:7], v[194:197], v[186:189], v[4:7]
	v_mfma_f32_16x16x32_bf16 v[0:3], v[204:207], v[186:189], v[0:3]
	v_mfma_f32_16x16x32_bf16 v[52:55], v[198:201], v[166:169], v[52:55]
	v_mfma_f32_16x16x32_bf16 v[48:51], v[208:211], v[166:169], v[48:51]
	v_mfma_f32_16x16x32_bf16 v[36:39], v[198:201], v[174:177], v[36:39]
	v_mfma_f32_16x16x32_bf16 v[32:35], v[208:211], v[174:177], v[32:35]
	v_mfma_f32_16x16x32_bf16 v[20:23], v[198:201], v[182:185], v[20:23]
	v_mfma_f32_16x16x32_bf16 v[16:19], v[208:211], v[182:185], v[16:19]
	v_mfma_f32_16x16x32_bf16 v[4:7], v[198:201], v[190:193], v[4:7]
	v_mfma_f32_16x16x32_bf16 v[0:3], v[208:211], v[190:193], v[0:3]
	s_setprio 0
	s_add_i32 s52, 0, 0x18000
	v_add_u32_e32 v158, s52, v141
	s_barrier
	ds_read_b128 v[146:149], v158
	ds_read_b128 v[150:153], v158 offset:1024
	ds_read_b128 v[154:157], v158 offset:2048
	ds_read_b128 v[158:161], v158 offset:3072
	s_add_u32 s24, s24, 0x200000
	s_addc_u32 s25, s25, 0
	s_mov_b32 m0, s34
	v_lshl_add_u64 v[194:195], s[24:25], 0, v[134:135]
	ds_read_b128 v[162:165], v144 offset:32768
	ds_read_b128 v[166:169], v144 offset:33792
	ds_read_b128 v[170:173], v144 offset:34816
	ds_read_b128 v[174:177], v144 offset:35840
	ds_read_b128 v[178:181], v144 offset:36864
	ds_read_b128 v[182:185], v144 offset:37888
	ds_read_b128 v[186:189], v144 offset:38912
	ds_read_b128 v[190:193], v144 offset:39936
	global_load_lds_dwordx4 v[194:195], off
	v_lshl_add_u64 v[194:195], s[24:25], 0, v[130:131]
	s_mov_b32 m0, s35
	s_nop 0
	global_load_lds_dwordx4 v[194:195], off
	s_waitcnt lgkmcnt(8)
	s_barrier
	s_waitcnt lgkmcnt(0)
	s_setprio 1
	s_waitcnt lgkmcnt(0)
	v_mfma_f32_16x16x32_bf16 v[124:127], v[146:149], v[162:165], v[124:127]
	v_mfma_f32_16x16x32_bf16 v[120:123], v[154:157], v[162:165], v[120:123]
	v_mfma_f32_16x16x32_bf16 v[108:111], v[146:149], v[170:173], v[108:111]
	v_mfma_f32_16x16x32_bf16 v[104:107], v[154:157], v[170:173], v[104:107]
	v_mfma_f32_16x16x32_bf16 v[92:95], v[146:149], v[178:181], v[92:95]
	v_mfma_f32_16x16x32_bf16 v[88:91], v[154:157], v[178:181], v[88:91]
	v_mfma_f32_16x16x32_bf16 v[76:79], v[146:149], v[186:189], v[76:79]
	v_mfma_f32_16x16x32_bf16 v[72:75], v[154:157], v[186:189], v[72:75]
	v_mfma_f32_16x16x32_bf16 v[124:127], v[150:153], v[166:169], v[124:127]
	v_mfma_f32_16x16x32_bf16 v[120:123], v[158:161], v[166:169], v[120:123]
	v_mfma_f32_16x16x32_bf16 v[108:111], v[150:153], v[174:177], v[108:111]
	v_mfma_f32_16x16x32_bf16 v[104:107], v[158:161], v[174:177], v[104:107]
	v_mfma_f32_16x16x32_bf16 v[92:95], v[150:153], v[182:185], v[92:95]
	v_mfma_f32_16x16x32_bf16 v[88:91], v[158:161], v[182:185], v[88:91]
	v_mfma_f32_16x16x32_bf16 v[76:79], v[150:153], v[190:193], v[76:79]
	v_mfma_f32_16x16x32_bf16 v[72:75], v[158:161], v[190:193], v[72:75]
	s_setprio 0
	s_barrier
	s_add_i32 s24, 0, 0x1c000
	s_add_i32 s25, s52, s29
	v_add_u32_e32 v208, s24, v141
	v_lshl_add_u64 v[212:213], v[212:213], 0, s[0:1]
	s_mov_b32 m0, s25
	ds_read_b128 v[194:197], v208
	ds_read_b128 v[198:201], v208 offset:1024
	ds_read_b128 v[204:207], v208 offset:2048
	ds_read_b128 v[208:211], v208 offset:3072
	global_load_lds_dwordx4 v[212:213], off
	v_lshl_add_u64 v[212:213], v[214:215], 0, s[0:1]
	s_add_i32 m0, s25, 0x2000
	s_nop 0
	global_load_lds_dwordx4 v[212:213], off
	s_barrier
	s_waitcnt lgkmcnt(0)
	s_setprio 1
	s_waitcnt lgkmcnt(0)
	v_mfma_f32_16x16x32_bf16 v[116:119], v[194:197], v[162:165], v[116:119]
	v_mfma_f32_16x16x32_bf16 v[112:115], v[204:207], v[162:165], v[112:115]
	v_mfma_f32_16x16x32_bf16 v[100:103], v[194:197], v[170:173], v[100:103]
	v_mfma_f32_16x16x32_bf16 v[96:99], v[204:207], v[170:173], v[96:99]
	v_mfma_f32_16x16x32_bf16 v[84:87], v[194:197], v[178:181], v[84:87]
	v_mfma_f32_16x16x32_bf16 v[80:83], v[204:207], v[178:181], v[80:83]
	v_mfma_f32_16x16x32_bf16 v[68:71], v[194:197], v[186:189], v[68:71]
	v_mfma_f32_16x16x32_bf16 v[64:67], v[204:207], v[186:189], v[64:67]
	v_mfma_f32_16x16x32_bf16 v[116:119], v[198:201], v[166:169], v[116:119]
	v_mfma_f32_16x16x32_bf16 v[112:115], v[208:211], v[166:169], v[112:115]
	v_mfma_f32_16x16x32_bf16 v[100:103], v[198:201], v[174:177], v[100:103]
	v_mfma_f32_16x16x32_bf16 v[96:99], v[208:211], v[174:177], v[96:99]
	v_mfma_f32_16x16x32_bf16 v[84:87], v[198:201], v[182:185], v[84:87]
	v_mfma_f32_16x16x32_bf16 v[80:83], v[208:211], v[182:185], v[80:83]
	v_mfma_f32_16x16x32_bf16 v[68:71], v[198:201], v[190:193], v[68:71]
	v_mfma_f32_16x16x32_bf16 v[64:67], v[208:211], v[190:193], v[64:67]
	s_setprio 0
	s_mov_b32 m0, s37
	v_lshl_add_u64 v[212:213], v[216:217], 0, s[0:1]
	s_barrier
	ds_read_b128 v[162:165], v144 offset:49152
	ds_read_b128 v[166:169], v144 offset:50176
	ds_read_b128 v[170:173], v144 offset:51200
	ds_read_b128 v[174:177], v144 offset:52224
	ds_read_b128 v[178:181], v144 offset:53248
	ds_read_b128 v[182:185], v144 offset:54272
	ds_read_b128 v[186:189], v144 offset:55296
	ds_read_b128 v[190:193], v144 offset:56320
	global_load_lds_dwordx4 v[212:213], off
	v_lshl_add_u64 v[212:213], v[218:219], 0, s[0:1]
	s_mov_b32 m0, s38
	s_nop 0
	global_load_lds_dwordx4 v[212:213], off
	s_barrier
	s_waitcnt lgkmcnt(0)
	s_setprio 1
	s_waitcnt lgkmcnt(0)
	v_mfma_f32_16x16x32_bf16 v[60:63], v[146:149], v[162:165], v[60:63]
	v_mfma_f32_16x16x32_bf16 v[56:59], v[154:157], v[162:165], v[56:59]
	v_mfma_f32_16x16x32_bf16 v[44:47], v[146:149], v[170:173], v[44:47]
	v_mfma_f32_16x16x32_bf16 v[40:43], v[154:157], v[170:173], v[40:43]
	v_mfma_f32_16x16x32_bf16 v[28:31], v[146:149], v[178:181], v[28:31]
	v_mfma_f32_16x16x32_bf16 v[24:27], v[154:157], v[178:181], v[24:27]
	v_mfma_f32_16x16x32_bf16 v[12:15], v[146:149], v[186:189], v[12:15]
	v_mfma_f32_16x16x32_bf16 v[8:11], v[154:157], v[186:189], v[8:11]
	v_mfma_f32_16x16x32_bf16 v[60:63], v[150:153], v[166:169], v[60:63]
	v_mfma_f32_16x16x32_bf16 v[56:59], v[158:161], v[166:169], v[56:59]
	v_mfma_f32_16x16x32_bf16 v[44:47], v[150:153], v[174:177], v[44:47]
	v_mfma_f32_16x16x32_bf16 v[40:43], v[158:161], v[174:177], v[40:43]
	v_mfma_f32_16x16x32_bf16 v[28:31], v[150:153], v[182:185], v[28:31]
	v_mfma_f32_16x16x32_bf16 v[24:27], v[158:161], v[182:185], v[24:27]
	v_mfma_f32_16x16x32_bf16 v[12:15], v[150:153], v[190:193], v[12:15]
	v_mfma_f32_16x16x32_bf16 v[8:11], v[158:161], v[190:193], v[8:11]
	s_setprio 0
	s_barrier
	s_add_u32 s22, s22, 0x80080
	s_addc_u32 s23, s23, 0
	s_add_i32 s24, s24, s29
	v_lshl_add_u64 v[146:147], s[22:23], 0, v[132:133]
	s_mov_b32 m0, s24
	s_nop 0
	global_load_lds_dwordx4 v[146:147], off
	v_lshl_add_u64 v[146:147], s[22:23], 0, v[128:129]
	s_add_i32 m0, s24, 0x2000
	s_nop 0
	global_load_lds_dwordx4 v[146:147], off
	s_waitcnt vmcnt(6)
	s_barrier
	s_setprio 1
	v_mfma_f32_16x16x32_bf16 v[52:55], v[194:197], v[162:165], v[52:55]
	v_mfma_f32_16x16x32_bf16 v[48:51], v[204:207], v[162:165], v[48:51]
	v_mfma_f32_16x16x32_bf16 v[36:39], v[194:197], v[170:173], v[36:39]
	v_mfma_f32_16x16x32_bf16 v[32:35], v[204:207], v[170:173], v[32:35]
	v_mfma_f32_16x16x32_bf16 v[20:23], v[194:197], v[178:181], v[20:23]
	v_mfma_f32_16x16x32_bf16 v[16:19], v[204:207], v[178:181], v[16:19]
	v_mfma_f32_16x16x32_bf16 v[4:7], v[194:197], v[186:189], v[4:7]
	v_mfma_f32_16x16x32_bf16 v[0:3], v[204:207], v[186:189], v[0:3]
	v_mfma_f32_16x16x32_bf16 v[52:55], v[198:201], v[166:169], v[52:55]
	v_mfma_f32_16x16x32_bf16 v[48:51], v[208:211], v[166:169], v[48:51]
	v_mfma_f32_16x16x32_bf16 v[36:39], v[198:201], v[174:177], v[36:39]
	v_mfma_f32_16x16x32_bf16 v[32:35], v[208:211], v[174:177], v[32:35]
	v_mfma_f32_16x16x32_bf16 v[20:23], v[198:201], v[182:185], v[20:23]
	v_mfma_f32_16x16x32_bf16 v[16:19], v[208:211], v[182:185], v[16:19]
	v_mfma_f32_16x16x32_bf16 v[4:7], v[198:201], v[190:193], v[4:7]
	v_mfma_f32_16x16x32_bf16 v[0:3], v[208:211], v[190:193], v[0:3]
	s_setprio 0
	s_add_u32 s20, s20, 0x100
	s_addc_u32 s21, s21, 0
	s_add_u32 s49, s49, 0x100
	s_addc_u32 s50, s50, 0
	s_cmp_ge_i32 s51, s33
	s_mov_b32 s22, s51
	s_barrier
	s_cbranch_scc0 .LBB0_1631
	s_branch .LBB0_1626
